# bf16 GEMM tile loops for PEER-q and output projections rewritten by hand with a 2-deep global prefetch and a locality-aware tile order; same bf16 MFMA / f32 accumulate
# speedup vs baseline: 1.0791x; 1.0109x over previous
.LBB0_786:
.Lgout0_tile:
	s_bfe_u32 s20, s5, 0x30005
	s_and_b32 s21, s5, 31
	s_lshr_b32 s7, s5, 8
	s_lshl_b32 s6, s7, 5
	s_lshr_b32 s7, s20, 1
	s_lshl_b32 s7, s7, 3
	s_add_u32 s6, s6, s7
	s_lshr_b32 s7, s21, 2
	s_add_u32 s6, s6, s7
	s_and_b32 s7, s20, 1
	s_lshl_b32 s7, s7, 2
	s_and_b32 s21, s21, 3
	s_add_u32 s7, s7, s21
	s_lshl_b32 s6, s6, 8
	s_lshl_b32 s7, s7, 8
	s_lshl_b32 s20, s6, 12
	s_add_u32 s20, s20, 0xe224000
	s_add_u32 s8, s92, s20
	s_addc_u32 s9, s93, 0
	s_and_b32 s9, s9, 0xffff
	s_mov_b32 s10, 0x100000
	s_mov_b32 s11, 0x20000
	s_lshl_b32 s20, s7, 12
	s_add_u32 s20, s20, 0x1380000
	s_add_u32 s24, s92, s20
	s_addc_u32 s25, s93, 0
	s_and_b32 s25, s25, 0xffff
	s_sub_u32 s20, 0x800, s7
	s_min_u32 s20, s20, 0x100
	s_lshl_b32 s26, s20, 12
	s_mov_b32 s27, 0x20000
	s_mov_b32 s28, 0x40000
	s_mov_b32 s29, 0x80000
	s_mov_b32 s30, 0xc0000
	v_lshrrev_b32_e32 v128, 3, v190
	v_and_b32_e32 v129, 7, v190
	v_lshlrev_b32_e32 v129, 4, v129
	v_lshl_add_u32 v160, v128, 12, v129
	v_mul_u32_u24_e32 v130, 0x90, v128
	v_add_u32_e32 v170, v130, v129
	v_add_u32_e32 v171, 0x12000, v170
	v_and_b32_e32 v131, 31, v190
	v_bfe_u32 v132, v190, 5, 1
	v_bfe_u32 v133, v190, 6, 2
	v_bfe_u32 v134, v190, 8, 1
	v_lshl_add_u32 v135, v134, 7, v131
	v_mul_u32_u24_e32 v135, 0x90, v135
	v_lshl_add_u32 v175, v132, 4, v135
	v_lshl_add_u32 v136, v133, 6, v131
	v_mul_u32_u24_e32 v136, 0x90, v136
	v_lshl_add_u32 v136, v132, 4, v136
	v_add_u32_e32 v254, 0x12000, v136
	v_mov_b32_e32 v0, 0
	v_mov_b32_e32 v1, 0
	v_mov_b32_e32 v2, 0
	v_mov_b32_e32 v3, 0
	v_mov_b32_e32 v4, 0
	v_mov_b32_e32 v5, 0
	v_mov_b32_e32 v6, 0
	v_mov_b32_e32 v7, 0
	v_mov_b32_e32 v8, 0
	v_mov_b32_e32 v9, 0
	v_mov_b32_e32 v10, 0
	v_mov_b32_e32 v11, 0
	v_mov_b32_e32 v12, 0
	v_mov_b32_e32 v13, 0
	v_mov_b32_e32 v14, 0
	v_mov_b32_e32 v15, 0
	v_mov_b32_e32 v16, 0
	v_mov_b32_e32 v17, 0
	v_mov_b32_e32 v18, 0
	v_mov_b32_e32 v19, 0
	v_mov_b32_e32 v20, 0
	v_mov_b32_e32 v21, 0
	v_mov_b32_e32 v22, 0
	v_mov_b32_e32 v23, 0
	v_mov_b32_e32 v24, 0
	v_mov_b32_e32 v25, 0
	v_mov_b32_e32 v26, 0
	v_mov_b32_e32 v27, 0
	v_mov_b32_e32 v28, 0
	v_mov_b32_e32 v29, 0
	v_mov_b32_e32 v30, 0
	v_mov_b32_e32 v31, 0
	v_mov_b32_e32 v32, 0
	v_mov_b32_e32 v33, 0
	v_mov_b32_e32 v34, 0
	v_mov_b32_e32 v35, 0
	v_mov_b32_e32 v36, 0
	v_mov_b32_e32 v37, 0
	v_mov_b32_e32 v38, 0
	v_mov_b32_e32 v39, 0
	v_mov_b32_e32 v40, 0
	v_mov_b32_e32 v41, 0
	v_mov_b32_e32 v42, 0
	v_mov_b32_e32 v43, 0
	v_mov_b32_e32 v44, 0
	v_mov_b32_e32 v45, 0
	v_mov_b32_e32 v46, 0
	v_mov_b32_e32 v47, 0
	v_mov_b32_e32 v48, 0
	v_mov_b32_e32 v49, 0
	v_mov_b32_e32 v50, 0
	v_mov_b32_e32 v51, 0
	v_mov_b32_e32 v52, 0
	v_mov_b32_e32 v53, 0
	v_mov_b32_e32 v54, 0
	v_mov_b32_e32 v55, 0
	v_mov_b32_e32 v56, 0
	v_mov_b32_e32 v57, 0
	v_mov_b32_e32 v58, 0
	v_mov_b32_e32 v59, 0
	v_mov_b32_e32 v60, 0
	v_mov_b32_e32 v61, 0
	v_mov_b32_e32 v62, 0
	v_mov_b32_e32 v63, 0
	v_mov_b32_e32 v64, 0
	v_mov_b32_e32 v65, 0
	v_mov_b32_e32 v66, 0
	v_mov_b32_e32 v67, 0
	v_mov_b32_e32 v68, 0
	v_mov_b32_e32 v69, 0
	v_mov_b32_e32 v70, 0
	v_mov_b32_e32 v71, 0
	v_mov_b32_e32 v72, 0
	v_mov_b32_e32 v73, 0
	v_mov_b32_e32 v74, 0
	v_mov_b32_e32 v75, 0
	v_mov_b32_e32 v76, 0
	v_mov_b32_e32 v77, 0
	v_mov_b32_e32 v78, 0
	v_mov_b32_e32 v79, 0
	v_mov_b32_e32 v80, 0
	v_mov_b32_e32 v81, 0
	v_mov_b32_e32 v82, 0
	v_mov_b32_e32 v83, 0
	v_mov_b32_e32 v84, 0
	v_mov_b32_e32 v85, 0
	v_mov_b32_e32 v86, 0
	v_mov_b32_e32 v87, 0
	v_mov_b32_e32 v88, 0
	v_mov_b32_e32 v89, 0
	v_mov_b32_e32 v90, 0
	v_mov_b32_e32 v91, 0
	v_mov_b32_e32 v92, 0
	v_mov_b32_e32 v93, 0
	v_mov_b32_e32 v94, 0
	v_mov_b32_e32 v95, 0
	v_mov_b32_e32 v96, 0
	v_mov_b32_e32 v97, 0
	v_mov_b32_e32 v98, 0
	v_mov_b32_e32 v99, 0
	v_mov_b32_e32 v100, 0
	v_mov_b32_e32 v101, 0
	v_mov_b32_e32 v102, 0
	v_mov_b32_e32 v103, 0
	v_mov_b32_e32 v104, 0
	v_mov_b32_e32 v105, 0
	v_mov_b32_e32 v106, 0
	v_mov_b32_e32 v107, 0
	v_mov_b32_e32 v108, 0
	v_mov_b32_e32 v109, 0
	v_mov_b32_e32 v110, 0
	v_mov_b32_e32 v111, 0
	v_mov_b32_e32 v112, 0
	v_mov_b32_e32 v113, 0
	v_mov_b32_e32 v114, 0
	v_mov_b32_e32 v115, 0
	v_mov_b32_e32 v116, 0
	v_mov_b32_e32 v117, 0
	v_mov_b32_e32 v118, 0
	v_mov_b32_e32 v119, 0
	v_mov_b32_e32 v120, 0
	v_mov_b32_e32 v121, 0
	v_mov_b32_e32 v122, 0
	v_mov_b32_e32 v123, 0
	v_mov_b32_e32 v124, 0
	v_mov_b32_e32 v125, 0
	v_mov_b32_e32 v126, 0
	v_mov_b32_e32 v127, 0
	v_mov_b32_e32 v192, 0
	v_mov_b32_e32 v193, 0
	v_mov_b32_e32 v194, 0
	v_mov_b32_e32 v195, 0
	v_mov_b32_e32 v196, 0
	v_mov_b32_e32 v197, 0
	v_mov_b32_e32 v198, 0
	v_mov_b32_e32 v199, 0
	v_mov_b32_e32 v200, 0
	v_mov_b32_e32 v201, 0
	v_mov_b32_e32 v202, 0
	v_mov_b32_e32 v203, 0
	v_mov_b32_e32 v204, 0
	v_mov_b32_e32 v205, 0
	v_mov_b32_e32 v206, 0
	v_mov_b32_e32 v207, 0
	v_mov_b32_e32 v208, 0
	v_mov_b32_e32 v209, 0
	v_mov_b32_e32 v210, 0
	v_mov_b32_e32 v211, 0
	v_mov_b32_e32 v212, 0
	v_mov_b32_e32 v213, 0
	v_mov_b32_e32 v214, 0
	v_mov_b32_e32 v215, 0
	v_mov_b32_e32 v188, 0
	v_mov_b32_e32 v189, 0
	buffer_load_dwordx4 v[216:219], v160, s[8:11], 0 offen
	buffer_load_dwordx4 v[220:223], v160, s[8:11], s28 offen
	buffer_load_dwordx4 v[224:227], v160, s[8:11], s29 offen
	buffer_load_dwordx4 v[228:231], v160, s[8:11], s30 offen
	buffer_load_dwordx4 v[232:235], v160, s[24:27], 0 offen
	buffer_load_dwordx4 v[236:239], v160, s[24:27], s28 offen
	buffer_load_dwordx4 v[152:155], v160, s[24:27], s29 offen
	buffer_load_dwordx4 v[156:159], v160, s[24:27], s30 offen
	v_add_u32_e32 v160, 0x80, v160
	buffer_load_dwordx4 v[162:165], v160, s[8:11], 0 offen
	buffer_load_dwordx4 v[166:169], v160, s[8:11], s28 offen
	buffer_load_dwordx4 v[176:179], v160, s[8:11], s29 offen
	buffer_load_dwordx4 v[180:183], v160, s[8:11], s30 offen
	buffer_load_dwordx4 v[184:187], v160, s[24:27], 0 offen
	buffer_load_dwordx4 v[242:245], v160, s[24:27], s28 offen
	buffer_load_dwordx4 v[246:249], v160, s[24:27], s29 offen
	buffer_load_dwordx4 v[250:253], v160, s[24:27], s30 offen
	v_add_u32_e32 v160, 0x80, v160
	s_waitcnt vmcnt(8)
	ds_write_b128 v170, v[216:219] offset:0
	ds_write_b128 v170, v[220:223] offset:9216
	ds_write_b128 v170, v[224:227] offset:18432
	ds_write_b128 v170, v[228:231] offset:27648
	ds_write_b128 v171, v[232:235] offset:0
	ds_write_b128 v171, v[236:239] offset:9216
	ds_write_b128 v171, v[152:155] offset:18432
	ds_write_b128 v171, v[156:159] offset:27648
	buffer_load_dwordx4 v[216:219], v160, s[8:11], 0 offen
	buffer_load_dwordx4 v[220:223], v160, s[8:11], s28 offen
	buffer_load_dwordx4 v[224:227], v160, s[8:11], s29 offen
	buffer_load_dwordx4 v[228:231], v160, s[8:11], s30 offen
	buffer_load_dwordx4 v[232:235], v160, s[24:27], 0 offen
	buffer_load_dwordx4 v[236:239], v160, s[24:27], s28 offen
	buffer_load_dwordx4 v[152:155], v160, s[24:27], s29 offen
	buffer_load_dwordx4 v[156:159], v160, s[24:27], s30 offen
	v_add_u32_e32 v160, 0x80, v160
	s_waitcnt lgkmcnt(0)
	s_barrier
	s_movk_i32 s31, 14
.Lgout0_loop:
	ds_read_b128 v[144:147], v254 offset:0
	ds_read_b128 v[148:151], v254 offset:4608
	ds_read_b128 v[128:131], v175 offset:0
	ds_read_b128 v[132:135], v175 offset:4608
	ds_read_b128 v[136:139], v175 offset:9216
	ds_read_b128 v[140:143], v175 offset:13824
	v_mfma_f32_32x32x16_bf16 v[112:127], v[192:195], v[208:211], v[112:127]
	s_waitcnt vmcnt(8)
	v_mfma_f32_32x32x16_bf16 v[96:111], v[192:195], v[212:215], v[96:111]
	ds_write_b128 v170, v[162:165] offset:36864
	v_mfma_f32_32x32x16_bf16 v[80:95], v[196:199], v[208:211], v[80:95]
	ds_write_b128 v170, v[166:169] offset:46080
	v_mfma_f32_32x32x16_bf16 v[64:79], v[196:199], v[212:215], v[64:79]
	ds_write_b128 v170, v[176:179] offset:55296
	v_mfma_f32_32x32x16_bf16 v[48:63], v[200:203], v[208:211], v[48:63]
	ds_write_b128 v170, v[180:183] offset:64512
	v_mfma_f32_32x32x16_bf16 v[32:47], v[200:203], v[212:215], v[32:47]
	ds_write_b128 v171, v[184:187] offset:36864
	v_mfma_f32_32x32x16_bf16 v[16:31], v[204:207], v[208:211], v[16:31]
	ds_write_b128 v171, v[242:245] offset:46080
	v_mfma_f32_32x32x16_bf16 v[0:15], v[204:207], v[212:215], v[0:15]
	ds_write_b128 v171, v[246:249] offset:55296
	ds_write_b128 v171, v[250:253] offset:64512
	s_waitcnt lgkmcnt(8)
	v_mfma_f32_32x32x16_bf16 v[112:127], v[128:131], v[144:147], v[112:127]
	ds_read_b128 v[208:211], v254 offset:32
	v_mfma_f32_32x32x16_bf16 v[96:111], v[128:131], v[148:151], v[96:111]
	ds_read_b128 v[212:215], v254 offset:4640
	ds_read_b128 v[192:195], v175 offset:32
	v_mfma_f32_32x32x16_bf16 v[80:95], v[132:135], v[144:147], v[80:95]
	ds_read_b128 v[196:199], v175 offset:4640
	ds_read_b128 v[200:203], v175 offset:9248
	v_mfma_f32_32x32x16_bf16 v[64:79], v[132:135], v[148:151], v[64:79]
	ds_read_b128 v[204:207], v175 offset:13856
	buffer_load_dwordx4 v[162:165], v160, s[8:11], 0 offen
	v_mfma_f32_32x32x16_bf16 v[48:63], v[136:139], v[144:147], v[48:63]
	buffer_load_dwordx4 v[166:169], v160, s[8:11], s28 offen
	buffer_load_dwordx4 v[176:179], v160, s[8:11], s29 offen
	v_mfma_f32_32x32x16_bf16 v[32:47], v[136:139], v[148:151], v[32:47]
	buffer_load_dwordx4 v[180:183], v160, s[8:11], s30 offen
	buffer_load_dwordx4 v[184:187], v160, s[24:27], 0 offen
	v_mfma_f32_32x32x16_bf16 v[16:31], v[140:143], v[144:147], v[16:31]
	buffer_load_dwordx4 v[242:245], v160, s[24:27], s28 offen
	buffer_load_dwordx4 v[246:249], v160, s[24:27], s29 offen
	v_mfma_f32_32x32x16_bf16 v[0:15], v[140:143], v[148:151], v[0:15]
	buffer_load_dwordx4 v[250:253], v160, s[24:27], s30 offen
	v_add_u32_e32 v160, 0x80, v160
	s_waitcnt lgkmcnt(0)
	v_mfma_f32_32x32x16_bf16 v[112:127], v[192:195], v[208:211], v[112:127]
	v_mfma_f32_32x32x16_bf16 v[96:111], v[192:195], v[212:215], v[96:111]
	ds_read_b128 v[144:147], v254 offset:64
	v_mfma_f32_32x32x16_bf16 v[80:95], v[196:199], v[208:211], v[80:95]
	ds_read_b128 v[148:151], v254 offset:4672
	v_mfma_f32_32x32x16_bf16 v[64:79], v[196:199], v[212:215], v[64:79]
	ds_read_b128 v[128:131], v175 offset:64
	v_mfma_f32_32x32x16_bf16 v[48:63], v[200:203], v[208:211], v[48:63]
	v_mfma_f32_32x32x16_bf16 v[32:47], v[200:203], v[212:215], v[32:47]
	ds_read_b128 v[132:135], v175 offset:4672
	v_mfma_f32_32x32x16_bf16 v[16:31], v[204:207], v[208:211], v[16:31]
	ds_read_b128 v[136:139], v175 offset:9280
	v_mfma_f32_32x32x16_bf16 v[0:15], v[204:207], v[212:215], v[0:15]
	ds_read_b128 v[140:143], v175 offset:13888
	s_waitcnt lgkmcnt(0)
	v_mfma_f32_32x32x16_bf16 v[112:127], v[128:131], v[144:147], v[112:127]
	v_mfma_f32_32x32x16_bf16 v[96:111], v[128:131], v[148:151], v[96:111]
	ds_read_b128 v[208:211], v254 offset:96
	v_mfma_f32_32x32x16_bf16 v[80:95], v[132:135], v[144:147], v[80:95]
	ds_read_b128 v[212:215], v254 offset:4704
	v_mfma_f32_32x32x16_bf16 v[64:79], v[132:135], v[148:151], v[64:79]
	ds_read_b128 v[192:195], v175 offset:96
	v_mfma_f32_32x32x16_bf16 v[48:63], v[136:139], v[144:147], v[48:63]
	v_mfma_f32_32x32x16_bf16 v[32:47], v[136:139], v[148:151], v[32:47]
	ds_read_b128 v[196:199], v175 offset:4704
	v_mfma_f32_32x32x16_bf16 v[16:31], v[140:143], v[144:147], v[16:31]
	ds_read_b128 v[200:203], v175 offset:9312
	v_mfma_f32_32x32x16_bf16 v[0:15], v[140:143], v[148:151], v[0:15]
	ds_read_b128 v[204:207], v175 offset:13920
	s_waitcnt lgkmcnt(0)
	s_barrier
	ds_read_b128 v[144:147], v254 offset:36864
	ds_read_b128 v[148:151], v254 offset:41472
	ds_read_b128 v[128:131], v175 offset:36864
	ds_read_b128 v[132:135], v175 offset:41472
	ds_read_b128 v[136:139], v175 offset:46080
	ds_read_b128 v[140:143], v175 offset:50688
	v_mfma_f32_32x32x16_bf16 v[112:127], v[192:195], v[208:211], v[112:127]
	s_waitcnt vmcnt(8)
	v_mfma_f32_32x32x16_bf16 v[96:111], v[192:195], v[212:215], v[96:111]
	ds_write_b128 v170, v[216:219] offset:0
	v_mfma_f32_32x32x16_bf16 v[80:95], v[196:199], v[208:211], v[80:95]
	ds_write_b128 v170, v[220:223] offset:9216
	v_mfma_f32_32x32x16_bf16 v[64:79], v[196:199], v[212:215], v[64:79]
	ds_write_b128 v170, v[224:227] offset:18432
	v_mfma_f32_32x32x16_bf16 v[48:63], v[200:203], v[208:211], v[48:63]
	ds_write_b128 v170, v[228:231] offset:27648
	v_mfma_f32_32x32x16_bf16 v[32:47], v[200:203], v[212:215], v[32:47]
	ds_write_b128 v171, v[232:235] offset:0
	v_mfma_f32_32x32x16_bf16 v[16:31], v[204:207], v[208:211], v[16:31]
	ds_write_b128 v171, v[236:239] offset:9216
	v_mfma_f32_32x32x16_bf16 v[0:15], v[204:207], v[212:215], v[0:15]
	ds_write_b128 v171, v[152:155] offset:18432
	ds_write_b128 v171, v[156:159] offset:27648
	s_waitcnt lgkmcnt(8)
	v_mfma_f32_32x32x16_bf16 v[112:127], v[128:131], v[144:147], v[112:127]
	ds_read_b128 v[208:211], v254 offset:36896
	v_mfma_f32_32x32x16_bf16 v[96:111], v[128:131], v[148:151], v[96:111]
	ds_read_b128 v[212:215], v254 offset:41504
	ds_read_b128 v[192:195], v175 offset:36896
	v_mfma_f32_32x32x16_bf16 v[80:95], v[132:135], v[144:147], v[80:95]
	ds_read_b128 v[196:199], v175 offset:41504
	ds_read_b128 v[200:203], v175 offset:46112
	v_mfma_f32_32x32x16_bf16 v[64:79], v[132:135], v[148:151], v[64:79]
	ds_read_b128 v[204:207], v175 offset:50720
	buffer_load_dwordx4 v[216:219], v160, s[8:11], 0 offen
	v_mfma_f32_32x32x16_bf16 v[48:63], v[136:139], v[144:147], v[48:63]
	buffer_load_dwordx4 v[220:223], v160, s[8:11], s28 offen
	buffer_load_dwordx4 v[224:227], v160, s[8:11], s29 offen
	v_mfma_f32_32x32x16_bf16 v[32:47], v[136:139], v[148:151], v[32:47]
	buffer_load_dwordx4 v[228:231], v160, s[8:11], s30 offen
	buffer_load_dwordx4 v[232:235], v160, s[24:27], 0 offen
	v_mfma_f32_32x32x16_bf16 v[16:31], v[140:143], v[144:147], v[16:31]
	buffer_load_dwordx4 v[236:239], v160, s[24:27], s28 offen
	buffer_load_dwordx4 v[152:155], v160, s[24:27], s29 offen
	v_mfma_f32_32x32x16_bf16 v[0:15], v[140:143], v[148:151], v[0:15]
	buffer_load_dwordx4 v[156:159], v160, s[24:27], s30 offen
	v_add_u32_e32 v160, 0x80, v160
	s_waitcnt lgkmcnt(0)
	v_mfma_f32_32x32x16_bf16 v[112:127], v[192:195], v[208:211], v[112:127]
	v_mfma_f32_32x32x16_bf16 v[96:111], v[192:195], v[212:215], v[96:111]
	ds_read_b128 v[144:147], v254 offset:36928
	v_mfma_f32_32x32x16_bf16 v[80:95], v[196:199], v[208:211], v[80:95]
	ds_read_b128 v[148:151], v254 offset:41536
	v_mfma_f32_32x32x16_bf16 v[64:79], v[196:199], v[212:215], v[64:79]
	ds_read_b128 v[128:131], v175 offset:36928
	v_mfma_f32_32x32x16_bf16 v[48:63], v[200:203], v[208:211], v[48:63]
	v_mfma_f32_32x32x16_bf16 v[32:47], v[200:203], v[212:215], v[32:47]
	ds_read_b128 v[132:135], v175 offset:41536
	v_mfma_f32_32x32x16_bf16 v[16:31], v[204:207], v[208:211], v[16:31]
	ds_read_b128 v[136:139], v175 offset:46144
	v_mfma_f32_32x32x16_bf16 v[0:15], v[204:207], v[212:215], v[0:15]
	ds_read_b128 v[140:143], v175 offset:50752
	s_waitcnt lgkmcnt(0)
	v_mfma_f32_32x32x16_bf16 v[112:127], v[128:131], v[144:147], v[112:127]
	v_mfma_f32_32x32x16_bf16 v[96:111], v[128:131], v[148:151], v[96:111]
	ds_read_b128 v[208:211], v254 offset:36960
	v_mfma_f32_32x32x16_bf16 v[80:95], v[132:135], v[144:147], v[80:95]
	ds_read_b128 v[212:215], v254 offset:41568
	v_mfma_f32_32x32x16_bf16 v[64:79], v[132:135], v[148:151], v[64:79]
	ds_read_b128 v[192:195], v175 offset:36960
	v_mfma_f32_32x32x16_bf16 v[48:63], v[136:139], v[144:147], v[48:63]
	v_mfma_f32_32x32x16_bf16 v[32:47], v[136:139], v[148:151], v[32:47]
	ds_read_b128 v[196:199], v175 offset:41568
	v_mfma_f32_32x32x16_bf16 v[16:31], v[140:143], v[144:147], v[16:31]
	ds_read_b128 v[200:203], v175 offset:46176
	v_mfma_f32_32x32x16_bf16 v[0:15], v[140:143], v[148:151], v[0:15]
	ds_read_b128 v[204:207], v175 offset:50784
	s_waitcnt lgkmcnt(0)
	s_barrier
	s_add_i32 s31, s31, -1
	s_cmp_lg_u32 s31, 0
	s_cbranch_scc1 .Lgout0_loop
	ds_read_b128 v[144:147], v254 offset:0
	ds_read_b128 v[148:151], v254 offset:4608
	ds_read_b128 v[128:131], v175 offset:0
	ds_read_b128 v[132:135], v175 offset:4608
	ds_read_b128 v[136:139], v175 offset:9216
	ds_read_b128 v[140:143], v175 offset:13824
	v_mfma_f32_32x32x16_bf16 v[112:127], v[192:195], v[208:211], v[112:127]
	s_waitcnt vmcnt(8)
	v_mfma_f32_32x32x16_bf16 v[96:111], v[192:195], v[212:215], v[96:111]
	ds_write_b128 v170, v[162:165] offset:36864
	v_mfma_f32_32x32x16_bf16 v[80:95], v[196:199], v[208:211], v[80:95]
	ds_write_b128 v170, v[166:169] offset:46080
	v_mfma_f32_32x32x16_bf16 v[64:79], v[196:199], v[212:215], v[64:79]
	ds_write_b128 v170, v[176:179] offset:55296
	v_mfma_f32_32x32x16_bf16 v[48:63], v[200:203], v[208:211], v[48:63]
	ds_write_b128 v170, v[180:183] offset:64512
	v_mfma_f32_32x32x16_bf16 v[32:47], v[200:203], v[212:215], v[32:47]
	ds_write_b128 v171, v[184:187] offset:36864
	v_mfma_f32_32x32x16_bf16 v[16:31], v[204:207], v[208:211], v[16:31]
	ds_write_b128 v171, v[242:245] offset:46080
	v_mfma_f32_32x32x16_bf16 v[0:15], v[204:207], v[212:215], v[0:15]
	ds_write_b128 v171, v[246:249] offset:55296
	ds_write_b128 v171, v[250:253] offset:64512
	s_waitcnt lgkmcnt(8)
	v_mfma_f32_32x32x16_bf16 v[112:127], v[128:131], v[144:147], v[112:127]
	ds_read_b128 v[208:211], v254 offset:32
	v_mfma_f32_32x32x16_bf16 v[96:111], v[128:131], v[148:151], v[96:111]
	ds_read_b128 v[212:215], v254 offset:4640
	ds_read_b128 v[192:195], v175 offset:32
	v_mfma_f32_32x32x16_bf16 v[80:95], v[132:135], v[144:147], v[80:95]
	ds_read_b128 v[196:199], v175 offset:4640
	ds_read_b128 v[200:203], v175 offset:9248
	v_mfma_f32_32x32x16_bf16 v[64:79], v[132:135], v[148:151], v[64:79]
	ds_read_b128 v[204:207], v175 offset:13856
	buffer_load_dwordx4 v[162:165], v160, s[8:11], 0 offen
	v_mfma_f32_32x32x16_bf16 v[48:63], v[136:139], v[144:147], v[48:63]
	buffer_load_dwordx4 v[166:169], v160, s[8:11], s28 offen
	buffer_load_dwordx4 v[176:179], v160, s[8:11], s29 offen
	v_mfma_f32_32x32x16_bf16 v[32:47], v[136:139], v[148:151], v[32:47]
	buffer_load_dwordx4 v[180:183], v160, s[8:11], s30 offen
	buffer_load_dwordx4 v[184:187], v160, s[24:27], 0 offen
	v_mfma_f32_32x32x16_bf16 v[16:31], v[140:143], v[144:147], v[16:31]
	buffer_load_dwordx4 v[242:245], v160, s[24:27], s28 offen
	buffer_load_dwordx4 v[246:249], v160, s[24:27], s29 offen
	v_mfma_f32_32x32x16_bf16 v[0:15], v[140:143], v[148:151], v[0:15]
	buffer_load_dwordx4 v[250:253], v160, s[24:27], s30 offen
	v_add_u32_e32 v160, 0x80, v160
	s_waitcnt lgkmcnt(0)
	v_mfma_f32_32x32x16_bf16 v[112:127], v[192:195], v[208:211], v[112:127]
	v_mfma_f32_32x32x16_bf16 v[96:111], v[192:195], v[212:215], v[96:111]
	ds_read_b128 v[144:147], v254 offset:64
	v_mfma_f32_32x32x16_bf16 v[80:95], v[196:199], v[208:211], v[80:95]
	ds_read_b128 v[148:151], v254 offset:4672
	v_mfma_f32_32x32x16_bf16 v[64:79], v[196:199], v[212:215], v[64:79]
	ds_read_b128 v[128:131], v175 offset:64
	v_mfma_f32_32x32x16_bf16 v[48:63], v[200:203], v[208:211], v[48:63]
	v_mfma_f32_32x32x16_bf16 v[32:47], v[200:203], v[212:215], v[32:47]
	ds_read_b128 v[132:135], v175 offset:4672
	v_mfma_f32_32x32x16_bf16 v[16:31], v[204:207], v[208:211], v[16:31]
	ds_read_b128 v[136:139], v175 offset:9280
	v_mfma_f32_32x32x16_bf16 v[0:15], v[204:207], v[212:215], v[0:15]
	ds_read_b128 v[140:143], v175 offset:13888
	s_waitcnt lgkmcnt(0)
	v_mfma_f32_32x32x16_bf16 v[112:127], v[128:131], v[144:147], v[112:127]
	v_mfma_f32_32x32x16_bf16 v[96:111], v[128:131], v[148:151], v[96:111]
	ds_read_b128 v[208:211], v254 offset:96
	v_mfma_f32_32x32x16_bf16 v[80:95], v[132:135], v[144:147], v[80:95]
	ds_read_b128 v[212:215], v254 offset:4704
	v_mfma_f32_32x32x16_bf16 v[64:79], v[132:135], v[148:151], v[64:79]
	ds_read_b128 v[192:195], v175 offset:96
	v_mfma_f32_32x32x16_bf16 v[48:63], v[136:139], v[144:147], v[48:63]
	v_mfma_f32_32x32x16_bf16 v[32:47], v[136:139], v[148:151], v[32:47]
	ds_read_b128 v[196:199], v175 offset:4704
	v_mfma_f32_32x32x16_bf16 v[16:31], v[140:143], v[144:147], v[16:31]
	ds_read_b128 v[200:203], v175 offset:9312
	v_mfma_f32_32x32x16_bf16 v[0:15], v[140:143], v[148:151], v[0:15]
	ds_read_b128 v[204:207], v175 offset:13920
	s_waitcnt lgkmcnt(0)
	s_barrier
	ds_read_b128 v[144:147], v254 offset:36864
	ds_read_b128 v[148:151], v254 offset:41472
	ds_read_b128 v[128:131], v175 offset:36864
	ds_read_b128 v[132:135], v175 offset:41472
	ds_read_b128 v[136:139], v175 offset:46080
	ds_read_b128 v[140:143], v175 offset:50688
	v_mfma_f32_32x32x16_bf16 v[112:127], v[192:195], v[208:211], v[112:127]
	s_waitcnt vmcnt(8)
	v_mfma_f32_32x32x16_bf16 v[96:111], v[192:195], v[212:215], v[96:111]
	ds_write_b128 v170, v[216:219] offset:0
	v_mfma_f32_32x32x16_bf16 v[80:95], v[196:199], v[208:211], v[80:95]
	ds_write_b128 v170, v[220:223] offset:9216
	v_mfma_f32_32x32x16_bf16 v[64:79], v[196:199], v[212:215], v[64:79]
	ds_write_b128 v170, v[224:227] offset:18432
	v_mfma_f32_32x32x16_bf16 v[48:63], v[200:203], v[208:211], v[48:63]
	ds_write_b128 v170, v[228:231] offset:27648
	v_mfma_f32_32x32x16_bf16 v[32:47], v[200:203], v[212:215], v[32:47]
	ds_write_b128 v171, v[232:235] offset:0
	v_mfma_f32_32x32x16_bf16 v[16:31], v[204:207], v[208:211], v[16:31]
	ds_write_b128 v171, v[236:239] offset:9216
	v_mfma_f32_32x32x16_bf16 v[0:15], v[204:207], v[212:215], v[0:15]
	ds_write_b128 v171, v[152:155] offset:18432
	ds_write_b128 v171, v[156:159] offset:27648
	s_waitcnt lgkmcnt(8)
	v_mfma_f32_32x32x16_bf16 v[112:127], v[128:131], v[144:147], v[112:127]
	v_mfma_f32_32x32x16_bf16 v[96:111], v[128:131], v[148:151], v[96:111]
	ds_read_b128 v[208:211], v254 offset:36896
	v_mfma_f32_32x32x16_bf16 v[80:95], v[132:135], v[144:147], v[80:95]
	ds_read_b128 v[212:215], v254 offset:41504
	v_mfma_f32_32x32x16_bf16 v[64:79], v[132:135], v[148:151], v[64:79]
	ds_read_b128 v[192:195], v175 offset:36896
	v_mfma_f32_32x32x16_bf16 v[48:63], v[136:139], v[144:147], v[48:63]
	v_mfma_f32_32x32x16_bf16 v[32:47], v[136:139], v[148:151], v[32:47]
	ds_read_b128 v[196:199], v175 offset:41504
	v_mfma_f32_32x32x16_bf16 v[16:31], v[140:143], v[144:147], v[16:31]
	ds_read_b128 v[200:203], v175 offset:46112
	v_mfma_f32_32x32x16_bf16 v[0:15], v[140:143], v[148:151], v[0:15]
	ds_read_b128 v[204:207], v175 offset:50720
	s_waitcnt lgkmcnt(0)
	v_mfma_f32_32x32x16_bf16 v[112:127], v[192:195], v[208:211], v[112:127]
	v_mfma_f32_32x32x16_bf16 v[96:111], v[192:195], v[212:215], v[96:111]
	ds_read_b128 v[144:147], v254 offset:36928
	v_mfma_f32_32x32x16_bf16 v[80:95], v[196:199], v[208:211], v[80:95]
	ds_read_b128 v[148:151], v254 offset:41536
	v_mfma_f32_32x32x16_bf16 v[64:79], v[196:199], v[212:215], v[64:79]
	ds_read_b128 v[128:131], v175 offset:36928
	v_mfma_f32_32x32x16_bf16 v[48:63], v[200:203], v[208:211], v[48:63]
	v_mfma_f32_32x32x16_bf16 v[32:47], v[200:203], v[212:215], v[32:47]
	ds_read_b128 v[132:135], v175 offset:41536
	v_mfma_f32_32x32x16_bf16 v[16:31], v[204:207], v[208:211], v[16:31]
	ds_read_b128 v[136:139], v175 offset:46144
	v_mfma_f32_32x32x16_bf16 v[0:15], v[204:207], v[212:215], v[0:15]
	ds_read_b128 v[140:143], v175 offset:50752
	s_waitcnt lgkmcnt(0)
	v_mfma_f32_32x32x16_bf16 v[112:127], v[128:131], v[144:147], v[112:127]
	v_mfma_f32_32x32x16_bf16 v[96:111], v[128:131], v[148:151], v[96:111]
	ds_read_b128 v[208:211], v254 offset:36960
	v_mfma_f32_32x32x16_bf16 v[80:95], v[132:135], v[144:147], v[80:95]
	ds_read_b128 v[212:215], v254 offset:41568
	v_mfma_f32_32x32x16_bf16 v[64:79], v[132:135], v[148:151], v[64:79]
	ds_read_b128 v[192:195], v175 offset:36960
	v_mfma_f32_32x32x16_bf16 v[48:63], v[136:139], v[144:147], v[48:63]
	v_mfma_f32_32x32x16_bf16 v[32:47], v[136:139], v[148:151], v[32:47]
	ds_read_b128 v[196:199], v175 offset:41568
	v_mfma_f32_32x32x16_bf16 v[16:31], v[140:143], v[144:147], v[16:31]
	ds_read_b128 v[200:203], v175 offset:46176
	v_mfma_f32_32x32x16_bf16 v[0:15], v[140:143], v[148:151], v[0:15]
	ds_read_b128 v[204:207], v175 offset:50784
	s_waitcnt lgkmcnt(0)
	s_barrier
	ds_read_b128 v[144:147], v254 offset:0
	ds_read_b128 v[148:151], v254 offset:4608
	ds_read_b128 v[128:131], v175 offset:0
	ds_read_b128 v[132:135], v175 offset:4608
	ds_read_b128 v[136:139], v175 offset:9216
	ds_read_b128 v[140:143], v175 offset:13824
	v_mfma_f32_32x32x16_bf16 v[112:127], v[192:195], v[208:211], v[112:127]
	s_waitcnt vmcnt(0)
	v_mfma_f32_32x32x16_bf16 v[96:111], v[192:195], v[212:215], v[96:111]
	ds_write_b128 v170, v[162:165] offset:36864
	v_mfma_f32_32x32x16_bf16 v[80:95], v[196:199], v[208:211], v[80:95]
	ds_write_b128 v170, v[166:169] offset:46080
	v_mfma_f32_32x32x16_bf16 v[64:79], v[196:199], v[212:215], v[64:79]
	ds_write_b128 v170, v[176:179] offset:55296
	v_mfma_f32_32x32x16_bf16 v[48:63], v[200:203], v[208:211], v[48:63]
	ds_write_b128 v170, v[180:183] offset:64512
	v_mfma_f32_32x32x16_bf16 v[32:47], v[200:203], v[212:215], v[32:47]
	ds_write_b128 v171, v[184:187] offset:36864
	v_mfma_f32_32x32x16_bf16 v[16:31], v[204:207], v[208:211], v[16:31]
	ds_write_b128 v171, v[242:245] offset:46080
	v_mfma_f32_32x32x16_bf16 v[0:15], v[204:207], v[212:215], v[0:15]
	ds_write_b128 v171, v[246:249] offset:55296
	ds_write_b128 v171, v[250:253] offset:64512
	s_waitcnt lgkmcnt(8)
	v_mfma_f32_32x32x16_bf16 v[112:127], v[128:131], v[144:147], v[112:127]
	v_mfma_f32_32x32x16_bf16 v[96:111], v[128:131], v[148:151], v[96:111]
	ds_read_b128 v[208:211], v254 offset:32
	v_mfma_f32_32x32x16_bf16 v[80:95], v[132:135], v[144:147], v[80:95]
	ds_read_b128 v[212:215], v254 offset:4640
	v_mfma_f32_32x32x16_bf16 v[64:79], v[132:135], v[148:151], v[64:79]
	ds_read_b128 v[192:195], v175 offset:32
	v_mfma_f32_32x32x16_bf16 v[48:63], v[136:139], v[144:147], v[48:63]
	v_mfma_f32_32x32x16_bf16 v[32:47], v[136:139], v[148:151], v[32:47]
	ds_read_b128 v[196:199], v175 offset:4640
	v_mfma_f32_32x32x16_bf16 v[16:31], v[140:143], v[144:147], v[16:31]
	ds_read_b128 v[200:203], v175 offset:9248
	v_mfma_f32_32x32x16_bf16 v[0:15], v[140:143], v[148:151], v[0:15]
	ds_read_b128 v[204:207], v175 offset:13856
	s_waitcnt lgkmcnt(0)
	v_mfma_f32_32x32x16_bf16 v[112:127], v[192:195], v[208:211], v[112:127]
	v_mfma_f32_32x32x16_bf16 v[96:111], v[192:195], v[212:215], v[96:111]
	ds_read_b128 v[144:147], v254 offset:64
	v_mfma_f32_32x32x16_bf16 v[80:95], v[196:199], v[208:211], v[80:95]
	ds_read_b128 v[148:151], v254 offset:4672
	v_mfma_f32_32x32x16_bf16 v[64:79], v[196:199], v[212:215], v[64:79]
	ds_read_b128 v[128:131], v175 offset:64
	v_mfma_f32_32x32x16_bf16 v[48:63], v[200:203], v[208:211], v[48:63]
	v_mfma_f32_32x32x16_bf16 v[32:47], v[200:203], v[212:215], v[32:47]
	ds_read_b128 v[132:135], v175 offset:4672
	v_mfma_f32_32x32x16_bf16 v[16:31], v[204:207], v[208:211], v[16:31]
	ds_read_b128 v[136:139], v175 offset:9280
	v_mfma_f32_32x32x16_bf16 v[0:15], v[204:207], v[212:215], v[0:15]
	ds_read_b128 v[140:143], v175 offset:13888
	s_waitcnt lgkmcnt(0)
	v_mfma_f32_32x32x16_bf16 v[112:127], v[128:131], v[144:147], v[112:127]
	v_mfma_f32_32x32x16_bf16 v[96:111], v[128:131], v[148:151], v[96:111]
	ds_read_b128 v[208:211], v254 offset:96
	v_mfma_f32_32x32x16_bf16 v[80:95], v[132:135], v[144:147], v[80:95]
	ds_read_b128 v[212:215], v254 offset:4704
	v_mfma_f32_32x32x16_bf16 v[64:79], v[132:135], v[148:151], v[64:79]
	ds_read_b128 v[192:195], v175 offset:96
	v_mfma_f32_32x32x16_bf16 v[48:63], v[136:139], v[144:147], v[48:63]
	v_mfma_f32_32x32x16_bf16 v[32:47], v[136:139], v[148:151], v[32:47]
	ds_read_b128 v[196:199], v175 offset:4704
	v_mfma_f32_32x32x16_bf16 v[16:31], v[140:143], v[144:147], v[16:31]
	ds_read_b128 v[200:203], v175 offset:9312
	v_mfma_f32_32x32x16_bf16 v[0:15], v[140:143], v[148:151], v[0:15]
	ds_read_b128 v[204:207], v175 offset:13920
	s_waitcnt lgkmcnt(0)
	s_barrier
	ds_read_b128 v[144:147], v254 offset:36864
	ds_read_b128 v[148:151], v254 offset:41472
	ds_read_b128 v[128:131], v175 offset:36864
	ds_read_b128 v[132:135], v175 offset:41472
	ds_read_b128 v[136:139], v175 offset:46080
	ds_read_b128 v[140:143], v175 offset:50688
	v_mfma_f32_32x32x16_bf16 v[112:127], v[192:195], v[208:211], v[112:127]
	v_mfma_f32_32x32x16_bf16 v[96:111], v[192:195], v[212:215], v[96:111]
	v_mfma_f32_32x32x16_bf16 v[80:95], v[196:199], v[208:211], v[80:95]
	v_mfma_f32_32x32x16_bf16 v[64:79], v[196:199], v[212:215], v[64:79]
	v_mfma_f32_32x32x16_bf16 v[48:63], v[200:203], v[208:211], v[48:63]
	v_mfma_f32_32x32x16_bf16 v[32:47], v[200:203], v[212:215], v[32:47]
	v_mfma_f32_32x32x16_bf16 v[16:31], v[204:207], v[208:211], v[16:31]
	v_mfma_f32_32x32x16_bf16 v[0:15], v[204:207], v[212:215], v[0:15]
	s_waitcnt lgkmcnt(0)
	v_mfma_f32_32x32x16_bf16 v[112:127], v[128:131], v[144:147], v[112:127]
	v_mfma_f32_32x32x16_bf16 v[96:111], v[128:131], v[148:151], v[96:111]
	ds_read_b128 v[208:211], v254 offset:36896
	v_mfma_f32_32x32x16_bf16 v[80:95], v[132:135], v[144:147], v[80:95]
	ds_read_b128 v[212:215], v254 offset:41504
	v_mfma_f32_32x32x16_bf16 v[64:79], v[132:135], v[148:151], v[64:79]
	ds_read_b128 v[192:195], v175 offset:36896
	v_mfma_f32_32x32x16_bf16 v[48:63], v[136:139], v[144:147], v[48:63]
	v_mfma_f32_32x32x16_bf16 v[32:47], v[136:139], v[148:151], v[32:47]
	ds_read_b128 v[196:199], v175 offset:41504
	v_mfma_f32_32x32x16_bf16 v[16:31], v[140:143], v[144:147], v[16:31]
	ds_read_b128 v[200:203], v175 offset:46112
	v_mfma_f32_32x32x16_bf16 v[0:15], v[140:143], v[148:151], v[0:15]
	ds_read_b128 v[204:207], v175 offset:50720
	s_waitcnt lgkmcnt(0)
	v_mfma_f32_32x32x16_bf16 v[112:127], v[192:195], v[208:211], v[112:127]
	v_mfma_f32_32x32x16_bf16 v[96:111], v[192:195], v[212:215], v[96:111]
	ds_read_b128 v[144:147], v254 offset:36928
	v_mfma_f32_32x32x16_bf16 v[80:95], v[196:199], v[208:211], v[80:95]
	ds_read_b128 v[148:151], v254 offset:41536
	v_mfma_f32_32x32x16_bf16 v[64:79], v[196:199], v[212:215], v[64:79]
	ds_read_b128 v[128:131], v175 offset:36928
	v_mfma_f32_32x32x16_bf16 v[48:63], v[200:203], v[208:211], v[48:63]
	v_mfma_f32_32x32x16_bf16 v[32:47], v[200:203], v[212:215], v[32:47]
	ds_read_b128 v[132:135], v175 offset:41536
	v_mfma_f32_32x32x16_bf16 v[16:31], v[204:207], v[208:211], v[16:31]
	ds_read_b128 v[136:139], v175 offset:46144
	v_mfma_f32_32x32x16_bf16 v[0:15], v[204:207], v[212:215], v[0:15]
	ds_read_b128 v[140:143], v175 offset:50752
	s_waitcnt lgkmcnt(0)
	v_mfma_f32_32x32x16_bf16 v[112:127], v[128:131], v[144:147], v[112:127]
	v_mfma_f32_32x32x16_bf16 v[96:111], v[128:131], v[148:151], v[96:111]
	ds_read_b128 v[208:211], v254 offset:36960
	v_mfma_f32_32x32x16_bf16 v[80:95], v[132:135], v[144:147], v[80:95]
	ds_read_b128 v[212:215], v254 offset:41568
	v_mfma_f32_32x32x16_bf16 v[64:79], v[132:135], v[148:151], v[64:79]
	ds_read_b128 v[192:195], v175 offset:36960
	v_mfma_f32_32x32x16_bf16 v[48:63], v[136:139], v[144:147], v[48:63]
	v_mfma_f32_32x32x16_bf16 v[32:47], v[136:139], v[148:151], v[32:47]
	ds_read_b128 v[196:199], v175 offset:41568
	v_mfma_f32_32x32x16_bf16 v[16:31], v[140:143], v[144:147], v[16:31]
	ds_read_b128 v[200:203], v175 offset:46176
	v_mfma_f32_32x32x16_bf16 v[0:15], v[140:143], v[148:151], v[0:15]
	ds_read_b128 v[204:207], v175 offset:50784
	s_waitcnt lgkmcnt(0)
	s_barrier
	v_mfma_f32_32x32x16_bf16 v[112:127], v[192:195], v[208:211], v[112:127]
	v_mfma_f32_32x32x16_bf16 v[96:111], v[192:195], v[212:215], v[96:111]
	v_mfma_f32_32x32x16_bf16 v[80:95], v[196:199], v[208:211], v[80:95]
	v_mfma_f32_32x32x16_bf16 v[64:79], v[196:199], v[212:215], v[64:79]
	v_mfma_f32_32x32x16_bf16 v[48:63], v[200:203], v[208:211], v[48:63]
	v_mfma_f32_32x32x16_bf16 v[32:47], v[200:203], v[212:215], v[32:47]
	v_mfma_f32_32x32x16_bf16 v[16:31], v[204:207], v[208:211], v[16:31]
	v_mfma_f32_32x32x16_bf16 v[0:15], v[204:207], v[212:215], v[0:15]
	s_nop 7
	s_nop 7
	s_cmp_lt_u32 s6, 0x2000
	s_cbranch_scc1 .Lo0_prompt
	s_sub_u32 s10, s6, 0x2000
	s_lshr_b32 s11, s10, 12
	s_add_u32 s11, s11, 1
	v_readlane_b32 s8, v241, 21
	v_readlane_b32 s9, v241, 22
	s_branch .Lo0_join

.LBB0_1415:
.Lgwq0_tile:
	s_bfe_u32 s100, s39, 0x30005
	s_and_b32 s101, s39, 31
	s_lshr_b32 s82, s39, 8
	s_lshl_b32 s64, s82, 5
	s_lshr_b32 s82, s100, 1
	s_lshl_b32 s82, s82, 3
	s_add_u32 s64, s64, s82
	s_lshr_b32 s82, s101, 2
	s_add_u32 s64, s64, s82
	s_and_b32 s82, s100, 1
	s_lshl_b32 s82, s82, 2
	s_and_b32 s101, s101, 3
	s_add_u32 s82, s82, s101
	s_lshl_b32 s64, s64, 8
	s_lshl_b32 s82, s82, 8
	s_lshl_b32 s100, s64, 12
	s_add_u32 s100, s100, 0x6224000
	s_add_u32 s48, s92, s100
	s_addc_u32 s49, s93, 0
	s_and_b32 s49, s49, 0xffff
	s_mov_b32 s50, 0x100000
	s_mov_b32 s51, 0x20000
	s_lshl_b32 s100, s82, 12
	s_add_u32 s100, s100, 0x3b80000
	s_add_u32 s52, s92, s100
	s_addc_u32 s53, s93, 0
	s_and_b32 s53, s53, 0xffff
	s_sub_u32 s100, 0x800, s82
	s_min_u32 s100, s100, 0x100
	s_lshl_b32 s54, s100, 12
	s_mov_b32 s55, 0x20000
	s_mov_b32 s46, 0x40000
	s_mov_b32 s47, 0x80000
	s_mov_b32 s58, 0xc0000
	v_lshrrev_b32_e32 v128, 3, v190
	v_and_b32_e32 v129, 7, v190
	v_lshlrev_b32_e32 v129, 4, v129
	v_lshl_add_u32 v160, v128, 12, v129
	v_mul_u32_u24_e32 v130, 0x90, v128
	v_add_u32_e32 v170, v130, v129
	v_add_u32_e32 v171, 0x12000, v170
	v_and_b32_e32 v131, 31, v190
	v_bfe_u32 v132, v190, 5, 1
	v_bfe_u32 v133, v190, 6, 2
	v_bfe_u32 v134, v190, 8, 1
	v_lshl_add_u32 v135, v134, 7, v131
	v_mul_u32_u24_e32 v135, 0x90, v135
	v_lshl_add_u32 v175, v132, 4, v135
	v_lshl_add_u32 v136, v133, 6, v131
	v_mul_u32_u24_e32 v136, 0x90, v136
	v_lshl_add_u32 v136, v132, 4, v136
	v_add_u32_e32 v254, 0x12000, v136
	v_mov_b32_e32 v0, 0
	v_mov_b32_e32 v1, 0
	v_mov_b32_e32 v2, 0
	v_mov_b32_e32 v3, 0
	v_mov_b32_e32 v4, 0
	v_mov_b32_e32 v5, 0
	v_mov_b32_e32 v6, 0
	v_mov_b32_e32 v7, 0
	v_mov_b32_e32 v8, 0
	v_mov_b32_e32 v9, 0
	v_mov_b32_e32 v10, 0
	v_mov_b32_e32 v11, 0
	v_mov_b32_e32 v12, 0
	v_mov_b32_e32 v13, 0
	v_mov_b32_e32 v14, 0
	v_mov_b32_e32 v15, 0
	v_mov_b32_e32 v16, 0
	v_mov_b32_e32 v17, 0
	v_mov_b32_e32 v18, 0
	v_mov_b32_e32 v19, 0
	v_mov_b32_e32 v20, 0
	v_mov_b32_e32 v21, 0
	v_mov_b32_e32 v22, 0
	v_mov_b32_e32 v23, 0
	v_mov_b32_e32 v24, 0
	v_mov_b32_e32 v25, 0
	v_mov_b32_e32 v26, 0
	v_mov_b32_e32 v27, 0
	v_mov_b32_e32 v28, 0
	v_mov_b32_e32 v29, 0
	v_mov_b32_e32 v30, 0
	v_mov_b32_e32 v31, 0
	v_mov_b32_e32 v32, 0
	v_mov_b32_e32 v33, 0
	v_mov_b32_e32 v34, 0
	v_mov_b32_e32 v35, 0
	v_mov_b32_e32 v36, 0
	v_mov_b32_e32 v37, 0
	v_mov_b32_e32 v38, 0
	v_mov_b32_e32 v39, 0
	v_mov_b32_e32 v40, 0
	v_mov_b32_e32 v41, 0
	v_mov_b32_e32 v42, 0
	v_mov_b32_e32 v43, 0
	v_mov_b32_e32 v44, 0
	v_mov_b32_e32 v45, 0
	v_mov_b32_e32 v46, 0
	v_mov_b32_e32 v47, 0
	v_mov_b32_e32 v48, 0
	v_mov_b32_e32 v49, 0
	v_mov_b32_e32 v50, 0
	v_mov_b32_e32 v51, 0
	v_mov_b32_e32 v52, 0
	v_mov_b32_e32 v53, 0
	v_mov_b32_e32 v54, 0
	v_mov_b32_e32 v55, 0
	v_mov_b32_e32 v56, 0
	v_mov_b32_e32 v57, 0
	v_mov_b32_e32 v58, 0
	v_mov_b32_e32 v59, 0
	v_mov_b32_e32 v60, 0
	v_mov_b32_e32 v61, 0
	v_mov_b32_e32 v62, 0
	v_mov_b32_e32 v63, 0
	v_mov_b32_e32 v64, 0
	v_mov_b32_e32 v65, 0
	v_mov_b32_e32 v66, 0
	v_mov_b32_e32 v67, 0
	v_mov_b32_e32 v68, 0
	v_mov_b32_e32 v69, 0
	v_mov_b32_e32 v70, 0
	v_mov_b32_e32 v71, 0
	v_mov_b32_e32 v72, 0
	v_mov_b32_e32 v73, 0
	v_mov_b32_e32 v74, 0
	v_mov_b32_e32 v75, 0
	v_mov_b32_e32 v76, 0
	v_mov_b32_e32 v77, 0
	v_mov_b32_e32 v78, 0
	v_mov_b32_e32 v79, 0
	v_mov_b32_e32 v80, 0
	v_mov_b32_e32 v81, 0
	v_mov_b32_e32 v82, 0
	v_mov_b32_e32 v83, 0
	v_mov_b32_e32 v84, 0
	v_mov_b32_e32 v85, 0
	v_mov_b32_e32 v86, 0
	v_mov_b32_e32 v87, 0
	v_mov_b32_e32 v88, 0
	v_mov_b32_e32 v89, 0
	v_mov_b32_e32 v90, 0
	v_mov_b32_e32 v91, 0
	v_mov_b32_e32 v92, 0
	v_mov_b32_e32 v93, 0
	v_mov_b32_e32 v94, 0
	v_mov_b32_e32 v95, 0
	v_mov_b32_e32 v96, 0
	v_mov_b32_e32 v97, 0
	v_mov_b32_e32 v98, 0
	v_mov_b32_e32 v99, 0
	v_mov_b32_e32 v100, 0
	v_mov_b32_e32 v101, 0
	v_mov_b32_e32 v102, 0
	v_mov_b32_e32 v103, 0
	v_mov_b32_e32 v104, 0
	v_mov_b32_e32 v105, 0
	v_mov_b32_e32 v106, 0
	v_mov_b32_e32 v107, 0
	v_mov_b32_e32 v108, 0
	v_mov_b32_e32 v109, 0
	v_mov_b32_e32 v110, 0
	v_mov_b32_e32 v111, 0
	v_mov_b32_e32 v112, 0
	v_mov_b32_e32 v113, 0
	v_mov_b32_e32 v114, 0
	v_mov_b32_e32 v115, 0
	v_mov_b32_e32 v116, 0
	v_mov_b32_e32 v117, 0
	v_mov_b32_e32 v118, 0
	v_mov_b32_e32 v119, 0
	v_mov_b32_e32 v120, 0
	v_mov_b32_e32 v121, 0
	v_mov_b32_e32 v122, 0
	v_mov_b32_e32 v123, 0
	v_mov_b32_e32 v124, 0
	v_mov_b32_e32 v125, 0
	v_mov_b32_e32 v126, 0
	v_mov_b32_e32 v127, 0
	v_mov_b32_e32 v192, 0
	v_mov_b32_e32 v193, 0
	v_mov_b32_e32 v194, 0
	v_mov_b32_e32 v195, 0
	v_mov_b32_e32 v196, 0
	v_mov_b32_e32 v197, 0
	v_mov_b32_e32 v198, 0
	v_mov_b32_e32 v199, 0
	v_mov_b32_e32 v200, 0
	v_mov_b32_e32 v201, 0
	v_mov_b32_e32 v202, 0
	v_mov_b32_e32 v203, 0
	v_mov_b32_e32 v204, 0
	v_mov_b32_e32 v205, 0
	v_mov_b32_e32 v206, 0
	v_mov_b32_e32 v207, 0
	v_mov_b32_e32 v208, 0
	v_mov_b32_e32 v209, 0
	v_mov_b32_e32 v210, 0
	v_mov_b32_e32 v211, 0
	v_mov_b32_e32 v212, 0
	v_mov_b32_e32 v213, 0
	v_mov_b32_e32 v214, 0
	v_mov_b32_e32 v215, 0
	v_mov_b32_e32 v188, 0
	v_mov_b32_e32 v189, 0
	buffer_load_dwordx4 v[216:219], v160, s[48:51], 0 offen
	buffer_load_dwordx4 v[220:223], v160, s[48:51], s46 offen
	buffer_load_dwordx4 v[224:227], v160, s[48:51], s47 offen
	buffer_load_dwordx4 v[228:231], v160, s[48:51], s58 offen
	buffer_load_dwordx4 v[232:235], v160, s[52:55], 0 offen
	buffer_load_dwordx4 v[236:239], v160, s[52:55], s46 offen
	buffer_load_dwordx4 v[152:155], v160, s[52:55], s47 offen
	buffer_load_dwordx4 v[156:159], v160, s[52:55], s58 offen
	v_add_u32_e32 v160, 0x80, v160
	buffer_load_dwordx4 v[162:165], v160, s[48:51], 0 offen
	buffer_load_dwordx4 v[166:169], v160, s[48:51], s46 offen
	buffer_load_dwordx4 v[176:179], v160, s[48:51], s47 offen
	buffer_load_dwordx4 v[180:183], v160, s[48:51], s58 offen
	buffer_load_dwordx4 v[184:187], v160, s[52:55], 0 offen
	buffer_load_dwordx4 v[242:245], v160, s[52:55], s46 offen
	buffer_load_dwordx4 v[246:249], v160, s[52:55], s47 offen
	buffer_load_dwordx4 v[250:253], v160, s[52:55], s58 offen
	v_add_u32_e32 v160, 0x80, v160
	s_waitcnt vmcnt(8)
	ds_write_b128 v170, v[216:219] offset:0
	ds_write_b128 v170, v[220:223] offset:9216
	ds_write_b128 v170, v[224:227] offset:18432
	ds_write_b128 v170, v[228:231] offset:27648
	ds_write_b128 v171, v[232:235] offset:0
	ds_write_b128 v171, v[236:239] offset:9216
	ds_write_b128 v171, v[152:155] offset:18432
	ds_write_b128 v171, v[156:159] offset:27648
	buffer_load_dwordx4 v[216:219], v160, s[48:51], 0 offen
	buffer_load_dwordx4 v[220:223], v160, s[48:51], s46 offen
	buffer_load_dwordx4 v[224:227], v160, s[48:51], s47 offen
	buffer_load_dwordx4 v[228:231], v160, s[48:51], s58 offen
	buffer_load_dwordx4 v[232:235], v160, s[52:55], 0 offen
	buffer_load_dwordx4 v[236:239], v160, s[52:55], s46 offen
	buffer_load_dwordx4 v[152:155], v160, s[52:55], s47 offen
	buffer_load_dwordx4 v[156:159], v160, s[52:55], s58 offen
	v_add_u32_e32 v160, 0x80, v160
	s_waitcnt lgkmcnt(0)
	s_barrier
	s_movk_i32 s59, 14
.Lgwq0_loop:
	ds_read_b128 v[144:147], v254 offset:0
	ds_read_b128 v[148:151], v254 offset:4608
	ds_read_b128 v[128:131], v175 offset:0
	ds_read_b128 v[132:135], v175 offset:4608
	ds_read_b128 v[136:139], v175 offset:9216
	ds_read_b128 v[140:143], v175 offset:13824
	v_mfma_f32_32x32x16_bf16 v[112:127], v[192:195], v[208:211], v[112:127]
	s_waitcnt vmcnt(8)
	v_mfma_f32_32x32x16_bf16 v[96:111], v[192:195], v[212:215], v[96:111]
	ds_write_b128 v170, v[162:165] offset:36864
	v_mfma_f32_32x32x16_bf16 v[80:95], v[196:199], v[208:211], v[80:95]
	ds_write_b128 v170, v[166:169] offset:46080
	v_mfma_f32_32x32x16_bf16 v[64:79], v[196:199], v[212:215], v[64:79]
	ds_write_b128 v170, v[176:179] offset:55296
	v_mfma_f32_32x32x16_bf16 v[48:63], v[200:203], v[208:211], v[48:63]
	ds_write_b128 v170, v[180:183] offset:64512
	v_mfma_f32_32x32x16_bf16 v[32:47], v[200:203], v[212:215], v[32:47]
	ds_write_b128 v171, v[184:187] offset:36864
	v_mfma_f32_32x32x16_bf16 v[16:31], v[204:207], v[208:211], v[16:31]
	ds_write_b128 v171, v[242:245] offset:46080
	v_mfma_f32_32x32x16_bf16 v[0:15], v[204:207], v[212:215], v[0:15]
	ds_write_b128 v171, v[246:249] offset:55296
	ds_write_b128 v171, v[250:253] offset:64512
	s_waitcnt lgkmcnt(8)
	v_mfma_f32_32x32x16_bf16 v[112:127], v[128:131], v[144:147], v[112:127]
	ds_read_b128 v[208:211], v254 offset:32
	v_mfma_f32_32x32x16_bf16 v[96:111], v[128:131], v[148:151], v[96:111]
	ds_read_b128 v[212:215], v254 offset:4640
	ds_read_b128 v[192:195], v175 offset:32
	v_mfma_f32_32x32x16_bf16 v[80:95], v[132:135], v[144:147], v[80:95]
	ds_read_b128 v[196:199], v175 offset:4640
	ds_read_b128 v[200:203], v175 offset:9248
	v_mfma_f32_32x32x16_bf16 v[64:79], v[132:135], v[148:151], v[64:79]
	ds_read_b128 v[204:207], v175 offset:13856
	buffer_load_dwordx4 v[162:165], v160, s[48:51], 0 offen
	v_mfma_f32_32x32x16_bf16 v[48:63], v[136:139], v[144:147], v[48:63]
	buffer_load_dwordx4 v[166:169], v160, s[48:51], s46 offen
	buffer_load_dwordx4 v[176:179], v160, s[48:51], s47 offen
	v_mfma_f32_32x32x16_bf16 v[32:47], v[136:139], v[148:151], v[32:47]
	buffer_load_dwordx4 v[180:183], v160, s[48:51], s58 offen
	buffer_load_dwordx4 v[184:187], v160, s[52:55], 0 offen
	v_mfma_f32_32x32x16_bf16 v[16:31], v[140:143], v[144:147], v[16:31]
	buffer_load_dwordx4 v[242:245], v160, s[52:55], s46 offen
	buffer_load_dwordx4 v[246:249], v160, s[52:55], s47 offen
	v_mfma_f32_32x32x16_bf16 v[0:15], v[140:143], v[148:151], v[0:15]
	buffer_load_dwordx4 v[250:253], v160, s[52:55], s58 offen
	v_add_u32_e32 v160, 0x80, v160
	s_waitcnt lgkmcnt(0)
	v_mfma_f32_32x32x16_bf16 v[112:127], v[192:195], v[208:211], v[112:127]
	v_mfma_f32_32x32x16_bf16 v[96:111], v[192:195], v[212:215], v[96:111]
	ds_read_b128 v[144:147], v254 offset:64
	v_mfma_f32_32x32x16_bf16 v[80:95], v[196:199], v[208:211], v[80:95]
	ds_read_b128 v[148:151], v254 offset:4672
	v_mfma_f32_32x32x16_bf16 v[64:79], v[196:199], v[212:215], v[64:79]
	ds_read_b128 v[128:131], v175 offset:64
	v_mfma_f32_32x32x16_bf16 v[48:63], v[200:203], v[208:211], v[48:63]
	v_mfma_f32_32x32x16_bf16 v[32:47], v[200:203], v[212:215], v[32:47]
	ds_read_b128 v[132:135], v175 offset:4672
	v_mfma_f32_32x32x16_bf16 v[16:31], v[204:207], v[208:211], v[16:31]
	ds_read_b128 v[136:139], v175 offset:9280
	v_mfma_f32_32x32x16_bf16 v[0:15], v[204:207], v[212:215], v[0:15]
	ds_read_b128 v[140:143], v175 offset:13888
	s_waitcnt lgkmcnt(0)
	v_mfma_f32_32x32x16_bf16 v[112:127], v[128:131], v[144:147], v[112:127]
	v_mfma_f32_32x32x16_bf16 v[96:111], v[128:131], v[148:151], v[96:111]
	ds_read_b128 v[208:211], v254 offset:96
	v_mfma_f32_32x32x16_bf16 v[80:95], v[132:135], v[144:147], v[80:95]
	ds_read_b128 v[212:215], v254 offset:4704
	v_mfma_f32_32x32x16_bf16 v[64:79], v[132:135], v[148:151], v[64:79]
	ds_read_b128 v[192:195], v175 offset:96
	v_mfma_f32_32x32x16_bf16 v[48:63], v[136:139], v[144:147], v[48:63]
	v_mfma_f32_32x32x16_bf16 v[32:47], v[136:139], v[148:151], v[32:47]
	ds_read_b128 v[196:199], v175 offset:4704
	v_mfma_f32_32x32x16_bf16 v[16:31], v[140:143], v[144:147], v[16:31]
	ds_read_b128 v[200:203], v175 offset:9312
	v_mfma_f32_32x32x16_bf16 v[0:15], v[140:143], v[148:151], v[0:15]
	ds_read_b128 v[204:207], v175 offset:13920
	s_waitcnt lgkmcnt(0)
	s_barrier
	ds_read_b128 v[144:147], v254 offset:36864
	ds_read_b128 v[148:151], v254 offset:41472
	ds_read_b128 v[128:131], v175 offset:36864
	ds_read_b128 v[132:135], v175 offset:41472
	ds_read_b128 v[136:139], v175 offset:46080
	ds_read_b128 v[140:143], v175 offset:50688
	v_mfma_f32_32x32x16_bf16 v[112:127], v[192:195], v[208:211], v[112:127]
	s_waitcnt vmcnt(8)
	v_mfma_f32_32x32x16_bf16 v[96:111], v[192:195], v[212:215], v[96:111]
	ds_write_b128 v170, v[216:219] offset:0
	v_mfma_f32_32x32x16_bf16 v[80:95], v[196:199], v[208:211], v[80:95]
	ds_write_b128 v170, v[220:223] offset:9216
	v_mfma_f32_32x32x16_bf16 v[64:79], v[196:199], v[212:215], v[64:79]
	ds_write_b128 v170, v[224:227] offset:18432
	v_mfma_f32_32x32x16_bf16 v[48:63], v[200:203], v[208:211], v[48:63]
	ds_write_b128 v170, v[228:231] offset:27648
	v_mfma_f32_32x32x16_bf16 v[32:47], v[200:203], v[212:215], v[32:47]
	ds_write_b128 v171, v[232:235] offset:0
	v_mfma_f32_32x32x16_bf16 v[16:31], v[204:207], v[208:211], v[16:31]
	ds_write_b128 v171, v[236:239] offset:9216
	v_mfma_f32_32x32x16_bf16 v[0:15], v[204:207], v[212:215], v[0:15]
	ds_write_b128 v171, v[152:155] offset:18432
	ds_write_b128 v171, v[156:159] offset:27648
	s_waitcnt lgkmcnt(8)
	v_mfma_f32_32x32x16_bf16 v[112:127], v[128:131], v[144:147], v[112:127]
	ds_read_b128 v[208:211], v254 offset:36896
	v_mfma_f32_32x32x16_bf16 v[96:111], v[128:131], v[148:151], v[96:111]
	ds_read_b128 v[212:215], v254 offset:41504
	ds_read_b128 v[192:195], v175 offset:36896
	v_mfma_f32_32x32x16_bf16 v[80:95], v[132:135], v[144:147], v[80:95]
	ds_read_b128 v[196:199], v175 offset:41504
	ds_read_b128 v[200:203], v175 offset:46112
	v_mfma_f32_32x32x16_bf16 v[64:79], v[132:135], v[148:151], v[64:79]
	ds_read_b128 v[204:207], v175 offset:50720
	buffer_load_dwordx4 v[216:219], v160, s[48:51], 0 offen
	v_mfma_f32_32x32x16_bf16 v[48:63], v[136:139], v[144:147], v[48:63]
	buffer_load_dwordx4 v[220:223], v160, s[48:51], s46 offen
	buffer_load_dwordx4 v[224:227], v160, s[48:51], s47 offen
	v_mfma_f32_32x32x16_bf16 v[32:47], v[136:139], v[148:151], v[32:47]
	buffer_load_dwordx4 v[228:231], v160, s[48:51], s58 offen
	buffer_load_dwordx4 v[232:235], v160, s[52:55], 0 offen
	v_mfma_f32_32x32x16_bf16 v[16:31], v[140:143], v[144:147], v[16:31]
	buffer_load_dwordx4 v[236:239], v160, s[52:55], s46 offen
	buffer_load_dwordx4 v[152:155], v160, s[52:55], s47 offen
	v_mfma_f32_32x32x16_bf16 v[0:15], v[140:143], v[148:151], v[0:15]
	buffer_load_dwordx4 v[156:159], v160, s[52:55], s58 offen
	v_add_u32_e32 v160, 0x80, v160
	s_waitcnt lgkmcnt(0)
	v_mfma_f32_32x32x16_bf16 v[112:127], v[192:195], v[208:211], v[112:127]
	v_mfma_f32_32x32x16_bf16 v[96:111], v[192:195], v[212:215], v[96:111]
	ds_read_b128 v[144:147], v254 offset:36928
	v_mfma_f32_32x32x16_bf16 v[80:95], v[196:199], v[208:211], v[80:95]
	ds_read_b128 v[148:151], v254 offset:41536
	v_mfma_f32_32x32x16_bf16 v[64:79], v[196:199], v[212:215], v[64:79]
	ds_read_b128 v[128:131], v175 offset:36928
	v_mfma_f32_32x32x16_bf16 v[48:63], v[200:203], v[208:211], v[48:63]
	v_mfma_f32_32x32x16_bf16 v[32:47], v[200:203], v[212:215], v[32:47]
	ds_read_b128 v[132:135], v175 offset:41536
	v_mfma_f32_32x32x16_bf16 v[16:31], v[204:207], v[208:211], v[16:31]
	ds_read_b128 v[136:139], v175 offset:46144
	v_mfma_f32_32x32x16_bf16 v[0:15], v[204:207], v[212:215], v[0:15]
	ds_read_b128 v[140:143], v175 offset:50752
	s_waitcnt lgkmcnt(0)
	v_mfma_f32_32x32x16_bf16 v[112:127], v[128:131], v[144:147], v[112:127]
	v_mfma_f32_32x32x16_bf16 v[96:111], v[128:131], v[148:151], v[96:111]
	ds_read_b128 v[208:211], v254 offset:36960
	v_mfma_f32_32x32x16_bf16 v[80:95], v[132:135], v[144:147], v[80:95]
	ds_read_b128 v[212:215], v254 offset:41568
	v_mfma_f32_32x32x16_bf16 v[64:79], v[132:135], v[148:151], v[64:79]
	ds_read_b128 v[192:195], v175 offset:36960
	v_mfma_f32_32x32x16_bf16 v[48:63], v[136:139], v[144:147], v[48:63]
	v_mfma_f32_32x32x16_bf16 v[32:47], v[136:139], v[148:151], v[32:47]
	ds_read_b128 v[196:199], v175 offset:41568
	v_mfma_f32_32x32x16_bf16 v[16:31], v[140:143], v[144:147], v[16:31]
	ds_read_b128 v[200:203], v175 offset:46176
	v_mfma_f32_32x32x16_bf16 v[0:15], v[140:143], v[148:151], v[0:15]
	ds_read_b128 v[204:207], v175 offset:50784
	s_waitcnt lgkmcnt(0)
	s_barrier
	s_add_i32 s59, s59, -1
	s_cmp_lg_u32 s59, 0
	s_cbranch_scc1 .Lgwq0_loop
	ds_read_b128 v[144:147], v254 offset:0
	ds_read_b128 v[148:151], v254 offset:4608
	ds_read_b128 v[128:131], v175 offset:0
	ds_read_b128 v[132:135], v175 offset:4608
	ds_read_b128 v[136:139], v175 offset:9216
	ds_read_b128 v[140:143], v175 offset:13824
	v_mfma_f32_32x32x16_bf16 v[112:127], v[192:195], v[208:211], v[112:127]
	s_waitcnt vmcnt(8)
	v_mfma_f32_32x32x16_bf16 v[96:111], v[192:195], v[212:215], v[96:111]
	ds_write_b128 v170, v[162:165] offset:36864
	v_mfma_f32_32x32x16_bf16 v[80:95], v[196:199], v[208:211], v[80:95]
	ds_write_b128 v170, v[166:169] offset:46080
	v_mfma_f32_32x32x16_bf16 v[64:79], v[196:199], v[212:215], v[64:79]
	ds_write_b128 v170, v[176:179] offset:55296
	v_mfma_f32_32x32x16_bf16 v[48:63], v[200:203], v[208:211], v[48:63]
	ds_write_b128 v170, v[180:183] offset:64512
	v_mfma_f32_32x32x16_bf16 v[32:47], v[200:203], v[212:215], v[32:47]
	ds_write_b128 v171, v[184:187] offset:36864
	v_mfma_f32_32x32x16_bf16 v[16:31], v[204:207], v[208:211], v[16:31]
	ds_write_b128 v171, v[242:245] offset:46080
	v_mfma_f32_32x32x16_bf16 v[0:15], v[204:207], v[212:215], v[0:15]
	ds_write_b128 v171, v[246:249] offset:55296
	ds_write_b128 v171, v[250:253] offset:64512
	s_waitcnt lgkmcnt(8)
	v_mfma_f32_32x32x16_bf16 v[112:127], v[128:131], v[144:147], v[112:127]
	ds_read_b128 v[208:211], v254 offset:32
	v_mfma_f32_32x32x16_bf16 v[96:111], v[128:131], v[148:151], v[96:111]
	ds_read_b128 v[212:215], v254 offset:4640
	ds_read_b128 v[192:195], v175 offset:32
	v_mfma_f32_32x32x16_bf16 v[80:95], v[132:135], v[144:147], v[80:95]
	ds_read_b128 v[196:199], v175 offset:4640
	ds_read_b128 v[200:203], v175 offset:9248
	v_mfma_f32_32x32x16_bf16 v[64:79], v[132:135], v[148:151], v[64:79]
	ds_read_b128 v[204:207], v175 offset:13856
	buffer_load_dwordx4 v[162:165], v160, s[48:51], 0 offen
	v_mfma_f32_32x32x16_bf16 v[48:63], v[136:139], v[144:147], v[48:63]
	buffer_load_dwordx4 v[166:169], v160, s[48:51], s46 offen
	buffer_load_dwordx4 v[176:179], v160, s[48:51], s47 offen
	v_mfma_f32_32x32x16_bf16 v[32:47], v[136:139], v[148:151], v[32:47]
	buffer_load_dwordx4 v[180:183], v160, s[48:51], s58 offen
	buffer_load_dwordx4 v[184:187], v160, s[52:55], 0 offen
	v_mfma_f32_32x32x16_bf16 v[16:31], v[140:143], v[144:147], v[16:31]
	buffer_load_dwordx4 v[242:245], v160, s[52:55], s46 offen
	buffer_load_dwordx4 v[246:249], v160, s[52:55], s47 offen
	v_mfma_f32_32x32x16_bf16 v[0:15], v[140:143], v[148:151], v[0:15]
	buffer_load_dwordx4 v[250:253], v160, s[52:55], s58 offen
	v_add_u32_e32 v160, 0x80, v160
	s_waitcnt lgkmcnt(0)
	v_mfma_f32_32x32x16_bf16 v[112:127], v[192:195], v[208:211], v[112:127]
	v_mfma_f32_32x32x16_bf16 v[96:111], v[192:195], v[212:215], v[96:111]
	ds_read_b128 v[144:147], v254 offset:64
	v_mfma_f32_32x32x16_bf16 v[80:95], v[196:199], v[208:211], v[80:95]
	ds_read_b128 v[148:151], v254 offset:4672
	v_mfma_f32_32x32x16_bf16 v[64:79], v[196:199], v[212:215], v[64:79]
	ds_read_b128 v[128:131], v175 offset:64
	v_mfma_f32_32x32x16_bf16 v[48:63], v[200:203], v[208:211], v[48:63]
	v_mfma_f32_32x32x16_bf16 v[32:47], v[200:203], v[212:215], v[32:47]
	ds_read_b128 v[132:135], v175 offset:4672
	v_mfma_f32_32x32x16_bf16 v[16:31], v[204:207], v[208:211], v[16:31]
	ds_read_b128 v[136:139], v175 offset:9280
	v_mfma_f32_32x32x16_bf16 v[0:15], v[204:207], v[212:215], v[0:15]
	ds_read_b128 v[140:143], v175 offset:13888
	s_waitcnt lgkmcnt(0)
	v_mfma_f32_32x32x16_bf16 v[112:127], v[128:131], v[144:147], v[112:127]
	v_mfma_f32_32x32x16_bf16 v[96:111], v[128:131], v[148:151], v[96:111]
	ds_read_b128 v[208:211], v254 offset:96
	v_mfma_f32_32x32x16_bf16 v[80:95], v[132:135], v[144:147], v[80:95]
	ds_read_b128 v[212:215], v254 offset:4704
	v_mfma_f32_32x32x16_bf16 v[64:79], v[132:135], v[148:151], v[64:79]
	ds_read_b128 v[192:195], v175 offset:96
	v_mfma_f32_32x32x16_bf16 v[48:63], v[136:139], v[144:147], v[48:63]
	v_mfma_f32_32x32x16_bf16 v[32:47], v[136:139], v[148:151], v[32:47]
	ds_read_b128 v[196:199], v175 offset:4704
	v_mfma_f32_32x32x16_bf16 v[16:31], v[140:143], v[144:147], v[16:31]
	ds_read_b128 v[200:203], v175 offset:9312
	v_mfma_f32_32x32x16_bf16 v[0:15], v[140:143], v[148:151], v[0:15]
	ds_read_b128 v[204:207], v175 offset:13920
	s_waitcnt lgkmcnt(0)
	s_barrier
	ds_read_b128 v[144:147], v254 offset:36864
	ds_read_b128 v[148:151], v254 offset:41472
	ds_read_b128 v[128:131], v175 offset:36864
	ds_read_b128 v[132:135], v175 offset:41472
	ds_read_b128 v[136:139], v175 offset:46080
	ds_read_b128 v[140:143], v175 offset:50688
	v_mfma_f32_32x32x16_bf16 v[112:127], v[192:195], v[208:211], v[112:127]
	s_waitcnt vmcnt(8)
	v_mfma_f32_32x32x16_bf16 v[96:111], v[192:195], v[212:215], v[96:111]
	ds_write_b128 v170, v[216:219] offset:0
	v_mfma_f32_32x32x16_bf16 v[80:95], v[196:199], v[208:211], v[80:95]
	ds_write_b128 v170, v[220:223] offset:9216
	v_mfma_f32_32x32x16_bf16 v[64:79], v[196:199], v[212:215], v[64:79]
	ds_write_b128 v170, v[224:227] offset:18432
	v_mfma_f32_32x32x16_bf16 v[48:63], v[200:203], v[208:211], v[48:63]
	ds_write_b128 v170, v[228:231] offset:27648
	v_mfma_f32_32x32x16_bf16 v[32:47], v[200:203], v[212:215], v[32:47]
	ds_write_b128 v171, v[232:235] offset:0
	v_mfma_f32_32x32x16_bf16 v[16:31], v[204:207], v[208:211], v[16:31]
	ds_write_b128 v171, v[236:239] offset:9216
	v_mfma_f32_32x32x16_bf16 v[0:15], v[204:207], v[212:215], v[0:15]
	ds_write_b128 v171, v[152:155] offset:18432
	ds_write_b128 v171, v[156:159] offset:27648
	s_waitcnt lgkmcnt(8)
	v_mfma_f32_32x32x16_bf16 v[112:127], v[128:131], v[144:147], v[112:127]
	v_mfma_f32_32x32x16_bf16 v[96:111], v[128:131], v[148:151], v[96:111]
	ds_read_b128 v[208:211], v254 offset:36896
	v_mfma_f32_32x32x16_bf16 v[80:95], v[132:135], v[144:147], v[80:95]
	ds_read_b128 v[212:215], v254 offset:41504
	v_mfma_f32_32x32x16_bf16 v[64:79], v[132:135], v[148:151], v[64:79]
	ds_read_b128 v[192:195], v175 offset:36896
	v_mfma_f32_32x32x16_bf16 v[48:63], v[136:139], v[144:147], v[48:63]
	v_mfma_f32_32x32x16_bf16 v[32:47], v[136:139], v[148:151], v[32:47]
	ds_read_b128 v[196:199], v175 offset:41504
	v_mfma_f32_32x32x16_bf16 v[16:31], v[140:143], v[144:147], v[16:31]
	ds_read_b128 v[200:203], v175 offset:46112
	v_mfma_f32_32x32x16_bf16 v[0:15], v[140:143], v[148:151], v[0:15]
	ds_read_b128 v[204:207], v175 offset:50720
	s_waitcnt lgkmcnt(0)
	v_mfma_f32_32x32x16_bf16 v[112:127], v[192:195], v[208:211], v[112:127]
	v_mfma_f32_32x32x16_bf16 v[96:111], v[192:195], v[212:215], v[96:111]
	ds_read_b128 v[144:147], v254 offset:36928
	v_mfma_f32_32x32x16_bf16 v[80:95], v[196:199], v[208:211], v[80:95]
	ds_read_b128 v[148:151], v254 offset:41536
	v_mfma_f32_32x32x16_bf16 v[64:79], v[196:199], v[212:215], v[64:79]
	ds_read_b128 v[128:131], v175 offset:36928
	v_mfma_f32_32x32x16_bf16 v[48:63], v[200:203], v[208:211], v[48:63]
	v_mfma_f32_32x32x16_bf16 v[32:47], v[200:203], v[212:215], v[32:47]
	ds_read_b128 v[132:135], v175 offset:41536
	v_mfma_f32_32x32x16_bf16 v[16:31], v[204:207], v[208:211], v[16:31]
	ds_read_b128 v[136:139], v175 offset:46144
	v_mfma_f32_32x32x16_bf16 v[0:15], v[204:207], v[212:215], v[0:15]
	ds_read_b128 v[140:143], v175 offset:50752
	s_waitcnt lgkmcnt(0)
	v_mfma_f32_32x32x16_bf16 v[112:127], v[128:131], v[144:147], v[112:127]
	v_mfma_f32_32x32x16_bf16 v[96:111], v[128:131], v[148:151], v[96:111]
	ds_read_b128 v[208:211], v254 offset:36960
	v_mfma_f32_32x32x16_bf16 v[80:95], v[132:135], v[144:147], v[80:95]
	ds_read_b128 v[212:215], v254 offset:41568
	v_mfma_f32_32x32x16_bf16 v[64:79], v[132:135], v[148:151], v[64:79]
	ds_read_b128 v[192:195], v175 offset:36960
	v_mfma_f32_32x32x16_bf16 v[48:63], v[136:139], v[144:147], v[48:63]
	v_mfma_f32_32x32x16_bf16 v[32:47], v[136:139], v[148:151], v[32:47]
	ds_read_b128 v[196:199], v175 offset:41568
	v_mfma_f32_32x32x16_bf16 v[16:31], v[140:143], v[144:147], v[16:31]
	ds_read_b128 v[200:203], v175 offset:46176
	v_mfma_f32_32x32x16_bf16 v[0:15], v[140:143], v[148:151], v[0:15]
	ds_read_b128 v[204:207], v175 offset:50784
	s_waitcnt lgkmcnt(0)
	s_barrier
	ds_read_b128 v[144:147], v254 offset:0
	ds_read_b128 v[148:151], v254 offset:4608
	ds_read_b128 v[128:131], v175 offset:0
	ds_read_b128 v[132:135], v175 offset:4608
	ds_read_b128 v[136:139], v175 offset:9216
	ds_read_b128 v[140:143], v175 offset:13824
	v_mfma_f32_32x32x16_bf16 v[112:127], v[192:195], v[208:211], v[112:127]
	s_waitcnt vmcnt(0)
	v_mfma_f32_32x32x16_bf16 v[96:111], v[192:195], v[212:215], v[96:111]
	ds_write_b128 v170, v[162:165] offset:36864
	v_mfma_f32_32x32x16_bf16 v[80:95], v[196:199], v[208:211], v[80:95]
	ds_write_b128 v170, v[166:169] offset:46080
	v_mfma_f32_32x32x16_bf16 v[64:79], v[196:199], v[212:215], v[64:79]
	ds_write_b128 v170, v[176:179] offset:55296
	v_mfma_f32_32x32x16_bf16 v[48:63], v[200:203], v[208:211], v[48:63]
	ds_write_b128 v170, v[180:183] offset:64512
	v_mfma_f32_32x32x16_bf16 v[32:47], v[200:203], v[212:215], v[32:47]
	ds_write_b128 v171, v[184:187] offset:36864
	v_mfma_f32_32x32x16_bf16 v[16:31], v[204:207], v[208:211], v[16:31]
	ds_write_b128 v171, v[242:245] offset:46080
	v_mfma_f32_32x32x16_bf16 v[0:15], v[204:207], v[212:215], v[0:15]
	ds_write_b128 v171, v[246:249] offset:55296
	ds_write_b128 v171, v[250:253] offset:64512
	s_waitcnt lgkmcnt(8)
	v_mfma_f32_32x32x16_bf16 v[112:127], v[128:131], v[144:147], v[112:127]
	v_mfma_f32_32x32x16_bf16 v[96:111], v[128:131], v[148:151], v[96:111]
	ds_read_b128 v[208:211], v254 offset:32
	v_mfma_f32_32x32x16_bf16 v[80:95], v[132:135], v[144:147], v[80:95]
	ds_read_b128 v[212:215], v254 offset:4640
	v_mfma_f32_32x32x16_bf16 v[64:79], v[132:135], v[148:151], v[64:79]
	ds_read_b128 v[192:195], v175 offset:32
	v_mfma_f32_32x32x16_bf16 v[48:63], v[136:139], v[144:147], v[48:63]
	v_mfma_f32_32x32x16_bf16 v[32:47], v[136:139], v[148:151], v[32:47]
	ds_read_b128 v[196:199], v175 offset:4640
	v_mfma_f32_32x32x16_bf16 v[16:31], v[140:143], v[144:147], v[16:31]
	ds_read_b128 v[200:203], v175 offset:9248
	v_mfma_f32_32x32x16_bf16 v[0:15], v[140:143], v[148:151], v[0:15]
	ds_read_b128 v[204:207], v175 offset:13856
	s_waitcnt lgkmcnt(0)
	v_mfma_f32_32x32x16_bf16 v[112:127], v[192:195], v[208:211], v[112:127]
	v_mfma_f32_32x32x16_bf16 v[96:111], v[192:195], v[212:215], v[96:111]
	ds_read_b128 v[144:147], v254 offset:64
	v_mfma_f32_32x32x16_bf16 v[80:95], v[196:199], v[208:211], v[80:95]
	ds_read_b128 v[148:151], v254 offset:4672
	v_mfma_f32_32x32x16_bf16 v[64:79], v[196:199], v[212:215], v[64:79]
	ds_read_b128 v[128:131], v175 offset:64
	v_mfma_f32_32x32x16_bf16 v[48:63], v[200:203], v[208:211], v[48:63]
	v_mfma_f32_32x32x16_bf16 v[32:47], v[200:203], v[212:215], v[32:47]
	ds_read_b128 v[132:135], v175 offset:4672
	v_mfma_f32_32x32x16_bf16 v[16:31], v[204:207], v[208:211], v[16:31]
	ds_read_b128 v[136:139], v175 offset:9280
	v_mfma_f32_32x32x16_bf16 v[0:15], v[204:207], v[212:215], v[0:15]
	ds_read_b128 v[140:143], v175 offset:13888
	s_waitcnt lgkmcnt(0)
	v_mfma_f32_32x32x16_bf16 v[112:127], v[128:131], v[144:147], v[112:127]
	v_mfma_f32_32x32x16_bf16 v[96:111], v[128:131], v[148:151], v[96:111]
	ds_read_b128 v[208:211], v254 offset:96
	v_mfma_f32_32x32x16_bf16 v[80:95], v[132:135], v[144:147], v[80:95]
	ds_read_b128 v[212:215], v254 offset:4704
	v_mfma_f32_32x32x16_bf16 v[64:79], v[132:135], v[148:151], v[64:79]
	ds_read_b128 v[192:195], v175 offset:96
	v_mfma_f32_32x32x16_bf16 v[48:63], v[136:139], v[144:147], v[48:63]
	v_mfma_f32_32x32x16_bf16 v[32:47], v[136:139], v[148:151], v[32:47]
	ds_read_b128 v[196:199], v175 offset:4704
	v_mfma_f32_32x32x16_bf16 v[16:31], v[140:143], v[144:147], v[16:31]
	ds_read_b128 v[200:203], v175 offset:9312
	v_mfma_f32_32x32x16_bf16 v[0:15], v[140:143], v[148:151], v[0:15]
	ds_read_b128 v[204:207], v175 offset:13920
	s_waitcnt lgkmcnt(0)
	s_barrier
	ds_read_b128 v[144:147], v254 offset:36864
	ds_read_b128 v[148:151], v254 offset:41472
	ds_read_b128 v[128:131], v175 offset:36864
	ds_read_b128 v[132:135], v175 offset:41472
	ds_read_b128 v[136:139], v175 offset:46080
	ds_read_b128 v[140:143], v175 offset:50688
	v_mfma_f32_32x32x16_bf16 v[112:127], v[192:195], v[208:211], v[112:127]
	v_mfma_f32_32x32x16_bf16 v[96:111], v[192:195], v[212:215], v[96:111]
	v_mfma_f32_32x32x16_bf16 v[80:95], v[196:199], v[208:211], v[80:95]
	v_mfma_f32_32x32x16_bf16 v[64:79], v[196:199], v[212:215], v[64:79]
	v_mfma_f32_32x32x16_bf16 v[48:63], v[200:203], v[208:211], v[48:63]
	v_mfma_f32_32x32x16_bf16 v[32:47], v[200:203], v[212:215], v[32:47]
	v_mfma_f32_32x32x16_bf16 v[16:31], v[204:207], v[208:211], v[16:31]
	v_mfma_f32_32x32x16_bf16 v[0:15], v[204:207], v[212:215], v[0:15]
	s_waitcnt lgkmcnt(0)
	v_mfma_f32_32x32x16_bf16 v[112:127], v[128:131], v[144:147], v[112:127]
	v_mfma_f32_32x32x16_bf16 v[96:111], v[128:131], v[148:151], v[96:111]
	ds_read_b128 v[208:211], v254 offset:36896
	v_mfma_f32_32x32x16_bf16 v[80:95], v[132:135], v[144:147], v[80:95]
	ds_read_b128 v[212:215], v254 offset:41504
	v_mfma_f32_32x32x16_bf16 v[64:79], v[132:135], v[148:151], v[64:79]
	ds_read_b128 v[192:195], v175 offset:36896
	v_mfma_f32_32x32x16_bf16 v[48:63], v[136:139], v[144:147], v[48:63]
	v_mfma_f32_32x32x16_bf16 v[32:47], v[136:139], v[148:151], v[32:47]
	ds_read_b128 v[196:199], v175 offset:41504
	v_mfma_f32_32x32x16_bf16 v[16:31], v[140:143], v[144:147], v[16:31]
	ds_read_b128 v[200:203], v175 offset:46112
	v_mfma_f32_32x32x16_bf16 v[0:15], v[140:143], v[148:151], v[0:15]
	ds_read_b128 v[204:207], v175 offset:50720
	s_waitcnt lgkmcnt(0)
	v_mfma_f32_32x32x16_bf16 v[112:127], v[192:195], v[208:211], v[112:127]
	v_mfma_f32_32x32x16_bf16 v[96:111], v[192:195], v[212:215], v[96:111]
	ds_read_b128 v[144:147], v254 offset:36928
	v_mfma_f32_32x32x16_bf16 v[80:95], v[196:199], v[208:211], v[80:95]
	ds_read_b128 v[148:151], v254 offset:41536
	v_mfma_f32_32x32x16_bf16 v[64:79], v[196:199], v[212:215], v[64:79]
	ds_read_b128 v[128:131], v175 offset:36928
	v_mfma_f32_32x32x16_bf16 v[48:63], v[200:203], v[208:211], v[48:63]
	v_mfma_f32_32x32x16_bf16 v[32:47], v[200:203], v[212:215], v[32:47]
	ds_read_b128 v[132:135], v175 offset:41536
	v_mfma_f32_32x32x16_bf16 v[16:31], v[204:207], v[208:211], v[16:31]
	ds_read_b128 v[136:139], v175 offset:46144
	v_mfma_f32_32x32x16_bf16 v[0:15], v[204:207], v[212:215], v[0:15]
	ds_read_b128 v[140:143], v175 offset:50752
	s_waitcnt lgkmcnt(0)
	v_mfma_f32_32x32x16_bf16 v[112:127], v[128:131], v[144:147], v[112:127]
	v_mfma_f32_32x32x16_bf16 v[96:111], v[128:131], v[148:151], v[96:111]
	ds_read_b128 v[208:211], v254 offset:36960
	v_mfma_f32_32x32x16_bf16 v[80:95], v[132:135], v[144:147], v[80:95]
	ds_read_b128 v[212:215], v254 offset:41568
	v_mfma_f32_32x32x16_bf16 v[64:79], v[132:135], v[148:151], v[64:79]
	ds_read_b128 v[192:195], v175 offset:36960
	v_mfma_f32_32x32x16_bf16 v[48:63], v[136:139], v[144:147], v[48:63]
	v_mfma_f32_32x32x16_bf16 v[32:47], v[136:139], v[148:151], v[32:47]
	ds_read_b128 v[196:199], v175 offset:41568
	v_mfma_f32_32x32x16_bf16 v[16:31], v[140:143], v[144:147], v[16:31]
	ds_read_b128 v[200:203], v175 offset:46176
	v_mfma_f32_32x32x16_bf16 v[0:15], v[140:143], v[148:151], v[0:15]
	ds_read_b128 v[204:207], v175 offset:50784
	s_waitcnt lgkmcnt(0)
	s_barrier
	v_mfma_f32_32x32x16_bf16 v[112:127], v[192:195], v[208:211], v[112:127]
	v_mfma_f32_32x32x16_bf16 v[96:111], v[192:195], v[212:215], v[96:111]
	v_mfma_f32_32x32x16_bf16 v[80:95], v[196:199], v[208:211], v[80:95]
	v_mfma_f32_32x32x16_bf16 v[64:79], v[196:199], v[212:215], v[64:79]
	v_mfma_f32_32x32x16_bf16 v[48:63], v[200:203], v[208:211], v[48:63]
	v_mfma_f32_32x32x16_bf16 v[32:47], v[200:203], v[212:215], v[32:47]
	v_mfma_f32_32x32x16_bf16 v[16:31], v[204:207], v[208:211], v[16:31]
	v_mfma_f32_32x32x16_bf16 v[0:15], v[204:207], v[212:215], v[0:15]
	s_nop 7
	s_nop 7
	s_mul_i32 s100, s64, 0x1000
	s_mul_hi_u32 s101, s64, 0x1000
	s_add_u32 s100, s100, 0xa224000
	s_addc_u32 s101, s101, 0
	s_add_u32 s96, s92, s100
	s_addc_u32 s97, s93, s101
	s_and_b32 s97, s97, 0xffff
	s_mov_b32 s98, 0x100000
	s_mov_b32 s99, 0x20000
	s_movk_i32 s46, 0x7fff
	v_and_b32_e32 v132, 31, v190
	v_bfe_u32 v133, v190, 5, 1
	v_bfe_u32 v134, v190, 6, 2
	v_bfe_u32 v135, v190, 8, 1
	v_lshl_add_u32 v132, v134, 6, v132
	v_add_u32_e32 v132, s82, v132
	v_lshlrev_b32_e32 v132, 1, v132
	v_lshlrev_b32_e32 v135, 7, v135
	v_lshl_add_u32 v135, v133, 2, v135
	s_mov_b32 s47, 0x1000
	v_mul_lo_u32 v135, s47, v135
	v_add_u32_e32 v128, v135, v132
	v_add_u32_e32 v129, 0x1000, v128
	v_add_u32_e32 v130, 0x2000, v128
	v_add_u32_e32 v131, 0x3000, v128
	v_bfe_u32 v136, v112, 16, 1
	v_bfe_u32 v137, v113, 16, 1
	v_bfe_u32 v138, v114, 16, 1
	v_bfe_u32 v139, v115, 16, 1
	v_add3_u32 v112, v112, v136, s46
	v_add3_u32 v113, v113, v137, s46
	v_add3_u32 v114, v114, v138, s46
	v_add3_u32 v115, v115, v139, s46
	s_mov_b32 s101, 0x0
	buffer_store_short_d16_hi v112, v128, s[96:99], s101 offen
	buffer_store_short_d16_hi v113, v129, s[96:99], s101 offen
	buffer_store_short_d16_hi v114, v130, s[96:99], s101 offen
	buffer_store_short_d16_hi v115, v131, s[96:99], s101 offen
	v_bfe_u32 v136, v116, 16, 1
	v_bfe_u32 v137, v117, 16, 1
	v_bfe_u32 v138, v118, 16, 1
	v_bfe_u32 v139, v119, 16, 1
	v_add3_u32 v116, v116, v136, s46
	v_add3_u32 v117, v117, v137, s46
	v_add3_u32 v118, v118, v138, s46
	v_add3_u32 v119, v119, v139, s46
	s_mov_b32 s101, 0x8000
	buffer_store_short_d16_hi v116, v128, s[96:99], s101 offen
	buffer_store_short_d16_hi v117, v129, s[96:99], s101 offen
	buffer_store_short_d16_hi v118, v130, s[96:99], s101 offen
	buffer_store_short_d16_hi v119, v131, s[96:99], s101 offen
	v_bfe_u32 v136, v120, 16, 1
	v_bfe_u32 v137, v121, 16, 1
	v_bfe_u32 v138, v122, 16, 1
	v_bfe_u32 v139, v123, 16, 1
	v_add3_u32 v120, v120, v136, s46
	v_add3_u32 v121, v121, v137, s46
	v_add3_u32 v122, v122, v138, s46
	v_add3_u32 v123, v123, v139, s46
	s_mov_b32 s101, 0x10000
	buffer_store_short_d16_hi v120, v128, s[96:99], s101 offen
	buffer_store_short_d16_hi v121, v129, s[96:99], s101 offen
	buffer_store_short_d16_hi v122, v130, s[96:99], s101 offen
	buffer_store_short_d16_hi v123, v131, s[96:99], s101 offen
	v_bfe_u32 v136, v124, 16, 1
	v_bfe_u32 v137, v125, 16, 1
	v_bfe_u32 v138, v126, 16, 1
	v_bfe_u32 v139, v127, 16, 1
	v_add3_u32 v124, v124, v136, s46
	v_add3_u32 v125, v125, v137, s46
	v_add3_u32 v126, v126, v138, s46
	v_add3_u32 v127, v127, v139, s46
	s_mov_b32 s101, 0x18000
	buffer_store_short_d16_hi v124, v128, s[96:99], s101 offen
	buffer_store_short_d16_hi v125, v129, s[96:99], s101 offen
	buffer_store_short_d16_hi v126, v130, s[96:99], s101 offen
	buffer_store_short_d16_hi v127, v131, s[96:99], s101 offen
	v_bfe_u32 v136, v96, 16, 1
	v_bfe_u32 v137, v97, 16, 1
	v_bfe_u32 v138, v98, 16, 1
	v_bfe_u32 v139, v99, 16, 1
	v_add3_u32 v96, v96, v136, s46
	v_add3_u32 v97, v97, v137, s46
	v_add3_u32 v98, v98, v138, s46
	v_add3_u32 v99, v99, v139, s46
	s_mov_b32 s101, 0x0
	buffer_store_short_d16_hi v96, v128, s[96:99], s101 offen offset:64
	buffer_store_short_d16_hi v97, v129, s[96:99], s101 offen offset:64
	buffer_store_short_d16_hi v98, v130, s[96:99], s101 offen offset:64
	buffer_store_short_d16_hi v99, v131, s[96:99], s101 offen offset:64
	v_bfe_u32 v136, v100, 16, 1
	v_bfe_u32 v137, v101, 16, 1
	v_bfe_u32 v138, v102, 16, 1
	v_bfe_u32 v139, v103, 16, 1
	v_add3_u32 v100, v100, v136, s46
	v_add3_u32 v101, v101, v137, s46
	v_add3_u32 v102, v102, v138, s46
	v_add3_u32 v103, v103, v139, s46
	s_mov_b32 s101, 0x8000
	buffer_store_short_d16_hi v100, v128, s[96:99], s101 offen offset:64
	buffer_store_short_d16_hi v101, v129, s[96:99], s101 offen offset:64
	buffer_store_short_d16_hi v102, v130, s[96:99], s101 offen offset:64
	buffer_store_short_d16_hi v103, v131, s[96:99], s101 offen offset:64
	v_bfe_u32 v136, v104, 16, 1
	v_bfe_u32 v137, v105, 16, 1
	v_bfe_u32 v138, v106, 16, 1
	v_bfe_u32 v139, v107, 16, 1
	v_add3_u32 v104, v104, v136, s46
	v_add3_u32 v105, v105, v137, s46
	v_add3_u32 v106, v106, v138, s46
	v_add3_u32 v107, v107, v139, s46
	s_mov_b32 s101, 0x10000
	buffer_store_short_d16_hi v104, v128, s[96:99], s101 offen offset:64
	buffer_store_short_d16_hi v105, v129, s[96:99], s101 offen offset:64
	buffer_store_short_d16_hi v106, v130, s[96:99], s101 offen offset:64
	buffer_store_short_d16_hi v107, v131, s[96:99], s101 offen offset:64
	v_bfe_u32 v136, v108, 16, 1
	v_bfe_u32 v137, v109, 16, 1
	v_bfe_u32 v138, v110, 16, 1
	v_bfe_u32 v139, v111, 16, 1
	v_add3_u32 v108, v108, v136, s46
	v_add3_u32 v109, v109, v137, s46
	v_add3_u32 v110, v110, v138, s46
	v_add3_u32 v111, v111, v139, s46
	s_mov_b32 s101, 0x18000
	buffer_store_short_d16_hi v108, v128, s[96:99], s101 offen offset:64
	buffer_store_short_d16_hi v109, v129, s[96:99], s101 offen offset:64
	buffer_store_short_d16_hi v110, v130, s[96:99], s101 offen offset:64
	buffer_store_short_d16_hi v111, v131, s[96:99], s101 offen offset:64
	v_bfe_u32 v136, v80, 16, 1
	v_bfe_u32 v137, v81, 16, 1
	v_bfe_u32 v138, v82, 16, 1
	v_bfe_u32 v139, v83, 16, 1
	v_add3_u32 v80, v80, v136, s46
	v_add3_u32 v81, v81, v137, s46
	v_add3_u32 v82, v82, v138, s46
	v_add3_u32 v83, v83, v139, s46
	s_mov_b32 s101, 0x20000
	buffer_store_short_d16_hi v80, v128, s[96:99], s101 offen
	buffer_store_short_d16_hi v81, v129, s[96:99], s101 offen
	buffer_store_short_d16_hi v82, v130, s[96:99], s101 offen
	buffer_store_short_d16_hi v83, v131, s[96:99], s101 offen
	v_bfe_u32 v136, v84, 16, 1
	v_bfe_u32 v137, v85, 16, 1
	v_bfe_u32 v138, v86, 16, 1
	v_bfe_u32 v139, v87, 16, 1
	v_add3_u32 v84, v84, v136, s46
	v_add3_u32 v85, v85, v137, s46
	v_add3_u32 v86, v86, v138, s46
	v_add3_u32 v87, v87, v139, s46
	s_mov_b32 s101, 0x28000
	buffer_store_short_d16_hi v84, v128, s[96:99], s101 offen
	buffer_store_short_d16_hi v85, v129, s[96:99], s101 offen
	buffer_store_short_d16_hi v86, v130, s[96:99], s101 offen
	buffer_store_short_d16_hi v87, v131, s[96:99], s101 offen
	v_bfe_u32 v136, v88, 16, 1
	v_bfe_u32 v137, v89, 16, 1
	v_bfe_u32 v138, v90, 16, 1
	v_bfe_u32 v139, v91, 16, 1
	v_add3_u32 v88, v88, v136, s46
	v_add3_u32 v89, v89, v137, s46
	v_add3_u32 v90, v90, v138, s46
	v_add3_u32 v91, v91, v139, s46
	s_mov_b32 s101, 0x30000
	buffer_store_short_d16_hi v88, v128, s[96:99], s101 offen
	buffer_store_short_d16_hi v89, v129, s[96:99], s101 offen
	buffer_store_short_d16_hi v90, v130, s[96:99], s101 offen
	buffer_store_short_d16_hi v91, v131, s[96:99], s101 offen
	v_bfe_u32 v136, v92, 16, 1
	v_bfe_u32 v137, v93, 16, 1
	v_bfe_u32 v138, v94, 16, 1
	v_bfe_u32 v139, v95, 16, 1
	v_add3_u32 v92, v92, v136, s46
	v_add3_u32 v93, v93, v137, s46
	v_add3_u32 v94, v94, v138, s46
	v_add3_u32 v95, v95, v139, s46
	s_mov_b32 s101, 0x38000
	buffer_store_short_d16_hi v92, v128, s[96:99], s101 offen
	buffer_store_short_d16_hi v93, v129, s[96:99], s101 offen
	buffer_store_short_d16_hi v94, v130, s[96:99], s101 offen
	buffer_store_short_d16_hi v95, v131, s[96:99], s101 offen
	v_bfe_u32 v136, v64, 16, 1
	v_bfe_u32 v137, v65, 16, 1
	v_bfe_u32 v138, v66, 16, 1
	v_bfe_u32 v139, v67, 16, 1
	v_add3_u32 v64, v64, v136, s46
	v_add3_u32 v65, v65, v137, s46
	v_add3_u32 v66, v66, v138, s46
	v_add3_u32 v67, v67, v139, s46
	s_mov_b32 s101, 0x20000
	buffer_store_short_d16_hi v64, v128, s[96:99], s101 offen offset:64
	buffer_store_short_d16_hi v65, v129, s[96:99], s101 offen offset:64
	buffer_store_short_d16_hi v66, v130, s[96:99], s101 offen offset:64
	buffer_store_short_d16_hi v67, v131, s[96:99], s101 offen offset:64
	v_bfe_u32 v136, v68, 16, 1
	v_bfe_u32 v137, v69, 16, 1
	v_bfe_u32 v138, v70, 16, 1
	v_bfe_u32 v139, v71, 16, 1
	v_add3_u32 v68, v68, v136, s46
	v_add3_u32 v69, v69, v137, s46
	v_add3_u32 v70, v70, v138, s46
	v_add3_u32 v71, v71, v139, s46
	s_mov_b32 s101, 0x28000
	buffer_store_short_d16_hi v68, v128, s[96:99], s101 offen offset:64
	buffer_store_short_d16_hi v69, v129, s[96:99], s101 offen offset:64
	buffer_store_short_d16_hi v70, v130, s[96:99], s101 offen offset:64
	buffer_store_short_d16_hi v71, v131, s[96:99], s101 offen offset:64
	v_bfe_u32 v136, v72, 16, 1
	v_bfe_u32 v137, v73, 16, 1
	v_bfe_u32 v138, v74, 16, 1
	v_bfe_u32 v139, v75, 16, 1
	v_add3_u32 v72, v72, v136, s46
	v_add3_u32 v73, v73, v137, s46
	v_add3_u32 v74, v74, v138, s46
	v_add3_u32 v75, v75, v139, s46
	s_mov_b32 s101, 0x30000
	buffer_store_short_d16_hi v72, v128, s[96:99], s101 offen offset:64
	buffer_store_short_d16_hi v73, v129, s[96:99], s101 offen offset:64
	buffer_store_short_d16_hi v74, v130, s[96:99], s101 offen offset:64
	buffer_store_short_d16_hi v75, v131, s[96:99], s101 offen offset:64
	v_bfe_u32 v136, v76, 16, 1
	v_bfe_u32 v137, v77, 16, 1
	v_bfe_u32 v138, v78, 16, 1
	v_bfe_u32 v139, v79, 16, 1
	v_add3_u32 v76, v76, v136, s46
	v_add3_u32 v77, v77, v137, s46
	v_add3_u32 v78, v78, v138, s46
	v_add3_u32 v79, v79, v139, s46
	s_mov_b32 s101, 0x38000
	buffer_store_short_d16_hi v76, v128, s[96:99], s101 offen offset:64
	buffer_store_short_d16_hi v77, v129, s[96:99], s101 offen offset:64
	buffer_store_short_d16_hi v78, v130, s[96:99], s101 offen offset:64
	buffer_store_short_d16_hi v79, v131, s[96:99], s101 offen offset:64
	v_bfe_u32 v136, v48, 16, 1
	v_bfe_u32 v137, v49, 16, 1
	v_bfe_u32 v138, v50, 16, 1
	v_bfe_u32 v139, v51, 16, 1
	v_add3_u32 v48, v48, v136, s46
	v_add3_u32 v49, v49, v137, s46
	v_add3_u32 v50, v50, v138, s46
	v_add3_u32 v51, v51, v139, s46
	s_mov_b32 s101, 0x40000
	buffer_store_short_d16_hi v48, v128, s[96:99], s101 offen
	buffer_store_short_d16_hi v49, v129, s[96:99], s101 offen
	buffer_store_short_d16_hi v50, v130, s[96:99], s101 offen
	buffer_store_short_d16_hi v51, v131, s[96:99], s101 offen
	v_bfe_u32 v136, v52, 16, 1
	v_bfe_u32 v137, v53, 16, 1
	v_bfe_u32 v138, v54, 16, 1
	v_bfe_u32 v139, v55, 16, 1
	v_add3_u32 v52, v52, v136, s46
	v_add3_u32 v53, v53, v137, s46
	v_add3_u32 v54, v54, v138, s46
	v_add3_u32 v55, v55, v139, s46
	s_mov_b32 s101, 0x48000
	buffer_store_short_d16_hi v52, v128, s[96:99], s101 offen
	buffer_store_short_d16_hi v53, v129, s[96:99], s101 offen
	buffer_store_short_d16_hi v54, v130, s[96:99], s101 offen
	buffer_store_short_d16_hi v55, v131, s[96:99], s101 offen
	v_bfe_u32 v136, v56, 16, 1
	v_bfe_u32 v137, v57, 16, 1
	v_bfe_u32 v138, v58, 16, 1
	v_bfe_u32 v139, v59, 16, 1
	v_add3_u32 v56, v56, v136, s46
	v_add3_u32 v57, v57, v137, s46
	v_add3_u32 v58, v58, v138, s46
	v_add3_u32 v59, v59, v139, s46
	s_mov_b32 s101, 0x50000
	buffer_store_short_d16_hi v56, v128, s[96:99], s101 offen
	buffer_store_short_d16_hi v57, v129, s[96:99], s101 offen
	buffer_store_short_d16_hi v58, v130, s[96:99], s101 offen
	buffer_store_short_d16_hi v59, v131, s[96:99], s101 offen
	v_bfe_u32 v136, v60, 16, 1
	v_bfe_u32 v137, v61, 16, 1
	v_bfe_u32 v138, v62, 16, 1
	v_bfe_u32 v139, v63, 16, 1
	v_add3_u32 v60, v60, v136, s46
	v_add3_u32 v61, v61, v137, s46
	v_add3_u32 v62, v62, v138, s46
	v_add3_u32 v63, v63, v139, s46
	s_mov_b32 s101, 0x58000
	buffer_store_short_d16_hi v60, v128, s[96:99], s101 offen
	buffer_store_short_d16_hi v61, v129, s[96:99], s101 offen
	buffer_store_short_d16_hi v62, v130, s[96:99], s101 offen
	buffer_store_short_d16_hi v63, v131, s[96:99], s101 offen
	v_bfe_u32 v136, v32, 16, 1
	v_bfe_u32 v137, v33, 16, 1
	v_bfe_u32 v138, v34, 16, 1
	v_bfe_u32 v139, v35, 16, 1
	v_add3_u32 v32, v32, v136, s46
	v_add3_u32 v33, v33, v137, s46
	v_add3_u32 v34, v34, v138, s46
	v_add3_u32 v35, v35, v139, s46
	s_mov_b32 s101, 0x40000
	buffer_store_short_d16_hi v32, v128, s[96:99], s101 offen offset:64
	buffer_store_short_d16_hi v33, v129, s[96:99], s101 offen offset:64
	buffer_store_short_d16_hi v34, v130, s[96:99], s101 offen offset:64
	buffer_store_short_d16_hi v35, v131, s[96:99], s101 offen offset:64
	v_bfe_u32 v136, v36, 16, 1
	v_bfe_u32 v137, v37, 16, 1
	v_bfe_u32 v138, v38, 16, 1
	v_bfe_u32 v139, v39, 16, 1
	v_add3_u32 v36, v36, v136, s46
	v_add3_u32 v37, v37, v137, s46
	v_add3_u32 v38, v38, v138, s46
	v_add3_u32 v39, v39, v139, s46
	s_mov_b32 s101, 0x48000
	buffer_store_short_d16_hi v36, v128, s[96:99], s101 offen offset:64
	buffer_store_short_d16_hi v37, v129, s[96:99], s101 offen offset:64
	buffer_store_short_d16_hi v38, v130, s[96:99], s101 offen offset:64
	buffer_store_short_d16_hi v39, v131, s[96:99], s101 offen offset:64
	v_bfe_u32 v136, v40, 16, 1
	v_bfe_u32 v137, v41, 16, 1
	v_bfe_u32 v138, v42, 16, 1
	v_bfe_u32 v139, v43, 16, 1
	v_add3_u32 v40, v40, v136, s46
	v_add3_u32 v41, v41, v137, s46
	v_add3_u32 v42, v42, v138, s46
	v_add3_u32 v43, v43, v139, s46
	s_mov_b32 s101, 0x50000
	buffer_store_short_d16_hi v40, v128, s[96:99], s101 offen offset:64
	buffer_store_short_d16_hi v41, v129, s[96:99], s101 offen offset:64
	buffer_store_short_d16_hi v42, v130, s[96:99], s101 offen offset:64
	buffer_store_short_d16_hi v43, v131, s[96:99], s101 offen offset:64
	v_bfe_u32 v136, v44, 16, 1
	v_bfe_u32 v137, v45, 16, 1
	v_bfe_u32 v138, v46, 16, 1
	v_bfe_u32 v139, v47, 16, 1
	v_add3_u32 v44, v44, v136, s46
	v_add3_u32 v45, v45, v137, s46
	v_add3_u32 v46, v46, v138, s46
	v_add3_u32 v47, v47, v139, s46
	s_mov_b32 s101, 0x58000
	buffer_store_short_d16_hi v44, v128, s[96:99], s101 offen offset:64
	buffer_store_short_d16_hi v45, v129, s[96:99], s101 offen offset:64
	buffer_store_short_d16_hi v46, v130, s[96:99], s101 offen offset:64
	buffer_store_short_d16_hi v47, v131, s[96:99], s101 offen offset:64
	v_bfe_u32 v136, v16, 16, 1
	v_bfe_u32 v137, v17, 16, 1
	v_bfe_u32 v138, v18, 16, 1
	v_bfe_u32 v139, v19, 16, 1
	v_add3_u32 v16, v16, v136, s46
	v_add3_u32 v17, v17, v137, s46
	v_add3_u32 v18, v18, v138, s46
	v_add3_u32 v19, v19, v139, s46
	s_mov_b32 s101, 0x60000
	buffer_store_short_d16_hi v16, v128, s[96:99], s101 offen
	buffer_store_short_d16_hi v17, v129, s[96:99], s101 offen
	buffer_store_short_d16_hi v18, v130, s[96:99], s101 offen
	buffer_store_short_d16_hi v19, v131, s[96:99], s101 offen
	v_bfe_u32 v136, v20, 16, 1
	v_bfe_u32 v137, v21, 16, 1
	v_bfe_u32 v138, v22, 16, 1
	v_bfe_u32 v139, v23, 16, 1
	v_add3_u32 v20, v20, v136, s46
	v_add3_u32 v21, v21, v137, s46
	v_add3_u32 v22, v22, v138, s46
	v_add3_u32 v23, v23, v139, s46
	s_mov_b32 s101, 0x68000
	buffer_store_short_d16_hi v20, v128, s[96:99], s101 offen
	buffer_store_short_d16_hi v21, v129, s[96:99], s101 offen
	buffer_store_short_d16_hi v22, v130, s[96:99], s101 offen
	buffer_store_short_d16_hi v23, v131, s[96:99], s101 offen
	v_bfe_u32 v136, v24, 16, 1
	v_bfe_u32 v137, v25, 16, 1
	v_bfe_u32 v138, v26, 16, 1
	v_bfe_u32 v139, v27, 16, 1
	v_add3_u32 v24, v24, v136, s46
	v_add3_u32 v25, v25, v137, s46
	v_add3_u32 v26, v26, v138, s46
	v_add3_u32 v27, v27, v139, s46
	s_mov_b32 s101, 0x70000
	buffer_store_short_d16_hi v24, v128, s[96:99], s101 offen
	buffer_store_short_d16_hi v25, v129, s[96:99], s101 offen
	buffer_store_short_d16_hi v26, v130, s[96:99], s101 offen
	buffer_store_short_d16_hi v27, v131, s[96:99], s101 offen
	v_bfe_u32 v136, v28, 16, 1
	v_bfe_u32 v137, v29, 16, 1
	v_bfe_u32 v138, v30, 16, 1
	v_bfe_u32 v139, v31, 16, 1
	v_add3_u32 v28, v28, v136, s46
	v_add3_u32 v29, v29, v137, s46
	v_add3_u32 v30, v30, v138, s46
	v_add3_u32 v31, v31, v139, s46
	s_mov_b32 s101, 0x78000
	buffer_store_short_d16_hi v28, v128, s[96:99], s101 offen
	buffer_store_short_d16_hi v29, v129, s[96:99], s101 offen
	buffer_store_short_d16_hi v30, v130, s[96:99], s101 offen
	buffer_store_short_d16_hi v31, v131, s[96:99], s101 offen
	v_bfe_u32 v136, v0, 16, 1
	v_bfe_u32 v137, v1, 16, 1
	v_bfe_u32 v138, v2, 16, 1
	v_bfe_u32 v139, v3, 16, 1
	v_add3_u32 v0, v0, v136, s46
	v_add3_u32 v1, v1, v137, s46
	v_add3_u32 v2, v2, v138, s46
	v_add3_u32 v3, v3, v139, s46
	s_mov_b32 s101, 0x60000
	buffer_store_short_d16_hi v0, v128, s[96:99], s101 offen offset:64
	buffer_store_short_d16_hi v1, v129, s[96:99], s101 offen offset:64
	buffer_store_short_d16_hi v2, v130, s[96:99], s101 offen offset:64
	buffer_store_short_d16_hi v3, v131, s[96:99], s101 offen offset:64
	v_bfe_u32 v136, v4, 16, 1
	v_bfe_u32 v137, v5, 16, 1
	v_bfe_u32 v138, v6, 16, 1
	v_bfe_u32 v139, v7, 16, 1
	v_add3_u32 v4, v4, v136, s46
	v_add3_u32 v5, v5, v137, s46
	v_add3_u32 v6, v6, v138, s46
	v_add3_u32 v7, v7, v139, s46
	s_mov_b32 s101, 0x68000
	buffer_store_short_d16_hi v4, v128, s[96:99], s101 offen offset:64
	buffer_store_short_d16_hi v5, v129, s[96:99], s101 offen offset:64
	buffer_store_short_d16_hi v6, v130, s[96:99], s101 offen offset:64
	buffer_store_short_d16_hi v7, v131, s[96:99], s101 offen offset:64
	v_bfe_u32 v136, v8, 16, 1
	v_bfe_u32 v137, v9, 16, 1
	v_bfe_u32 v138, v10, 16, 1
	v_bfe_u32 v139, v11, 16, 1
	v_add3_u32 v8, v8, v136, s46
	v_add3_u32 v9, v9, v137, s46
	v_add3_u32 v10, v10, v138, s46
	v_add3_u32 v11, v11, v139, s46
	s_mov_b32 s101, 0x70000
	buffer_store_short_d16_hi v8, v128, s[96:99], s101 offen offset:64
	buffer_store_short_d16_hi v9, v129, s[96:99], s101 offen offset:64
	buffer_store_short_d16_hi v10, v130, s[96:99], s101 offen offset:64
	buffer_store_short_d16_hi v11, v131, s[96:99], s101 offen offset:64
	v_bfe_u32 v136, v12, 16, 1
	v_bfe_u32 v137, v13, 16, 1
	v_bfe_u32 v138, v14, 16, 1
	v_bfe_u32 v139, v15, 16, 1
	v_add3_u32 v12, v12, v136, s46
	v_add3_u32 v13, v13, v137, s46
	v_add3_u32 v14, v14, v138, s46
	v_add3_u32 v15, v15, v139, s46
	s_mov_b32 s101, 0x78000
	buffer_store_short_d16_hi v12, v128, s[96:99], s101 offen offset:64
	buffer_store_short_d16_hi v13, v129, s[96:99], s101 offen offset:64
	buffer_store_short_d16_hi v14, v130, s[96:99], s101 offen offset:64
	buffer_store_short_d16_hi v15, v131, s[96:99], s101 offen offset:64
	s_add_i32 s39, s39, s94
	s_cmpk_lt_i32 s39, 0x200
	s_cbranch_scc1 .Lgwq0_tile
	s_branch .LBB0_1433

.LBB0_2004:
.Lgout1_tile:
	s_bfe_u32 s20, s79, 0x30005
	s_and_b32 s21, s79, 31
	s_lshr_b32 s7, s79, 8
	s_lshl_b32 s6, s7, 5
	s_lshr_b32 s7, s20, 1
	s_lshl_b32 s7, s7, 3
	s_add_u32 s6, s6, s7
	s_lshr_b32 s7, s21, 2
	s_add_u32 s6, s6, s7
	s_and_b32 s7, s20, 1
	s_lshl_b32 s7, s7, 2
	s_and_b32 s21, s21, 3
	s_add_u32 s7, s7, s21
	s_lshl_b32 s6, s6, 8
	s_lshl_b32 s7, s7, 8
	s_lshl_b32 s20, s6, 12
	s_add_u32 s20, s20, 0x6224000
	s_add_u32 s8, s92, s20
	s_addc_u32 s9, s93, 0
	s_and_b32 s9, s9, 0xffff
	s_mov_b32 s10, 0x100000
	s_mov_b32 s11, 0x20000
	s_lshl_b32 s20, s7, 12
	s_add_u32 s20, s20, 0x3380000
	s_add_u32 s24, s92, s20
	s_addc_u32 s25, s93, 0
	s_and_b32 s25, s25, 0xffff
	s_sub_u32 s20, 0x800, s7
	s_min_u32 s20, s20, 0x100
	s_lshl_b32 s26, s20, 12
	s_mov_b32 s27, 0x20000
	s_mov_b32 s28, 0x40000
	s_mov_b32 s29, 0x80000
	s_mov_b32 s30, 0xc0000
	v_lshrrev_b32_e32 v128, 3, v190
	v_and_b32_e32 v129, 7, v190
	v_lshlrev_b32_e32 v129, 4, v129
	v_lshl_add_u32 v160, v128, 12, v129
	v_mul_u32_u24_e32 v130, 0x90, v128
	v_add_u32_e32 v170, v130, v129
	v_add_u32_e32 v171, 0x12000, v170
	v_and_b32_e32 v131, 31, v190
	v_bfe_u32 v132, v190, 5, 1
	v_bfe_u32 v133, v190, 6, 2
	v_bfe_u32 v134, v190, 8, 1
	v_lshl_add_u32 v135, v134, 7, v131
	v_mul_u32_u24_e32 v135, 0x90, v135
	v_lshl_add_u32 v175, v132, 4, v135
	v_lshl_add_u32 v136, v133, 6, v131
	v_mul_u32_u24_e32 v136, 0x90, v136
	v_lshl_add_u32 v136, v132, 4, v136
	v_add_u32_e32 v254, 0x12000, v136
	v_mov_b32_e32 v0, 0
	v_mov_b32_e32 v1, 0
	v_mov_b32_e32 v2, 0
	v_mov_b32_e32 v3, 0
	v_mov_b32_e32 v4, 0
	v_mov_b32_e32 v5, 0
	v_mov_b32_e32 v6, 0
	v_mov_b32_e32 v7, 0
	v_mov_b32_e32 v8, 0
	v_mov_b32_e32 v9, 0
	v_mov_b32_e32 v10, 0
	v_mov_b32_e32 v11, 0
	v_mov_b32_e32 v12, 0
	v_mov_b32_e32 v13, 0
	v_mov_b32_e32 v14, 0
	v_mov_b32_e32 v15, 0
	v_mov_b32_e32 v16, 0
	v_mov_b32_e32 v17, 0
	v_mov_b32_e32 v18, 0
	v_mov_b32_e32 v19, 0
	v_mov_b32_e32 v20, 0
	v_mov_b32_e32 v21, 0
	v_mov_b32_e32 v22, 0
	v_mov_b32_e32 v23, 0
	v_mov_b32_e32 v24, 0
	v_mov_b32_e32 v25, 0
	v_mov_b32_e32 v26, 0
	v_mov_b32_e32 v27, 0
	v_mov_b32_e32 v28, 0
	v_mov_b32_e32 v29, 0
	v_mov_b32_e32 v30, 0
	v_mov_b32_e32 v31, 0
	v_mov_b32_e32 v32, 0
	v_mov_b32_e32 v33, 0
	v_mov_b32_e32 v34, 0
	v_mov_b32_e32 v35, 0
	v_mov_b32_e32 v36, 0
	v_mov_b32_e32 v37, 0
	v_mov_b32_e32 v38, 0
	v_mov_b32_e32 v39, 0
	v_mov_b32_e32 v40, 0
	v_mov_b32_e32 v41, 0
	v_mov_b32_e32 v42, 0
	v_mov_b32_e32 v43, 0
	v_mov_b32_e32 v44, 0
	v_mov_b32_e32 v45, 0
	v_mov_b32_e32 v46, 0
	v_mov_b32_e32 v47, 0
	v_mov_b32_e32 v48, 0
	v_mov_b32_e32 v49, 0
	v_mov_b32_e32 v50, 0
	v_mov_b32_e32 v51, 0
	v_mov_b32_e32 v52, 0
	v_mov_b32_e32 v53, 0
	v_mov_b32_e32 v54, 0
	v_mov_b32_e32 v55, 0
	v_mov_b32_e32 v56, 0
	v_mov_b32_e32 v57, 0
	v_mov_b32_e32 v58, 0
	v_mov_b32_e32 v59, 0
	v_mov_b32_e32 v60, 0
	v_mov_b32_e32 v61, 0
	v_mov_b32_e32 v62, 0
	v_mov_b32_e32 v63, 0
	v_mov_b32_e32 v64, 0
	v_mov_b32_e32 v65, 0
	v_mov_b32_e32 v66, 0
	v_mov_b32_e32 v67, 0
	v_mov_b32_e32 v68, 0
	v_mov_b32_e32 v69, 0
	v_mov_b32_e32 v70, 0
	v_mov_b32_e32 v71, 0
	v_mov_b32_e32 v72, 0
	v_mov_b32_e32 v73, 0
	v_mov_b32_e32 v74, 0
	v_mov_b32_e32 v75, 0
	v_mov_b32_e32 v76, 0
	v_mov_b32_e32 v77, 0
	v_mov_b32_e32 v78, 0
	v_mov_b32_e32 v79, 0
	v_mov_b32_e32 v80, 0
	v_mov_b32_e32 v81, 0
	v_mov_b32_e32 v82, 0
	v_mov_b32_e32 v83, 0
	v_mov_b32_e32 v84, 0
	v_mov_b32_e32 v85, 0
	v_mov_b32_e32 v86, 0
	v_mov_b32_e32 v87, 0
	v_mov_b32_e32 v88, 0
	v_mov_b32_e32 v89, 0
	v_mov_b32_e32 v90, 0
	v_mov_b32_e32 v91, 0
	v_mov_b32_e32 v92, 0
	v_mov_b32_e32 v93, 0
	v_mov_b32_e32 v94, 0
	v_mov_b32_e32 v95, 0
	v_mov_b32_e32 v96, 0
	v_mov_b32_e32 v97, 0
	v_mov_b32_e32 v98, 0
	v_mov_b32_e32 v99, 0
	v_mov_b32_e32 v100, 0
	v_mov_b32_e32 v101, 0
	v_mov_b32_e32 v102, 0
	v_mov_b32_e32 v103, 0
	v_mov_b32_e32 v104, 0
	v_mov_b32_e32 v105, 0
	v_mov_b32_e32 v106, 0
	v_mov_b32_e32 v107, 0
	v_mov_b32_e32 v108, 0
	v_mov_b32_e32 v109, 0
	v_mov_b32_e32 v110, 0
	v_mov_b32_e32 v111, 0
	v_mov_b32_e32 v112, 0
	v_mov_b32_e32 v113, 0
	v_mov_b32_e32 v114, 0
	v_mov_b32_e32 v115, 0
	v_mov_b32_e32 v116, 0
	v_mov_b32_e32 v117, 0
	v_mov_b32_e32 v118, 0
	v_mov_b32_e32 v119, 0
	v_mov_b32_e32 v120, 0
	v_mov_b32_e32 v121, 0
	v_mov_b32_e32 v122, 0
	v_mov_b32_e32 v123, 0
	v_mov_b32_e32 v124, 0
	v_mov_b32_e32 v125, 0
	v_mov_b32_e32 v126, 0
	v_mov_b32_e32 v127, 0
	v_mov_b32_e32 v192, 0
	v_mov_b32_e32 v193, 0
	v_mov_b32_e32 v194, 0
	v_mov_b32_e32 v195, 0
	v_mov_b32_e32 v196, 0
	v_mov_b32_e32 v197, 0
	v_mov_b32_e32 v198, 0
	v_mov_b32_e32 v199, 0
	v_mov_b32_e32 v200, 0
	v_mov_b32_e32 v201, 0
	v_mov_b32_e32 v202, 0
	v_mov_b32_e32 v203, 0
	v_mov_b32_e32 v204, 0
	v_mov_b32_e32 v205, 0
	v_mov_b32_e32 v206, 0
	v_mov_b32_e32 v207, 0
	v_mov_b32_e32 v208, 0
	v_mov_b32_e32 v209, 0
	v_mov_b32_e32 v210, 0
	v_mov_b32_e32 v211, 0
	v_mov_b32_e32 v212, 0
	v_mov_b32_e32 v213, 0
	v_mov_b32_e32 v214, 0
	v_mov_b32_e32 v215, 0
	v_mov_b32_e32 v188, 0
	v_mov_b32_e32 v189, 0
	buffer_load_dwordx4 v[216:219], v160, s[8:11], 0 offen
	buffer_load_dwordx4 v[220:223], v160, s[8:11], s28 offen
	buffer_load_dwordx4 v[224:227], v160, s[8:11], s29 offen
	buffer_load_dwordx4 v[228:231], v160, s[8:11], s30 offen
	buffer_load_dwordx4 v[232:235], v160, s[24:27], 0 offen
	buffer_load_dwordx4 v[236:239], v160, s[24:27], s28 offen
	buffer_load_dwordx4 v[152:155], v160, s[24:27], s29 offen
	buffer_load_dwordx4 v[156:159], v160, s[24:27], s30 offen
	v_add_u32_e32 v160, 0x80, v160
	buffer_load_dwordx4 v[162:165], v160, s[8:11], 0 offen
	buffer_load_dwordx4 v[166:169], v160, s[8:11], s28 offen
	buffer_load_dwordx4 v[176:179], v160, s[8:11], s29 offen
	buffer_load_dwordx4 v[180:183], v160, s[8:11], s30 offen
	buffer_load_dwordx4 v[184:187], v160, s[24:27], 0 offen
	buffer_load_dwordx4 v[242:245], v160, s[24:27], s28 offen
	buffer_load_dwordx4 v[246:249], v160, s[24:27], s29 offen
	buffer_load_dwordx4 v[250:253], v160, s[24:27], s30 offen
	v_add_u32_e32 v160, 0x80, v160
	s_waitcnt vmcnt(8)
	ds_write_b128 v170, v[216:219] offset:0
	ds_write_b128 v170, v[220:223] offset:9216
	ds_write_b128 v170, v[224:227] offset:18432
	ds_write_b128 v170, v[228:231] offset:27648
	ds_write_b128 v171, v[232:235] offset:0
	ds_write_b128 v171, v[236:239] offset:9216
	ds_write_b128 v171, v[152:155] offset:18432
	ds_write_b128 v171, v[156:159] offset:27648
	buffer_load_dwordx4 v[216:219], v160, s[8:11], 0 offen
	buffer_load_dwordx4 v[220:223], v160, s[8:11], s28 offen
	buffer_load_dwordx4 v[224:227], v160, s[8:11], s29 offen
	buffer_load_dwordx4 v[228:231], v160, s[8:11], s30 offen
	buffer_load_dwordx4 v[232:235], v160, s[24:27], 0 offen
	buffer_load_dwordx4 v[236:239], v160, s[24:27], s28 offen
	buffer_load_dwordx4 v[152:155], v160, s[24:27], s29 offen
	buffer_load_dwordx4 v[156:159], v160, s[24:27], s30 offen
	v_add_u32_e32 v160, 0x80, v160
	s_waitcnt lgkmcnt(0)
	s_barrier
	s_movk_i32 s31, 14
.Lgout1_loop:
	ds_read_b128 v[144:147], v254 offset:0
	ds_read_b128 v[148:151], v254 offset:4608
	ds_read_b128 v[128:131], v175 offset:0
	ds_read_b128 v[132:135], v175 offset:4608
	ds_read_b128 v[136:139], v175 offset:9216
	ds_read_b128 v[140:143], v175 offset:13824
	v_mfma_f32_32x32x16_bf16 v[112:127], v[192:195], v[208:211], v[112:127]
	s_waitcnt vmcnt(8)
	v_mfma_f32_32x32x16_bf16 v[96:111], v[192:195], v[212:215], v[96:111]
	ds_write_b128 v170, v[162:165] offset:36864
	v_mfma_f32_32x32x16_bf16 v[80:95], v[196:199], v[208:211], v[80:95]
	ds_write_b128 v170, v[166:169] offset:46080
	v_mfma_f32_32x32x16_bf16 v[64:79], v[196:199], v[212:215], v[64:79]
	ds_write_b128 v170, v[176:179] offset:55296
	v_mfma_f32_32x32x16_bf16 v[48:63], v[200:203], v[208:211], v[48:63]
	ds_write_b128 v170, v[180:183] offset:64512
	v_mfma_f32_32x32x16_bf16 v[32:47], v[200:203], v[212:215], v[32:47]
	ds_write_b128 v171, v[184:187] offset:36864
	v_mfma_f32_32x32x16_bf16 v[16:31], v[204:207], v[208:211], v[16:31]
	ds_write_b128 v171, v[242:245] offset:46080
	v_mfma_f32_32x32x16_bf16 v[0:15], v[204:207], v[212:215], v[0:15]
	ds_write_b128 v171, v[246:249] offset:55296
	ds_write_b128 v171, v[250:253] offset:64512
	s_waitcnt lgkmcnt(8)
	v_mfma_f32_32x32x16_bf16 v[112:127], v[128:131], v[144:147], v[112:127]
	ds_read_b128 v[208:211], v254 offset:32
	v_mfma_f32_32x32x16_bf16 v[96:111], v[128:131], v[148:151], v[96:111]
	ds_read_b128 v[212:215], v254 offset:4640
	ds_read_b128 v[192:195], v175 offset:32
	v_mfma_f32_32x32x16_bf16 v[80:95], v[132:135], v[144:147], v[80:95]
	ds_read_b128 v[196:199], v175 offset:4640
	ds_read_b128 v[200:203], v175 offset:9248
	v_mfma_f32_32x32x16_bf16 v[64:79], v[132:135], v[148:151], v[64:79]
	ds_read_b128 v[204:207], v175 offset:13856
	buffer_load_dwordx4 v[162:165], v160, s[8:11], 0 offen
	v_mfma_f32_32x32x16_bf16 v[48:63], v[136:139], v[144:147], v[48:63]
	buffer_load_dwordx4 v[166:169], v160, s[8:11], s28 offen
	buffer_load_dwordx4 v[176:179], v160, s[8:11], s29 offen
	v_mfma_f32_32x32x16_bf16 v[32:47], v[136:139], v[148:151], v[32:47]
	buffer_load_dwordx4 v[180:183], v160, s[8:11], s30 offen
	buffer_load_dwordx4 v[184:187], v160, s[24:27], 0 offen
	v_mfma_f32_32x32x16_bf16 v[16:31], v[140:143], v[144:147], v[16:31]
	buffer_load_dwordx4 v[242:245], v160, s[24:27], s28 offen
	buffer_load_dwordx4 v[246:249], v160, s[24:27], s29 offen
	v_mfma_f32_32x32x16_bf16 v[0:15], v[140:143], v[148:151], v[0:15]
	buffer_load_dwordx4 v[250:253], v160, s[24:27], s30 offen
	v_add_u32_e32 v160, 0x80, v160
	s_waitcnt lgkmcnt(0)
	v_mfma_f32_32x32x16_bf16 v[112:127], v[192:195], v[208:211], v[112:127]
	v_mfma_f32_32x32x16_bf16 v[96:111], v[192:195], v[212:215], v[96:111]
	ds_read_b128 v[144:147], v254 offset:64
	v_mfma_f32_32x32x16_bf16 v[80:95], v[196:199], v[208:211], v[80:95]
	ds_read_b128 v[148:151], v254 offset:4672
	v_mfma_f32_32x32x16_bf16 v[64:79], v[196:199], v[212:215], v[64:79]
	ds_read_b128 v[128:131], v175 offset:64
	v_mfma_f32_32x32x16_bf16 v[48:63], v[200:203], v[208:211], v[48:63]
	v_mfma_f32_32x32x16_bf16 v[32:47], v[200:203], v[212:215], v[32:47]
	ds_read_b128 v[132:135], v175 offset:4672
	v_mfma_f32_32x32x16_bf16 v[16:31], v[204:207], v[208:211], v[16:31]
	ds_read_b128 v[136:139], v175 offset:9280
	v_mfma_f32_32x32x16_bf16 v[0:15], v[204:207], v[212:215], v[0:15]
	ds_read_b128 v[140:143], v175 offset:13888
	s_waitcnt lgkmcnt(0)
	v_mfma_f32_32x32x16_bf16 v[112:127], v[128:131], v[144:147], v[112:127]
	v_mfma_f32_32x32x16_bf16 v[96:111], v[128:131], v[148:151], v[96:111]
	ds_read_b128 v[208:211], v254 offset:96
	v_mfma_f32_32x32x16_bf16 v[80:95], v[132:135], v[144:147], v[80:95]
	ds_read_b128 v[212:215], v254 offset:4704
	v_mfma_f32_32x32x16_bf16 v[64:79], v[132:135], v[148:151], v[64:79]
	ds_read_b128 v[192:195], v175 offset:96
	v_mfma_f32_32x32x16_bf16 v[48:63], v[136:139], v[144:147], v[48:63]
	v_mfma_f32_32x32x16_bf16 v[32:47], v[136:139], v[148:151], v[32:47]
	ds_read_b128 v[196:199], v175 offset:4704
	v_mfma_f32_32x32x16_bf16 v[16:31], v[140:143], v[144:147], v[16:31]
	ds_read_b128 v[200:203], v175 offset:9312
	v_mfma_f32_32x32x16_bf16 v[0:15], v[140:143], v[148:151], v[0:15]
	ds_read_b128 v[204:207], v175 offset:13920
	s_waitcnt lgkmcnt(0)
	s_barrier
	ds_read_b128 v[144:147], v254 offset:36864
	ds_read_b128 v[148:151], v254 offset:41472
	ds_read_b128 v[128:131], v175 offset:36864
	ds_read_b128 v[132:135], v175 offset:41472
	ds_read_b128 v[136:139], v175 offset:46080
	ds_read_b128 v[140:143], v175 offset:50688
	v_mfma_f32_32x32x16_bf16 v[112:127], v[192:195], v[208:211], v[112:127]
	s_waitcnt vmcnt(8)
	v_mfma_f32_32x32x16_bf16 v[96:111], v[192:195], v[212:215], v[96:111]
	ds_write_b128 v170, v[216:219] offset:0
	v_mfma_f32_32x32x16_bf16 v[80:95], v[196:199], v[208:211], v[80:95]
	ds_write_b128 v170, v[220:223] offset:9216
	v_mfma_f32_32x32x16_bf16 v[64:79], v[196:199], v[212:215], v[64:79]
	ds_write_b128 v170, v[224:227] offset:18432
	v_mfma_f32_32x32x16_bf16 v[48:63], v[200:203], v[208:211], v[48:63]
	ds_write_b128 v170, v[228:231] offset:27648
	v_mfma_f32_32x32x16_bf16 v[32:47], v[200:203], v[212:215], v[32:47]
	ds_write_b128 v171, v[232:235] offset:0
	v_mfma_f32_32x32x16_bf16 v[16:31], v[204:207], v[208:211], v[16:31]
	ds_write_b128 v171, v[236:239] offset:9216
	v_mfma_f32_32x32x16_bf16 v[0:15], v[204:207], v[212:215], v[0:15]
	ds_write_b128 v171, v[152:155] offset:18432
	ds_write_b128 v171, v[156:159] offset:27648
	s_waitcnt lgkmcnt(8)
	v_mfma_f32_32x32x16_bf16 v[112:127], v[128:131], v[144:147], v[112:127]
	ds_read_b128 v[208:211], v254 offset:36896
	v_mfma_f32_32x32x16_bf16 v[96:111], v[128:131], v[148:151], v[96:111]
	ds_read_b128 v[212:215], v254 offset:41504
	ds_read_b128 v[192:195], v175 offset:36896
	v_mfma_f32_32x32x16_bf16 v[80:95], v[132:135], v[144:147], v[80:95]
	ds_read_b128 v[196:199], v175 offset:41504
	ds_read_b128 v[200:203], v175 offset:46112
	v_mfma_f32_32x32x16_bf16 v[64:79], v[132:135], v[148:151], v[64:79]
	ds_read_b128 v[204:207], v175 offset:50720
	buffer_load_dwordx4 v[216:219], v160, s[8:11], 0 offen
	v_mfma_f32_32x32x16_bf16 v[48:63], v[136:139], v[144:147], v[48:63]
	buffer_load_dwordx4 v[220:223], v160, s[8:11], s28 offen
	buffer_load_dwordx4 v[224:227], v160, s[8:11], s29 offen
	v_mfma_f32_32x32x16_bf16 v[32:47], v[136:139], v[148:151], v[32:47]
	buffer_load_dwordx4 v[228:231], v160, s[8:11], s30 offen
	buffer_load_dwordx4 v[232:235], v160, s[24:27], 0 offen
	v_mfma_f32_32x32x16_bf16 v[16:31], v[140:143], v[144:147], v[16:31]
	buffer_load_dwordx4 v[236:239], v160, s[24:27], s28 offen
	buffer_load_dwordx4 v[152:155], v160, s[24:27], s29 offen
	v_mfma_f32_32x32x16_bf16 v[0:15], v[140:143], v[148:151], v[0:15]
	buffer_load_dwordx4 v[156:159], v160, s[24:27], s30 offen
	v_add_u32_e32 v160, 0x80, v160
	s_waitcnt lgkmcnt(0)
	v_mfma_f32_32x32x16_bf16 v[112:127], v[192:195], v[208:211], v[112:127]
	v_mfma_f32_32x32x16_bf16 v[96:111], v[192:195], v[212:215], v[96:111]
	ds_read_b128 v[144:147], v254 offset:36928
	v_mfma_f32_32x32x16_bf16 v[80:95], v[196:199], v[208:211], v[80:95]
	ds_read_b128 v[148:151], v254 offset:41536
	v_mfma_f32_32x32x16_bf16 v[64:79], v[196:199], v[212:215], v[64:79]
	ds_read_b128 v[128:131], v175 offset:36928
	v_mfma_f32_32x32x16_bf16 v[48:63], v[200:203], v[208:211], v[48:63]
	v_mfma_f32_32x32x16_bf16 v[32:47], v[200:203], v[212:215], v[32:47]
	ds_read_b128 v[132:135], v175 offset:41536
	v_mfma_f32_32x32x16_bf16 v[16:31], v[204:207], v[208:211], v[16:31]
	ds_read_b128 v[136:139], v175 offset:46144
	v_mfma_f32_32x32x16_bf16 v[0:15], v[204:207], v[212:215], v[0:15]
	ds_read_b128 v[140:143], v175 offset:50752
	s_waitcnt lgkmcnt(0)
	v_mfma_f32_32x32x16_bf16 v[112:127], v[128:131], v[144:147], v[112:127]
	v_mfma_f32_32x32x16_bf16 v[96:111], v[128:131], v[148:151], v[96:111]
	ds_read_b128 v[208:211], v254 offset:36960
	v_mfma_f32_32x32x16_bf16 v[80:95], v[132:135], v[144:147], v[80:95]
	ds_read_b128 v[212:215], v254 offset:41568
	v_mfma_f32_32x32x16_bf16 v[64:79], v[132:135], v[148:151], v[64:79]
	ds_read_b128 v[192:195], v175 offset:36960
	v_mfma_f32_32x32x16_bf16 v[48:63], v[136:139], v[144:147], v[48:63]
	v_mfma_f32_32x32x16_bf16 v[32:47], v[136:139], v[148:151], v[32:47]
	ds_read_b128 v[196:199], v175 offset:41568
	v_mfma_f32_32x32x16_bf16 v[16:31], v[140:143], v[144:147], v[16:31]
	ds_read_b128 v[200:203], v175 offset:46176
	v_mfma_f32_32x32x16_bf16 v[0:15], v[140:143], v[148:151], v[0:15]
	ds_read_b128 v[204:207], v175 offset:50784
	s_waitcnt lgkmcnt(0)
	s_barrier
	s_add_i32 s31, s31, -1
	s_cmp_lg_u32 s31, 0
	s_cbranch_scc1 .Lgout1_loop
	ds_read_b128 v[144:147], v254 offset:0
	ds_read_b128 v[148:151], v254 offset:4608
	ds_read_b128 v[128:131], v175 offset:0
	ds_read_b128 v[132:135], v175 offset:4608
	ds_read_b128 v[136:139], v175 offset:9216
	ds_read_b128 v[140:143], v175 offset:13824
	v_mfma_f32_32x32x16_bf16 v[112:127], v[192:195], v[208:211], v[112:127]
	s_waitcnt vmcnt(8)
	v_mfma_f32_32x32x16_bf16 v[96:111], v[192:195], v[212:215], v[96:111]
	ds_write_b128 v170, v[162:165] offset:36864
	v_mfma_f32_32x32x16_bf16 v[80:95], v[196:199], v[208:211], v[80:95]
	ds_write_b128 v170, v[166:169] offset:46080
	v_mfma_f32_32x32x16_bf16 v[64:79], v[196:199], v[212:215], v[64:79]
	ds_write_b128 v170, v[176:179] offset:55296
	v_mfma_f32_32x32x16_bf16 v[48:63], v[200:203], v[208:211], v[48:63]
	ds_write_b128 v170, v[180:183] offset:64512
	v_mfma_f32_32x32x16_bf16 v[32:47], v[200:203], v[212:215], v[32:47]
	ds_write_b128 v171, v[184:187] offset:36864
	v_mfma_f32_32x32x16_bf16 v[16:31], v[204:207], v[208:211], v[16:31]
	ds_write_b128 v171, v[242:245] offset:46080
	v_mfma_f32_32x32x16_bf16 v[0:15], v[204:207], v[212:215], v[0:15]
	ds_write_b128 v171, v[246:249] offset:55296
	ds_write_b128 v171, v[250:253] offset:64512
	s_waitcnt lgkmcnt(8)
	v_mfma_f32_32x32x16_bf16 v[112:127], v[128:131], v[144:147], v[112:127]
	ds_read_b128 v[208:211], v254 offset:32
	v_mfma_f32_32x32x16_bf16 v[96:111], v[128:131], v[148:151], v[96:111]
	ds_read_b128 v[212:215], v254 offset:4640
	ds_read_b128 v[192:195], v175 offset:32
	v_mfma_f32_32x32x16_bf16 v[80:95], v[132:135], v[144:147], v[80:95]
	ds_read_b128 v[196:199], v175 offset:4640
	ds_read_b128 v[200:203], v175 offset:9248
	v_mfma_f32_32x32x16_bf16 v[64:79], v[132:135], v[148:151], v[64:79]
	ds_read_b128 v[204:207], v175 offset:13856
	buffer_load_dwordx4 v[162:165], v160, s[8:11], 0 offen
	v_mfma_f32_32x32x16_bf16 v[48:63], v[136:139], v[144:147], v[48:63]
	buffer_load_dwordx4 v[166:169], v160, s[8:11], s28 offen
	buffer_load_dwordx4 v[176:179], v160, s[8:11], s29 offen
	v_mfma_f32_32x32x16_bf16 v[32:47], v[136:139], v[148:151], v[32:47]
	buffer_load_dwordx4 v[180:183], v160, s[8:11], s30 offen
	buffer_load_dwordx4 v[184:187], v160, s[24:27], 0 offen
	v_mfma_f32_32x32x16_bf16 v[16:31], v[140:143], v[144:147], v[16:31]
	buffer_load_dwordx4 v[242:245], v160, s[24:27], s28 offen
	buffer_load_dwordx4 v[246:249], v160, s[24:27], s29 offen
	v_mfma_f32_32x32x16_bf16 v[0:15], v[140:143], v[148:151], v[0:15]
	buffer_load_dwordx4 v[250:253], v160, s[24:27], s30 offen
	v_add_u32_e32 v160, 0x80, v160
	s_waitcnt lgkmcnt(0)
	v_mfma_f32_32x32x16_bf16 v[112:127], v[192:195], v[208:211], v[112:127]
	v_mfma_f32_32x32x16_bf16 v[96:111], v[192:195], v[212:215], v[96:111]
	ds_read_b128 v[144:147], v254 offset:64
	v_mfma_f32_32x32x16_bf16 v[80:95], v[196:199], v[208:211], v[80:95]
	ds_read_b128 v[148:151], v254 offset:4672
	v_mfma_f32_32x32x16_bf16 v[64:79], v[196:199], v[212:215], v[64:79]
	ds_read_b128 v[128:131], v175 offset:64
	v_mfma_f32_32x32x16_bf16 v[48:63], v[200:203], v[208:211], v[48:63]
	v_mfma_f32_32x32x16_bf16 v[32:47], v[200:203], v[212:215], v[32:47]
	ds_read_b128 v[132:135], v175 offset:4672
	v_mfma_f32_32x32x16_bf16 v[16:31], v[204:207], v[208:211], v[16:31]
	ds_read_b128 v[136:139], v175 offset:9280
	v_mfma_f32_32x32x16_bf16 v[0:15], v[204:207], v[212:215], v[0:15]
	ds_read_b128 v[140:143], v175 offset:13888
	s_waitcnt lgkmcnt(0)
	v_mfma_f32_32x32x16_bf16 v[112:127], v[128:131], v[144:147], v[112:127]
	v_mfma_f32_32x32x16_bf16 v[96:111], v[128:131], v[148:151], v[96:111]
	ds_read_b128 v[208:211], v254 offset:96
	v_mfma_f32_32x32x16_bf16 v[80:95], v[132:135], v[144:147], v[80:95]
	ds_read_b128 v[212:215], v254 offset:4704
	v_mfma_f32_32x32x16_bf16 v[64:79], v[132:135], v[148:151], v[64:79]
	ds_read_b128 v[192:195], v175 offset:96
	v_mfma_f32_32x32x16_bf16 v[48:63], v[136:139], v[144:147], v[48:63]
	v_mfma_f32_32x32x16_bf16 v[32:47], v[136:139], v[148:151], v[32:47]
	ds_read_b128 v[196:199], v175 offset:4704
	v_mfma_f32_32x32x16_bf16 v[16:31], v[140:143], v[144:147], v[16:31]
	ds_read_b128 v[200:203], v175 offset:9312
	v_mfma_f32_32x32x16_bf16 v[0:15], v[140:143], v[148:151], v[0:15]
	ds_read_b128 v[204:207], v175 offset:13920
	s_waitcnt lgkmcnt(0)
	s_barrier
	ds_read_b128 v[144:147], v254 offset:36864
	ds_read_b128 v[148:151], v254 offset:41472
	ds_read_b128 v[128:131], v175 offset:36864
	ds_read_b128 v[132:135], v175 offset:41472
	ds_read_b128 v[136:139], v175 offset:46080
	ds_read_b128 v[140:143], v175 offset:50688
	v_mfma_f32_32x32x16_bf16 v[112:127], v[192:195], v[208:211], v[112:127]
	s_waitcnt vmcnt(8)
	v_mfma_f32_32x32x16_bf16 v[96:111], v[192:195], v[212:215], v[96:111]
	ds_write_b128 v170, v[216:219] offset:0
	v_mfma_f32_32x32x16_bf16 v[80:95], v[196:199], v[208:211], v[80:95]
	ds_write_b128 v170, v[220:223] offset:9216
	v_mfma_f32_32x32x16_bf16 v[64:79], v[196:199], v[212:215], v[64:79]
	ds_write_b128 v170, v[224:227] offset:18432
	v_mfma_f32_32x32x16_bf16 v[48:63], v[200:203], v[208:211], v[48:63]
	ds_write_b128 v170, v[228:231] offset:27648
	v_mfma_f32_32x32x16_bf16 v[32:47], v[200:203], v[212:215], v[32:47]
	ds_write_b128 v171, v[232:235] offset:0
	v_mfma_f32_32x32x16_bf16 v[16:31], v[204:207], v[208:211], v[16:31]
	ds_write_b128 v171, v[236:239] offset:9216
	v_mfma_f32_32x32x16_bf16 v[0:15], v[204:207], v[212:215], v[0:15]
	ds_write_b128 v171, v[152:155] offset:18432
	ds_write_b128 v171, v[156:159] offset:27648
	s_waitcnt lgkmcnt(8)
	v_mfma_f32_32x32x16_bf16 v[112:127], v[128:131], v[144:147], v[112:127]
	v_mfma_f32_32x32x16_bf16 v[96:111], v[128:131], v[148:151], v[96:111]
	ds_read_b128 v[208:211], v254 offset:36896
	v_mfma_f32_32x32x16_bf16 v[80:95], v[132:135], v[144:147], v[80:95]
	ds_read_b128 v[212:215], v254 offset:41504
	v_mfma_f32_32x32x16_bf16 v[64:79], v[132:135], v[148:151], v[64:79]
	ds_read_b128 v[192:195], v175 offset:36896
	v_mfma_f32_32x32x16_bf16 v[48:63], v[136:139], v[144:147], v[48:63]
	v_mfma_f32_32x32x16_bf16 v[32:47], v[136:139], v[148:151], v[32:47]
	ds_read_b128 v[196:199], v175 offset:41504
	v_mfma_f32_32x32x16_bf16 v[16:31], v[140:143], v[144:147], v[16:31]
	ds_read_b128 v[200:203], v175 offset:46112
	v_mfma_f32_32x32x16_bf16 v[0:15], v[140:143], v[148:151], v[0:15]
	ds_read_b128 v[204:207], v175 offset:50720
	s_waitcnt lgkmcnt(0)
	v_mfma_f32_32x32x16_bf16 v[112:127], v[192:195], v[208:211], v[112:127]
	v_mfma_f32_32x32x16_bf16 v[96:111], v[192:195], v[212:215], v[96:111]
	ds_read_b128 v[144:147], v254 offset:36928
	v_mfma_f32_32x32x16_bf16 v[80:95], v[196:199], v[208:211], v[80:95]
	ds_read_b128 v[148:151], v254 offset:41536
	v_mfma_f32_32x32x16_bf16 v[64:79], v[196:199], v[212:215], v[64:79]
	ds_read_b128 v[128:131], v175 offset:36928
	v_mfma_f32_32x32x16_bf16 v[48:63], v[200:203], v[208:211], v[48:63]
	v_mfma_f32_32x32x16_bf16 v[32:47], v[200:203], v[212:215], v[32:47]
	ds_read_b128 v[132:135], v175 offset:41536
	v_mfma_f32_32x32x16_bf16 v[16:31], v[204:207], v[208:211], v[16:31]
	ds_read_b128 v[136:139], v175 offset:46144
	v_mfma_f32_32x32x16_bf16 v[0:15], v[204:207], v[212:215], v[0:15]
	ds_read_b128 v[140:143], v175 offset:50752
	s_waitcnt lgkmcnt(0)
	v_mfma_f32_32x32x16_bf16 v[112:127], v[128:131], v[144:147], v[112:127]
	v_mfma_f32_32x32x16_bf16 v[96:111], v[128:131], v[148:151], v[96:111]
	ds_read_b128 v[208:211], v254 offset:36960
	v_mfma_f32_32x32x16_bf16 v[80:95], v[132:135], v[144:147], v[80:95]
	ds_read_b128 v[212:215], v254 offset:41568
	v_mfma_f32_32x32x16_bf16 v[64:79], v[132:135], v[148:151], v[64:79]
	ds_read_b128 v[192:195], v175 offset:36960
	v_mfma_f32_32x32x16_bf16 v[48:63], v[136:139], v[144:147], v[48:63]
	v_mfma_f32_32x32x16_bf16 v[32:47], v[136:139], v[148:151], v[32:47]
	ds_read_b128 v[196:199], v175 offset:41568
	v_mfma_f32_32x32x16_bf16 v[16:31], v[140:143], v[144:147], v[16:31]
	ds_read_b128 v[200:203], v175 offset:46176
	v_mfma_f32_32x32x16_bf16 v[0:15], v[140:143], v[148:151], v[0:15]
	ds_read_b128 v[204:207], v175 offset:50784
	s_waitcnt lgkmcnt(0)
	s_barrier
	ds_read_b128 v[144:147], v254 offset:0
	ds_read_b128 v[148:151], v254 offset:4608
	ds_read_b128 v[128:131], v175 offset:0
	ds_read_b128 v[132:135], v175 offset:4608
	ds_read_b128 v[136:139], v175 offset:9216
	ds_read_b128 v[140:143], v175 offset:13824
	v_mfma_f32_32x32x16_bf16 v[112:127], v[192:195], v[208:211], v[112:127]
	s_waitcnt vmcnt(0)
	v_mfma_f32_32x32x16_bf16 v[96:111], v[192:195], v[212:215], v[96:111]
	ds_write_b128 v170, v[162:165] offset:36864
	v_mfma_f32_32x32x16_bf16 v[80:95], v[196:199], v[208:211], v[80:95]
	ds_write_b128 v170, v[166:169] offset:46080
	v_mfma_f32_32x32x16_bf16 v[64:79], v[196:199], v[212:215], v[64:79]
	ds_write_b128 v170, v[176:179] offset:55296
	v_mfma_f32_32x32x16_bf16 v[48:63], v[200:203], v[208:211], v[48:63]
	ds_write_b128 v170, v[180:183] offset:64512
	v_mfma_f32_32x32x16_bf16 v[32:47], v[200:203], v[212:215], v[32:47]
	ds_write_b128 v171, v[184:187] offset:36864
	v_mfma_f32_32x32x16_bf16 v[16:31], v[204:207], v[208:211], v[16:31]
	ds_write_b128 v171, v[242:245] offset:46080
	v_mfma_f32_32x32x16_bf16 v[0:15], v[204:207], v[212:215], v[0:15]
	ds_write_b128 v171, v[246:249] offset:55296
	ds_write_b128 v171, v[250:253] offset:64512
	s_waitcnt lgkmcnt(8)
	v_mfma_f32_32x32x16_bf16 v[112:127], v[128:131], v[144:147], v[112:127]
	v_mfma_f32_32x32x16_bf16 v[96:111], v[128:131], v[148:151], v[96:111]
	ds_read_b128 v[208:211], v254 offset:32
	v_mfma_f32_32x32x16_bf16 v[80:95], v[132:135], v[144:147], v[80:95]
	ds_read_b128 v[212:215], v254 offset:4640
	v_mfma_f32_32x32x16_bf16 v[64:79], v[132:135], v[148:151], v[64:79]
	ds_read_b128 v[192:195], v175 offset:32
	v_mfma_f32_32x32x16_bf16 v[48:63], v[136:139], v[144:147], v[48:63]
	v_mfma_f32_32x32x16_bf16 v[32:47], v[136:139], v[148:151], v[32:47]
	ds_read_b128 v[196:199], v175 offset:4640
	v_mfma_f32_32x32x16_bf16 v[16:31], v[140:143], v[144:147], v[16:31]
	ds_read_b128 v[200:203], v175 offset:9248
	v_mfma_f32_32x32x16_bf16 v[0:15], v[140:143], v[148:151], v[0:15]
	ds_read_b128 v[204:207], v175 offset:13856
	s_waitcnt lgkmcnt(0)
	v_mfma_f32_32x32x16_bf16 v[112:127], v[192:195], v[208:211], v[112:127]
	v_mfma_f32_32x32x16_bf16 v[96:111], v[192:195], v[212:215], v[96:111]
	ds_read_b128 v[144:147], v254 offset:64
	v_mfma_f32_32x32x16_bf16 v[80:95], v[196:199], v[208:211], v[80:95]
	ds_read_b128 v[148:151], v254 offset:4672
	v_mfma_f32_32x32x16_bf16 v[64:79], v[196:199], v[212:215], v[64:79]
	ds_read_b128 v[128:131], v175 offset:64
	v_mfma_f32_32x32x16_bf16 v[48:63], v[200:203], v[208:211], v[48:63]
	v_mfma_f32_32x32x16_bf16 v[32:47], v[200:203], v[212:215], v[32:47]
	ds_read_b128 v[132:135], v175 offset:4672
	v_mfma_f32_32x32x16_bf16 v[16:31], v[204:207], v[208:211], v[16:31]
	ds_read_b128 v[136:139], v175 offset:9280
	v_mfma_f32_32x32x16_bf16 v[0:15], v[204:207], v[212:215], v[0:15]
	ds_read_b128 v[140:143], v175 offset:13888
	s_waitcnt lgkmcnt(0)
	v_mfma_f32_32x32x16_bf16 v[112:127], v[128:131], v[144:147], v[112:127]
	v_mfma_f32_32x32x16_bf16 v[96:111], v[128:131], v[148:151], v[96:111]
	ds_read_b128 v[208:211], v254 offset:96
	v_mfma_f32_32x32x16_bf16 v[80:95], v[132:135], v[144:147], v[80:95]
	ds_read_b128 v[212:215], v254 offset:4704
	v_mfma_f32_32x32x16_bf16 v[64:79], v[132:135], v[148:151], v[64:79]
	ds_read_b128 v[192:195], v175 offset:96
	v_mfma_f32_32x32x16_bf16 v[48:63], v[136:139], v[144:147], v[48:63]
	v_mfma_f32_32x32x16_bf16 v[32:47], v[136:139], v[148:151], v[32:47]
	ds_read_b128 v[196:199], v175 offset:4704
	v_mfma_f32_32x32x16_bf16 v[16:31], v[140:143], v[144:147], v[16:31]
	ds_read_b128 v[200:203], v175 offset:9312
	v_mfma_f32_32x32x16_bf16 v[0:15], v[140:143], v[148:151], v[0:15]
	ds_read_b128 v[204:207], v175 offset:13920
	s_waitcnt lgkmcnt(0)
	s_barrier
	ds_read_b128 v[144:147], v254 offset:36864
	ds_read_b128 v[148:151], v254 offset:41472
	ds_read_b128 v[128:131], v175 offset:36864
	ds_read_b128 v[132:135], v175 offset:41472
	ds_read_b128 v[136:139], v175 offset:46080
	ds_read_b128 v[140:143], v175 offset:50688
	v_mfma_f32_32x32x16_bf16 v[112:127], v[192:195], v[208:211], v[112:127]
	v_mfma_f32_32x32x16_bf16 v[96:111], v[192:195], v[212:215], v[96:111]
	v_mfma_f32_32x32x16_bf16 v[80:95], v[196:199], v[208:211], v[80:95]
	v_mfma_f32_32x32x16_bf16 v[64:79], v[196:199], v[212:215], v[64:79]
	v_mfma_f32_32x32x16_bf16 v[48:63], v[200:203], v[208:211], v[48:63]
	v_mfma_f32_32x32x16_bf16 v[32:47], v[200:203], v[212:215], v[32:47]
	v_mfma_f32_32x32x16_bf16 v[16:31], v[204:207], v[208:211], v[16:31]
	v_mfma_f32_32x32x16_bf16 v[0:15], v[204:207], v[212:215], v[0:15]
	s_waitcnt lgkmcnt(0)
	v_mfma_f32_32x32x16_bf16 v[112:127], v[128:131], v[144:147], v[112:127]
	v_mfma_f32_32x32x16_bf16 v[96:111], v[128:131], v[148:151], v[96:111]
	ds_read_b128 v[208:211], v254 offset:36896
	v_mfma_f32_32x32x16_bf16 v[80:95], v[132:135], v[144:147], v[80:95]
	ds_read_b128 v[212:215], v254 offset:41504
	v_mfma_f32_32x32x16_bf16 v[64:79], v[132:135], v[148:151], v[64:79]
	ds_read_b128 v[192:195], v175 offset:36896
	v_mfma_f32_32x32x16_bf16 v[48:63], v[136:139], v[144:147], v[48:63]
	v_mfma_f32_32x32x16_bf16 v[32:47], v[136:139], v[148:151], v[32:47]
	ds_read_b128 v[196:199], v175 offset:41504
	v_mfma_f32_32x32x16_bf16 v[16:31], v[140:143], v[144:147], v[16:31]
	ds_read_b128 v[200:203], v175 offset:46112
	v_mfma_f32_32x32x16_bf16 v[0:15], v[140:143], v[148:151], v[0:15]
	ds_read_b128 v[204:207], v175 offset:50720
	s_waitcnt lgkmcnt(0)
	v_mfma_f32_32x32x16_bf16 v[112:127], v[192:195], v[208:211], v[112:127]
	v_mfma_f32_32x32x16_bf16 v[96:111], v[192:195], v[212:215], v[96:111]
	ds_read_b128 v[144:147], v254 offset:36928
	v_mfma_f32_32x32x16_bf16 v[80:95], v[196:199], v[208:211], v[80:95]
	ds_read_b128 v[148:151], v254 offset:41536
	v_mfma_f32_32x32x16_bf16 v[64:79], v[196:199], v[212:215], v[64:79]
	ds_read_b128 v[128:131], v175 offset:36928
	v_mfma_f32_32x32x16_bf16 v[48:63], v[200:203], v[208:211], v[48:63]
	v_mfma_f32_32x32x16_bf16 v[32:47], v[200:203], v[212:215], v[32:47]
	ds_read_b128 v[132:135], v175 offset:41536
	v_mfma_f32_32x32x16_bf16 v[16:31], v[204:207], v[208:211], v[16:31]
	ds_read_b128 v[136:139], v175 offset:46144
	v_mfma_f32_32x32x16_bf16 v[0:15], v[204:207], v[212:215], v[0:15]
	ds_read_b128 v[140:143], v175 offset:50752
	s_waitcnt lgkmcnt(0)
	v_mfma_f32_32x32x16_bf16 v[112:127], v[128:131], v[144:147], v[112:127]
	v_mfma_f32_32x32x16_bf16 v[96:111], v[128:131], v[148:151], v[96:111]
	ds_read_b128 v[208:211], v254 offset:36960
	v_mfma_f32_32x32x16_bf16 v[80:95], v[132:135], v[144:147], v[80:95]
	ds_read_b128 v[212:215], v254 offset:41568
	v_mfma_f32_32x32x16_bf16 v[64:79], v[132:135], v[148:151], v[64:79]
	ds_read_b128 v[192:195], v175 offset:36960
	v_mfma_f32_32x32x16_bf16 v[48:63], v[136:139], v[144:147], v[48:63]
	v_mfma_f32_32x32x16_bf16 v[32:47], v[136:139], v[148:151], v[32:47]
	ds_read_b128 v[196:199], v175 offset:41568
	v_mfma_f32_32x32x16_bf16 v[16:31], v[140:143], v[144:147], v[16:31]
	ds_read_b128 v[200:203], v175 offset:46176
	v_mfma_f32_32x32x16_bf16 v[0:15], v[140:143], v[148:151], v[0:15]
	ds_read_b128 v[204:207], v175 offset:50784
	s_waitcnt lgkmcnt(0)
	s_barrier
	v_mfma_f32_32x32x16_bf16 v[112:127], v[192:195], v[208:211], v[112:127]
	v_mfma_f32_32x32x16_bf16 v[96:111], v[192:195], v[212:215], v[96:111]
	v_mfma_f32_32x32x16_bf16 v[80:95], v[196:199], v[208:211], v[80:95]
	v_mfma_f32_32x32x16_bf16 v[64:79], v[196:199], v[212:215], v[64:79]
	v_mfma_f32_32x32x16_bf16 v[48:63], v[200:203], v[208:211], v[48:63]
	v_mfma_f32_32x32x16_bf16 v[32:47], v[200:203], v[212:215], v[32:47]
	v_mfma_f32_32x32x16_bf16 v[16:31], v[204:207], v[208:211], v[16:31]
	v_mfma_f32_32x32x16_bf16 v[0:15], v[204:207], v[212:215], v[0:15]
	s_nop 7
	s_nop 7
	s_cmp_lt_u32 s6, 0x2000
	s_cbranch_scc1 .Lo1_prompt
	s_sub_u32 s10, s6, 0x2000
	s_lshr_b32 s11, s10, 12
	s_add_u32 s11, s11, 1
	s_branch .Lo1_join

.LBB0_2633:
.Lgwq1_tile:
	s_bfe_u32 s100, s38, 0x30005
	s_and_b32 s101, s38, 31
	s_lshr_b32 s82, s38, 8
	s_lshl_b32 s64, s82, 5
	s_lshr_b32 s82, s100, 1
	s_lshl_b32 s82, s82, 3
	s_add_u32 s64, s64, s82
	s_lshr_b32 s82, s101, 2
	s_add_u32 s64, s64, s82
	s_and_b32 s82, s100, 1
	s_lshl_b32 s82, s82, 2
	s_and_b32 s101, s101, 3
	s_add_u32 s82, s82, s101
	s_lshl_b32 s64, s64, 8
	s_lshl_b32 s82, s82, 8
	s_lshl_b32 s100, s64, 12
	s_add_u32 s100, s100, 0x6224000
	s_add_u32 s48, s92, s100
	s_addc_u32 s49, s93, 0
	s_and_b32 s49, s49, 0xffff
	s_mov_b32 s50, 0x100000
	s_mov_b32 s51, 0x20000
	s_lshl_b32 s100, s82, 12
	s_add_u32 s100, s100, 0x4380000
	s_add_u32 s52, s92, s100
	s_addc_u32 s53, s93, 0
	s_and_b32 s53, s53, 0xffff
	s_sub_u32 s100, 0x800, s82
	s_min_u32 s100, s100, 0x100
	s_lshl_b32 s54, s100, 12
	s_mov_b32 s55, 0x20000
	s_mov_b32 s46, 0x40000
	s_mov_b32 s47, 0x80000
	s_mov_b32 s58, 0xc0000
	v_lshrrev_b32_e32 v128, 3, v190
	v_and_b32_e32 v129, 7, v190
	v_lshlrev_b32_e32 v129, 4, v129
	v_lshl_add_u32 v160, v128, 12, v129
	v_mul_u32_u24_e32 v130, 0x90, v128
	v_add_u32_e32 v170, v130, v129
	v_add_u32_e32 v171, 0x12000, v170
	v_and_b32_e32 v131, 31, v190
	v_bfe_u32 v132, v190, 5, 1
	v_bfe_u32 v133, v190, 6, 2
	v_bfe_u32 v134, v190, 8, 1
	v_lshl_add_u32 v135, v134, 7, v131
	v_mul_u32_u24_e32 v135, 0x90, v135
	v_lshl_add_u32 v175, v132, 4, v135
	v_lshl_add_u32 v136, v133, 6, v131
	v_mul_u32_u24_e32 v136, 0x90, v136
	v_lshl_add_u32 v136, v132, 4, v136
	v_add_u32_e32 v254, 0x12000, v136
	v_mov_b32_e32 v0, 0
	v_mov_b32_e32 v1, 0
	v_mov_b32_e32 v2, 0
	v_mov_b32_e32 v3, 0
	v_mov_b32_e32 v4, 0
	v_mov_b32_e32 v5, 0
	v_mov_b32_e32 v6, 0
	v_mov_b32_e32 v7, 0
	v_mov_b32_e32 v8, 0
	v_mov_b32_e32 v9, 0
	v_mov_b32_e32 v10, 0
	v_mov_b32_e32 v11, 0
	v_mov_b32_e32 v12, 0
	v_mov_b32_e32 v13, 0
	v_mov_b32_e32 v14, 0
	v_mov_b32_e32 v15, 0
	v_mov_b32_e32 v16, 0
	v_mov_b32_e32 v17, 0
	v_mov_b32_e32 v18, 0
	v_mov_b32_e32 v19, 0
	v_mov_b32_e32 v20, 0
	v_mov_b32_e32 v21, 0
	v_mov_b32_e32 v22, 0
	v_mov_b32_e32 v23, 0
	v_mov_b32_e32 v24, 0
	v_mov_b32_e32 v25, 0
	v_mov_b32_e32 v26, 0
	v_mov_b32_e32 v27, 0
	v_mov_b32_e32 v28, 0
	v_mov_b32_e32 v29, 0
	v_mov_b32_e32 v30, 0
	v_mov_b32_e32 v31, 0
	v_mov_b32_e32 v32, 0
	v_mov_b32_e32 v33, 0
	v_mov_b32_e32 v34, 0
	v_mov_b32_e32 v35, 0
	v_mov_b32_e32 v36, 0
	v_mov_b32_e32 v37, 0
	v_mov_b32_e32 v38, 0
	v_mov_b32_e32 v39, 0
	v_mov_b32_e32 v40, 0
	v_mov_b32_e32 v41, 0
	v_mov_b32_e32 v42, 0
	v_mov_b32_e32 v43, 0
	v_mov_b32_e32 v44, 0
	v_mov_b32_e32 v45, 0
	v_mov_b32_e32 v46, 0
	v_mov_b32_e32 v47, 0
	v_mov_b32_e32 v48, 0
	v_mov_b32_e32 v49, 0
	v_mov_b32_e32 v50, 0
	v_mov_b32_e32 v51, 0
	v_mov_b32_e32 v52, 0
	v_mov_b32_e32 v53, 0
	v_mov_b32_e32 v54, 0
	v_mov_b32_e32 v55, 0
	v_mov_b32_e32 v56, 0
	v_mov_b32_e32 v57, 0
	v_mov_b32_e32 v58, 0
	v_mov_b32_e32 v59, 0
	v_mov_b32_e32 v60, 0
	v_mov_b32_e32 v61, 0
	v_mov_b32_e32 v62, 0
	v_mov_b32_e32 v63, 0
	v_mov_b32_e32 v64, 0
	v_mov_b32_e32 v65, 0
	v_mov_b32_e32 v66, 0
	v_mov_b32_e32 v67, 0
	v_mov_b32_e32 v68, 0
	v_mov_b32_e32 v69, 0
	v_mov_b32_e32 v70, 0
	v_mov_b32_e32 v71, 0
	v_mov_b32_e32 v72, 0
	v_mov_b32_e32 v73, 0
	v_mov_b32_e32 v74, 0
	v_mov_b32_e32 v75, 0
	v_mov_b32_e32 v76, 0
	v_mov_b32_e32 v77, 0
	v_mov_b32_e32 v78, 0
	v_mov_b32_e32 v79, 0
	v_mov_b32_e32 v80, 0
	v_mov_b32_e32 v81, 0
	v_mov_b32_e32 v82, 0
	v_mov_b32_e32 v83, 0
	v_mov_b32_e32 v84, 0
	v_mov_b32_e32 v85, 0
	v_mov_b32_e32 v86, 0
	v_mov_b32_e32 v87, 0
	v_mov_b32_e32 v88, 0
	v_mov_b32_e32 v89, 0
	v_mov_b32_e32 v90, 0
	v_mov_b32_e32 v91, 0
	v_mov_b32_e32 v92, 0
	v_mov_b32_e32 v93, 0
	v_mov_b32_e32 v94, 0
	v_mov_b32_e32 v95, 0
	v_mov_b32_e32 v96, 0
	v_mov_b32_e32 v97, 0
	v_mov_b32_e32 v98, 0
	v_mov_b32_e32 v99, 0
	v_mov_b32_e32 v100, 0
	v_mov_b32_e32 v101, 0
	v_mov_b32_e32 v102, 0
	v_mov_b32_e32 v103, 0
	v_mov_b32_e32 v104, 0
	v_mov_b32_e32 v105, 0
	v_mov_b32_e32 v106, 0
	v_mov_b32_e32 v107, 0
	v_mov_b32_e32 v108, 0
	v_mov_b32_e32 v109, 0
	v_mov_b32_e32 v110, 0
	v_mov_b32_e32 v111, 0
	v_mov_b32_e32 v112, 0
	v_mov_b32_e32 v113, 0
	v_mov_b32_e32 v114, 0
	v_mov_b32_e32 v115, 0
	v_mov_b32_e32 v116, 0
	v_mov_b32_e32 v117, 0
	v_mov_b32_e32 v118, 0
	v_mov_b32_e32 v119, 0
	v_mov_b32_e32 v120, 0
	v_mov_b32_e32 v121, 0
	v_mov_b32_e32 v122, 0
	v_mov_b32_e32 v123, 0
	v_mov_b32_e32 v124, 0
	v_mov_b32_e32 v125, 0
	v_mov_b32_e32 v126, 0
	v_mov_b32_e32 v127, 0
	v_mov_b32_e32 v192, 0
	v_mov_b32_e32 v193, 0
	v_mov_b32_e32 v194, 0
	v_mov_b32_e32 v195, 0
	v_mov_b32_e32 v196, 0
	v_mov_b32_e32 v197, 0
	v_mov_b32_e32 v198, 0
	v_mov_b32_e32 v199, 0
	v_mov_b32_e32 v200, 0
	v_mov_b32_e32 v201, 0
	v_mov_b32_e32 v202, 0
	v_mov_b32_e32 v203, 0
	v_mov_b32_e32 v204, 0
	v_mov_b32_e32 v205, 0
	v_mov_b32_e32 v206, 0
	v_mov_b32_e32 v207, 0
	v_mov_b32_e32 v208, 0
	v_mov_b32_e32 v209, 0
	v_mov_b32_e32 v210, 0
	v_mov_b32_e32 v211, 0
	v_mov_b32_e32 v212, 0
	v_mov_b32_e32 v213, 0
	v_mov_b32_e32 v214, 0
	v_mov_b32_e32 v215, 0
	v_mov_b32_e32 v188, 0
	v_mov_b32_e32 v189, 0
	buffer_load_dwordx4 v[216:219], v160, s[48:51], 0 offen
	buffer_load_dwordx4 v[220:223], v160, s[48:51], s46 offen
	buffer_load_dwordx4 v[224:227], v160, s[48:51], s47 offen
	buffer_load_dwordx4 v[228:231], v160, s[48:51], s58 offen
	buffer_load_dwordx4 v[232:235], v160, s[52:55], 0 offen
	buffer_load_dwordx4 v[236:239], v160, s[52:55], s46 offen
	buffer_load_dwordx4 v[152:155], v160, s[52:55], s47 offen
	buffer_load_dwordx4 v[156:159], v160, s[52:55], s58 offen
	v_add_u32_e32 v160, 0x80, v160
	buffer_load_dwordx4 v[162:165], v160, s[48:51], 0 offen
	buffer_load_dwordx4 v[166:169], v160, s[48:51], s46 offen
	buffer_load_dwordx4 v[176:179], v160, s[48:51], s47 offen
	buffer_load_dwordx4 v[180:183], v160, s[48:51], s58 offen
	buffer_load_dwordx4 v[184:187], v160, s[52:55], 0 offen
	buffer_load_dwordx4 v[242:245], v160, s[52:55], s46 offen
	buffer_load_dwordx4 v[246:249], v160, s[52:55], s47 offen
	buffer_load_dwordx4 v[250:253], v160, s[52:55], s58 offen
	v_add_u32_e32 v160, 0x80, v160
	s_waitcnt vmcnt(8)
	ds_write_b128 v170, v[216:219] offset:0
	ds_write_b128 v170, v[220:223] offset:9216
	ds_write_b128 v170, v[224:227] offset:18432
	ds_write_b128 v170, v[228:231] offset:27648
	ds_write_b128 v171, v[232:235] offset:0
	ds_write_b128 v171, v[236:239] offset:9216
	ds_write_b128 v171, v[152:155] offset:18432
	ds_write_b128 v171, v[156:159] offset:27648
	buffer_load_dwordx4 v[216:219], v160, s[48:51], 0 offen
	buffer_load_dwordx4 v[220:223], v160, s[48:51], s46 offen
	buffer_load_dwordx4 v[224:227], v160, s[48:51], s47 offen
	buffer_load_dwordx4 v[228:231], v160, s[48:51], s58 offen
	buffer_load_dwordx4 v[232:235], v160, s[52:55], 0 offen
	buffer_load_dwordx4 v[236:239], v160, s[52:55], s46 offen
	buffer_load_dwordx4 v[152:155], v160, s[52:55], s47 offen
	buffer_load_dwordx4 v[156:159], v160, s[52:55], s58 offen
	v_add_u32_e32 v160, 0x80, v160
	s_waitcnt lgkmcnt(0)
	s_barrier
	s_movk_i32 s59, 14
.Lgwq1_loop:
	ds_read_b128 v[144:147], v254 offset:0
	ds_read_b128 v[148:151], v254 offset:4608
	ds_read_b128 v[128:131], v175 offset:0
	ds_read_b128 v[132:135], v175 offset:4608
	ds_read_b128 v[136:139], v175 offset:9216
	ds_read_b128 v[140:143], v175 offset:13824
	v_mfma_f32_32x32x16_bf16 v[112:127], v[192:195], v[208:211], v[112:127]
	s_waitcnt vmcnt(8)
	v_mfma_f32_32x32x16_bf16 v[96:111], v[192:195], v[212:215], v[96:111]
	ds_write_b128 v170, v[162:165] offset:36864
	v_mfma_f32_32x32x16_bf16 v[80:95], v[196:199], v[208:211], v[80:95]
	ds_write_b128 v170, v[166:169] offset:46080
	v_mfma_f32_32x32x16_bf16 v[64:79], v[196:199], v[212:215], v[64:79]
	ds_write_b128 v170, v[176:179] offset:55296
	v_mfma_f32_32x32x16_bf16 v[48:63], v[200:203], v[208:211], v[48:63]
	ds_write_b128 v170, v[180:183] offset:64512
	v_mfma_f32_32x32x16_bf16 v[32:47], v[200:203], v[212:215], v[32:47]
	ds_write_b128 v171, v[184:187] offset:36864
	v_mfma_f32_32x32x16_bf16 v[16:31], v[204:207], v[208:211], v[16:31]
	ds_write_b128 v171, v[242:245] offset:46080
	v_mfma_f32_32x32x16_bf16 v[0:15], v[204:207], v[212:215], v[0:15]
	ds_write_b128 v171, v[246:249] offset:55296
	ds_write_b128 v171, v[250:253] offset:64512
	s_waitcnt lgkmcnt(8)
	v_mfma_f32_32x32x16_bf16 v[112:127], v[128:131], v[144:147], v[112:127]
	ds_read_b128 v[208:211], v254 offset:32
	v_mfma_f32_32x32x16_bf16 v[96:111], v[128:131], v[148:151], v[96:111]
	ds_read_b128 v[212:215], v254 offset:4640
	ds_read_b128 v[192:195], v175 offset:32
	v_mfma_f32_32x32x16_bf16 v[80:95], v[132:135], v[144:147], v[80:95]
	ds_read_b128 v[196:199], v175 offset:4640
	ds_read_b128 v[200:203], v175 offset:9248
	v_mfma_f32_32x32x16_bf16 v[64:79], v[132:135], v[148:151], v[64:79]
	ds_read_b128 v[204:207], v175 offset:13856
	buffer_load_dwordx4 v[162:165], v160, s[48:51], 0 offen
	v_mfma_f32_32x32x16_bf16 v[48:63], v[136:139], v[144:147], v[48:63]
	buffer_load_dwordx4 v[166:169], v160, s[48:51], s46 offen
	buffer_load_dwordx4 v[176:179], v160, s[48:51], s47 offen
	v_mfma_f32_32x32x16_bf16 v[32:47], v[136:139], v[148:151], v[32:47]
	buffer_load_dwordx4 v[180:183], v160, s[48:51], s58 offen
	buffer_load_dwordx4 v[184:187], v160, s[52:55], 0 offen
	v_mfma_f32_32x32x16_bf16 v[16:31], v[140:143], v[144:147], v[16:31]
	buffer_load_dwordx4 v[242:245], v160, s[52:55], s46 offen
	buffer_load_dwordx4 v[246:249], v160, s[52:55], s47 offen
	v_mfma_f32_32x32x16_bf16 v[0:15], v[140:143], v[148:151], v[0:15]
	buffer_load_dwordx4 v[250:253], v160, s[52:55], s58 offen
	v_add_u32_e32 v160, 0x80, v160
	s_waitcnt lgkmcnt(0)
	v_mfma_f32_32x32x16_bf16 v[112:127], v[192:195], v[208:211], v[112:127]
	v_mfma_f32_32x32x16_bf16 v[96:111], v[192:195], v[212:215], v[96:111]
	ds_read_b128 v[144:147], v254 offset:64
	v_mfma_f32_32x32x16_bf16 v[80:95], v[196:199], v[208:211], v[80:95]
	ds_read_b128 v[148:151], v254 offset:4672
	v_mfma_f32_32x32x16_bf16 v[64:79], v[196:199], v[212:215], v[64:79]
	ds_read_b128 v[128:131], v175 offset:64
	v_mfma_f32_32x32x16_bf16 v[48:63], v[200:203], v[208:211], v[48:63]
	v_mfma_f32_32x32x16_bf16 v[32:47], v[200:203], v[212:215], v[32:47]
	ds_read_b128 v[132:135], v175 offset:4672
	v_mfma_f32_32x32x16_bf16 v[16:31], v[204:207], v[208:211], v[16:31]
	ds_read_b128 v[136:139], v175 offset:9280
	v_mfma_f32_32x32x16_bf16 v[0:15], v[204:207], v[212:215], v[0:15]
	ds_read_b128 v[140:143], v175 offset:13888
	s_waitcnt lgkmcnt(0)
	v_mfma_f32_32x32x16_bf16 v[112:127], v[128:131], v[144:147], v[112:127]
	v_mfma_f32_32x32x16_bf16 v[96:111], v[128:131], v[148:151], v[96:111]
	ds_read_b128 v[208:211], v254 offset:96
	v_mfma_f32_32x32x16_bf16 v[80:95], v[132:135], v[144:147], v[80:95]
	ds_read_b128 v[212:215], v254 offset:4704
	v_mfma_f32_32x32x16_bf16 v[64:79], v[132:135], v[148:151], v[64:79]
	ds_read_b128 v[192:195], v175 offset:96
	v_mfma_f32_32x32x16_bf16 v[48:63], v[136:139], v[144:147], v[48:63]
	v_mfma_f32_32x32x16_bf16 v[32:47], v[136:139], v[148:151], v[32:47]
	ds_read_b128 v[196:199], v175 offset:4704
	v_mfma_f32_32x32x16_bf16 v[16:31], v[140:143], v[144:147], v[16:31]
	ds_read_b128 v[200:203], v175 offset:9312
	v_mfma_f32_32x32x16_bf16 v[0:15], v[140:143], v[148:151], v[0:15]
	ds_read_b128 v[204:207], v175 offset:13920
	s_waitcnt lgkmcnt(0)
	s_barrier
	ds_read_b128 v[144:147], v254 offset:36864
	ds_read_b128 v[148:151], v254 offset:41472
	ds_read_b128 v[128:131], v175 offset:36864
	ds_read_b128 v[132:135], v175 offset:41472
	ds_read_b128 v[136:139], v175 offset:46080
	ds_read_b128 v[140:143], v175 offset:50688
	v_mfma_f32_32x32x16_bf16 v[112:127], v[192:195], v[208:211], v[112:127]
	s_waitcnt vmcnt(8)
	v_mfma_f32_32x32x16_bf16 v[96:111], v[192:195], v[212:215], v[96:111]
	ds_write_b128 v170, v[216:219] offset:0
	v_mfma_f32_32x32x16_bf16 v[80:95], v[196:199], v[208:211], v[80:95]
	ds_write_b128 v170, v[220:223] offset:9216
	v_mfma_f32_32x32x16_bf16 v[64:79], v[196:199], v[212:215], v[64:79]
	ds_write_b128 v170, v[224:227] offset:18432
	v_mfma_f32_32x32x16_bf16 v[48:63], v[200:203], v[208:211], v[48:63]
	ds_write_b128 v170, v[228:231] offset:27648
	v_mfma_f32_32x32x16_bf16 v[32:47], v[200:203], v[212:215], v[32:47]
	ds_write_b128 v171, v[232:235] offset:0
	v_mfma_f32_32x32x16_bf16 v[16:31], v[204:207], v[208:211], v[16:31]
	ds_write_b128 v171, v[236:239] offset:9216
	v_mfma_f32_32x32x16_bf16 v[0:15], v[204:207], v[212:215], v[0:15]
	ds_write_b128 v171, v[152:155] offset:18432
	ds_write_b128 v171, v[156:159] offset:27648
	s_waitcnt lgkmcnt(8)
	v_mfma_f32_32x32x16_bf16 v[112:127], v[128:131], v[144:147], v[112:127]
	ds_read_b128 v[208:211], v254 offset:36896
	v_mfma_f32_32x32x16_bf16 v[96:111], v[128:131], v[148:151], v[96:111]
	ds_read_b128 v[212:215], v254 offset:41504
	ds_read_b128 v[192:195], v175 offset:36896
	v_mfma_f32_32x32x16_bf16 v[80:95], v[132:135], v[144:147], v[80:95]
	ds_read_b128 v[196:199], v175 offset:41504
	ds_read_b128 v[200:203], v175 offset:46112
	v_mfma_f32_32x32x16_bf16 v[64:79], v[132:135], v[148:151], v[64:79]
	ds_read_b128 v[204:207], v175 offset:50720
	buffer_load_dwordx4 v[216:219], v160, s[48:51], 0 offen
	v_mfma_f32_32x32x16_bf16 v[48:63], v[136:139], v[144:147], v[48:63]
	buffer_load_dwordx4 v[220:223], v160, s[48:51], s46 offen
	buffer_load_dwordx4 v[224:227], v160, s[48:51], s47 offen
	v_mfma_f32_32x32x16_bf16 v[32:47], v[136:139], v[148:151], v[32:47]
	buffer_load_dwordx4 v[228:231], v160, s[48:51], s58 offen
	buffer_load_dwordx4 v[232:235], v160, s[52:55], 0 offen
	v_mfma_f32_32x32x16_bf16 v[16:31], v[140:143], v[144:147], v[16:31]
	buffer_load_dwordx4 v[236:239], v160, s[52:55], s46 offen
	buffer_load_dwordx4 v[152:155], v160, s[52:55], s47 offen
	v_mfma_f32_32x32x16_bf16 v[0:15], v[140:143], v[148:151], v[0:15]
	buffer_load_dwordx4 v[156:159], v160, s[52:55], s58 offen
	v_add_u32_e32 v160, 0x80, v160
	s_waitcnt lgkmcnt(0)
	v_mfma_f32_32x32x16_bf16 v[112:127], v[192:195], v[208:211], v[112:127]
	v_mfma_f32_32x32x16_bf16 v[96:111], v[192:195], v[212:215], v[96:111]
	ds_read_b128 v[144:147], v254 offset:36928
	v_mfma_f32_32x32x16_bf16 v[80:95], v[196:199], v[208:211], v[80:95]
	ds_read_b128 v[148:151], v254 offset:41536
	v_mfma_f32_32x32x16_bf16 v[64:79], v[196:199], v[212:215], v[64:79]
	ds_read_b128 v[128:131], v175 offset:36928
	v_mfma_f32_32x32x16_bf16 v[48:63], v[200:203], v[208:211], v[48:63]
	v_mfma_f32_32x32x16_bf16 v[32:47], v[200:203], v[212:215], v[32:47]
	ds_read_b128 v[132:135], v175 offset:41536
	v_mfma_f32_32x32x16_bf16 v[16:31], v[204:207], v[208:211], v[16:31]
	ds_read_b128 v[136:139], v175 offset:46144
	v_mfma_f32_32x32x16_bf16 v[0:15], v[204:207], v[212:215], v[0:15]
	ds_read_b128 v[140:143], v175 offset:50752
	s_waitcnt lgkmcnt(0)
	v_mfma_f32_32x32x16_bf16 v[112:127], v[128:131], v[144:147], v[112:127]
	v_mfma_f32_32x32x16_bf16 v[96:111], v[128:131], v[148:151], v[96:111]
	ds_read_b128 v[208:211], v254 offset:36960
	v_mfma_f32_32x32x16_bf16 v[80:95], v[132:135], v[144:147], v[80:95]
	ds_read_b128 v[212:215], v254 offset:41568
	v_mfma_f32_32x32x16_bf16 v[64:79], v[132:135], v[148:151], v[64:79]
	ds_read_b128 v[192:195], v175 offset:36960
	v_mfma_f32_32x32x16_bf16 v[48:63], v[136:139], v[144:147], v[48:63]
	v_mfma_f32_32x32x16_bf16 v[32:47], v[136:139], v[148:151], v[32:47]
	ds_read_b128 v[196:199], v175 offset:41568
	v_mfma_f32_32x32x16_bf16 v[16:31], v[140:143], v[144:147], v[16:31]
	ds_read_b128 v[200:203], v175 offset:46176
	v_mfma_f32_32x32x16_bf16 v[0:15], v[140:143], v[148:151], v[0:15]
	ds_read_b128 v[204:207], v175 offset:50784
	s_waitcnt lgkmcnt(0)
	s_barrier
	s_add_i32 s59, s59, -1
	s_cmp_lg_u32 s59, 0
	s_cbranch_scc1 .Lgwq1_loop
	ds_read_b128 v[144:147], v254 offset:0
	ds_read_b128 v[148:151], v254 offset:4608
	ds_read_b128 v[128:131], v175 offset:0
	ds_read_b128 v[132:135], v175 offset:4608
	ds_read_b128 v[136:139], v175 offset:9216
	ds_read_b128 v[140:143], v175 offset:13824
	v_mfma_f32_32x32x16_bf16 v[112:127], v[192:195], v[208:211], v[112:127]
	s_waitcnt vmcnt(8)
	v_mfma_f32_32x32x16_bf16 v[96:111], v[192:195], v[212:215], v[96:111]
	ds_write_b128 v170, v[162:165] offset:36864
	v_mfma_f32_32x32x16_bf16 v[80:95], v[196:199], v[208:211], v[80:95]
	ds_write_b128 v170, v[166:169] offset:46080
	v_mfma_f32_32x32x16_bf16 v[64:79], v[196:199], v[212:215], v[64:79]
	ds_write_b128 v170, v[176:179] offset:55296
	v_mfma_f32_32x32x16_bf16 v[48:63], v[200:203], v[208:211], v[48:63]
	ds_write_b128 v170, v[180:183] offset:64512
	v_mfma_f32_32x32x16_bf16 v[32:47], v[200:203], v[212:215], v[32:47]
	ds_write_b128 v171, v[184:187] offset:36864
	v_mfma_f32_32x32x16_bf16 v[16:31], v[204:207], v[208:211], v[16:31]
	ds_write_b128 v171, v[242:245] offset:46080
	v_mfma_f32_32x32x16_bf16 v[0:15], v[204:207], v[212:215], v[0:15]
	ds_write_b128 v171, v[246:249] offset:55296
	ds_write_b128 v171, v[250:253] offset:64512
	s_waitcnt lgkmcnt(8)
	v_mfma_f32_32x32x16_bf16 v[112:127], v[128:131], v[144:147], v[112:127]
	ds_read_b128 v[208:211], v254 offset:32
	v_mfma_f32_32x32x16_bf16 v[96:111], v[128:131], v[148:151], v[96:111]
	ds_read_b128 v[212:215], v254 offset:4640
	ds_read_b128 v[192:195], v175 offset:32
	v_mfma_f32_32x32x16_bf16 v[80:95], v[132:135], v[144:147], v[80:95]
	ds_read_b128 v[196:199], v175 offset:4640
	ds_read_b128 v[200:203], v175 offset:9248
	v_mfma_f32_32x32x16_bf16 v[64:79], v[132:135], v[148:151], v[64:79]
	ds_read_b128 v[204:207], v175 offset:13856
	buffer_load_dwordx4 v[162:165], v160, s[48:51], 0 offen
	v_mfma_f32_32x32x16_bf16 v[48:63], v[136:139], v[144:147], v[48:63]
	buffer_load_dwordx4 v[166:169], v160, s[48:51], s46 offen
	buffer_load_dwordx4 v[176:179], v160, s[48:51], s47 offen
	v_mfma_f32_32x32x16_bf16 v[32:47], v[136:139], v[148:151], v[32:47]
	buffer_load_dwordx4 v[180:183], v160, s[48:51], s58 offen
	buffer_load_dwordx4 v[184:187], v160, s[52:55], 0 offen
	v_mfma_f32_32x32x16_bf16 v[16:31], v[140:143], v[144:147], v[16:31]
	buffer_load_dwordx4 v[242:245], v160, s[52:55], s46 offen
	buffer_load_dwordx4 v[246:249], v160, s[52:55], s47 offen
	v_mfma_f32_32x32x16_bf16 v[0:15], v[140:143], v[148:151], v[0:15]
	buffer_load_dwordx4 v[250:253], v160, s[52:55], s58 offen
	v_add_u32_e32 v160, 0x80, v160
	s_waitcnt lgkmcnt(0)
	v_mfma_f32_32x32x16_bf16 v[112:127], v[192:195], v[208:211], v[112:127]
	v_mfma_f32_32x32x16_bf16 v[96:111], v[192:195], v[212:215], v[96:111]
	ds_read_b128 v[144:147], v254 offset:64
	v_mfma_f32_32x32x16_bf16 v[80:95], v[196:199], v[208:211], v[80:95]
	ds_read_b128 v[148:151], v254 offset:4672
	v_mfma_f32_32x32x16_bf16 v[64:79], v[196:199], v[212:215], v[64:79]
	ds_read_b128 v[128:131], v175 offset:64
	v_mfma_f32_32x32x16_bf16 v[48:63], v[200:203], v[208:211], v[48:63]
	v_mfma_f32_32x32x16_bf16 v[32:47], v[200:203], v[212:215], v[32:47]
	ds_read_b128 v[132:135], v175 offset:4672
	v_mfma_f32_32x32x16_bf16 v[16:31], v[204:207], v[208:211], v[16:31]
	ds_read_b128 v[136:139], v175 offset:9280
	v_mfma_f32_32x32x16_bf16 v[0:15], v[204:207], v[212:215], v[0:15]
	ds_read_b128 v[140:143], v175 offset:13888
	s_waitcnt lgkmcnt(0)
	v_mfma_f32_32x32x16_bf16 v[112:127], v[128:131], v[144:147], v[112:127]
	v_mfma_f32_32x32x16_bf16 v[96:111], v[128:131], v[148:151], v[96:111]
	ds_read_b128 v[208:211], v254 offset:96
	v_mfma_f32_32x32x16_bf16 v[80:95], v[132:135], v[144:147], v[80:95]
	ds_read_b128 v[212:215], v254 offset:4704
	v_mfma_f32_32x32x16_bf16 v[64:79], v[132:135], v[148:151], v[64:79]
	ds_read_b128 v[192:195], v175 offset:96
	v_mfma_f32_32x32x16_bf16 v[48:63], v[136:139], v[144:147], v[48:63]
	v_mfma_f32_32x32x16_bf16 v[32:47], v[136:139], v[148:151], v[32:47]
	ds_read_b128 v[196:199], v175 offset:4704
	v_mfma_f32_32x32x16_bf16 v[16:31], v[140:143], v[144:147], v[16:31]
	ds_read_b128 v[200:203], v175 offset:9312
	v_mfma_f32_32x32x16_bf16 v[0:15], v[140:143], v[148:151], v[0:15]
	ds_read_b128 v[204:207], v175 offset:13920
	s_waitcnt lgkmcnt(0)
	s_barrier
	ds_read_b128 v[144:147], v254 offset:36864
	ds_read_b128 v[148:151], v254 offset:41472
	ds_read_b128 v[128:131], v175 offset:36864
	ds_read_b128 v[132:135], v175 offset:41472
	ds_read_b128 v[136:139], v175 offset:46080
	ds_read_b128 v[140:143], v175 offset:50688
	v_mfma_f32_32x32x16_bf16 v[112:127], v[192:195], v[208:211], v[112:127]
	s_waitcnt vmcnt(8)
	v_mfma_f32_32x32x16_bf16 v[96:111], v[192:195], v[212:215], v[96:111]
	ds_write_b128 v170, v[216:219] offset:0
	v_mfma_f32_32x32x16_bf16 v[80:95], v[196:199], v[208:211], v[80:95]
	ds_write_b128 v170, v[220:223] offset:9216
	v_mfma_f32_32x32x16_bf16 v[64:79], v[196:199], v[212:215], v[64:79]
	ds_write_b128 v170, v[224:227] offset:18432
	v_mfma_f32_32x32x16_bf16 v[48:63], v[200:203], v[208:211], v[48:63]
	ds_write_b128 v170, v[228:231] offset:27648
	v_mfma_f32_32x32x16_bf16 v[32:47], v[200:203], v[212:215], v[32:47]
	ds_write_b128 v171, v[232:235] offset:0
	v_mfma_f32_32x32x16_bf16 v[16:31], v[204:207], v[208:211], v[16:31]
	ds_write_b128 v171, v[236:239] offset:9216
	v_mfma_f32_32x32x16_bf16 v[0:15], v[204:207], v[212:215], v[0:15]
	ds_write_b128 v171, v[152:155] offset:18432
	ds_write_b128 v171, v[156:159] offset:27648
	s_waitcnt lgkmcnt(8)
	v_mfma_f32_32x32x16_bf16 v[112:127], v[128:131], v[144:147], v[112:127]
	v_mfma_f32_32x32x16_bf16 v[96:111], v[128:131], v[148:151], v[96:111]
	ds_read_b128 v[208:211], v254 offset:36896
	v_mfma_f32_32x32x16_bf16 v[80:95], v[132:135], v[144:147], v[80:95]
	ds_read_b128 v[212:215], v254 offset:41504
	v_mfma_f32_32x32x16_bf16 v[64:79], v[132:135], v[148:151], v[64:79]
	ds_read_b128 v[192:195], v175 offset:36896
	v_mfma_f32_32x32x16_bf16 v[48:63], v[136:139], v[144:147], v[48:63]
	v_mfma_f32_32x32x16_bf16 v[32:47], v[136:139], v[148:151], v[32:47]
	ds_read_b128 v[196:199], v175 offset:41504
	v_mfma_f32_32x32x16_bf16 v[16:31], v[140:143], v[144:147], v[16:31]
	ds_read_b128 v[200:203], v175 offset:46112
	v_mfma_f32_32x32x16_bf16 v[0:15], v[140:143], v[148:151], v[0:15]
	ds_read_b128 v[204:207], v175 offset:50720
	s_waitcnt lgkmcnt(0)
	v_mfma_f32_32x32x16_bf16 v[112:127], v[192:195], v[208:211], v[112:127]
	v_mfma_f32_32x32x16_bf16 v[96:111], v[192:195], v[212:215], v[96:111]
	ds_read_b128 v[144:147], v254 offset:36928
	v_mfma_f32_32x32x16_bf16 v[80:95], v[196:199], v[208:211], v[80:95]
	ds_read_b128 v[148:151], v254 offset:41536
	v_mfma_f32_32x32x16_bf16 v[64:79], v[196:199], v[212:215], v[64:79]
	ds_read_b128 v[128:131], v175 offset:36928
	v_mfma_f32_32x32x16_bf16 v[48:63], v[200:203], v[208:211], v[48:63]
	v_mfma_f32_32x32x16_bf16 v[32:47], v[200:203], v[212:215], v[32:47]
	ds_read_b128 v[132:135], v175 offset:41536
	v_mfma_f32_32x32x16_bf16 v[16:31], v[204:207], v[208:211], v[16:31]
	ds_read_b128 v[136:139], v175 offset:46144
	v_mfma_f32_32x32x16_bf16 v[0:15], v[204:207], v[212:215], v[0:15]
	ds_read_b128 v[140:143], v175 offset:50752
	s_waitcnt lgkmcnt(0)
	v_mfma_f32_32x32x16_bf16 v[112:127], v[128:131], v[144:147], v[112:127]
	v_mfma_f32_32x32x16_bf16 v[96:111], v[128:131], v[148:151], v[96:111]
	ds_read_b128 v[208:211], v254 offset:36960
	v_mfma_f32_32x32x16_bf16 v[80:95], v[132:135], v[144:147], v[80:95]
	ds_read_b128 v[212:215], v254 offset:41568
	v_mfma_f32_32x32x16_bf16 v[64:79], v[132:135], v[148:151], v[64:79]
	ds_read_b128 v[192:195], v175 offset:36960
	v_mfma_f32_32x32x16_bf16 v[48:63], v[136:139], v[144:147], v[48:63]
	v_mfma_f32_32x32x16_bf16 v[32:47], v[136:139], v[148:151], v[32:47]
	ds_read_b128 v[196:199], v175 offset:41568
	v_mfma_f32_32x32x16_bf16 v[16:31], v[140:143], v[144:147], v[16:31]
	ds_read_b128 v[200:203], v175 offset:46176
	v_mfma_f32_32x32x16_bf16 v[0:15], v[140:143], v[148:151], v[0:15]
	ds_read_b128 v[204:207], v175 offset:50784
	s_waitcnt lgkmcnt(0)
	s_barrier
	ds_read_b128 v[144:147], v254 offset:0
	ds_read_b128 v[148:151], v254 offset:4608
	ds_read_b128 v[128:131], v175 offset:0
	ds_read_b128 v[132:135], v175 offset:4608
	ds_read_b128 v[136:139], v175 offset:9216
	ds_read_b128 v[140:143], v175 offset:13824
	v_mfma_f32_32x32x16_bf16 v[112:127], v[192:195], v[208:211], v[112:127]
	s_waitcnt vmcnt(0)
	v_mfma_f32_32x32x16_bf16 v[96:111], v[192:195], v[212:215], v[96:111]
	ds_write_b128 v170, v[162:165] offset:36864
	v_mfma_f32_32x32x16_bf16 v[80:95], v[196:199], v[208:211], v[80:95]
	ds_write_b128 v170, v[166:169] offset:46080
	v_mfma_f32_32x32x16_bf16 v[64:79], v[196:199], v[212:215], v[64:79]
	ds_write_b128 v170, v[176:179] offset:55296
	v_mfma_f32_32x32x16_bf16 v[48:63], v[200:203], v[208:211], v[48:63]
	ds_write_b128 v170, v[180:183] offset:64512
	v_mfma_f32_32x32x16_bf16 v[32:47], v[200:203], v[212:215], v[32:47]
	ds_write_b128 v171, v[184:187] offset:36864
	v_mfma_f32_32x32x16_bf16 v[16:31], v[204:207], v[208:211], v[16:31]
	ds_write_b128 v171, v[242:245] offset:46080
	v_mfma_f32_32x32x16_bf16 v[0:15], v[204:207], v[212:215], v[0:15]
	ds_write_b128 v171, v[246:249] offset:55296
	ds_write_b128 v171, v[250:253] offset:64512
	s_waitcnt lgkmcnt(8)
	v_mfma_f32_32x32x16_bf16 v[112:127], v[128:131], v[144:147], v[112:127]
	v_mfma_f32_32x32x16_bf16 v[96:111], v[128:131], v[148:151], v[96:111]
	ds_read_b128 v[208:211], v254 offset:32
	v_mfma_f32_32x32x16_bf16 v[80:95], v[132:135], v[144:147], v[80:95]
	ds_read_b128 v[212:215], v254 offset:4640
	v_mfma_f32_32x32x16_bf16 v[64:79], v[132:135], v[148:151], v[64:79]
	ds_read_b128 v[192:195], v175 offset:32
	v_mfma_f32_32x32x16_bf16 v[48:63], v[136:139], v[144:147], v[48:63]
	v_mfma_f32_32x32x16_bf16 v[32:47], v[136:139], v[148:151], v[32:47]
	ds_read_b128 v[196:199], v175 offset:4640
	v_mfma_f32_32x32x16_bf16 v[16:31], v[140:143], v[144:147], v[16:31]
	ds_read_b128 v[200:203], v175 offset:9248
	v_mfma_f32_32x32x16_bf16 v[0:15], v[140:143], v[148:151], v[0:15]
	ds_read_b128 v[204:207], v175 offset:13856
	s_waitcnt lgkmcnt(0)
	v_mfma_f32_32x32x16_bf16 v[112:127], v[192:195], v[208:211], v[112:127]
	v_mfma_f32_32x32x16_bf16 v[96:111], v[192:195], v[212:215], v[96:111]
	ds_read_b128 v[144:147], v254 offset:64
	v_mfma_f32_32x32x16_bf16 v[80:95], v[196:199], v[208:211], v[80:95]
	ds_read_b128 v[148:151], v254 offset:4672
	v_mfma_f32_32x32x16_bf16 v[64:79], v[196:199], v[212:215], v[64:79]
	ds_read_b128 v[128:131], v175 offset:64
	v_mfma_f32_32x32x16_bf16 v[48:63], v[200:203], v[208:211], v[48:63]
	v_mfma_f32_32x32x16_bf16 v[32:47], v[200:203], v[212:215], v[32:47]
	ds_read_b128 v[132:135], v175 offset:4672
	v_mfma_f32_32x32x16_bf16 v[16:31], v[204:207], v[208:211], v[16:31]
	ds_read_b128 v[136:139], v175 offset:9280
	v_mfma_f32_32x32x16_bf16 v[0:15], v[204:207], v[212:215], v[0:15]
	ds_read_b128 v[140:143], v175 offset:13888
	s_waitcnt lgkmcnt(0)
	v_mfma_f32_32x32x16_bf16 v[112:127], v[128:131], v[144:147], v[112:127]
	v_mfma_f32_32x32x16_bf16 v[96:111], v[128:131], v[148:151], v[96:111]
	ds_read_b128 v[208:211], v254 offset:96
	v_mfma_f32_32x32x16_bf16 v[80:95], v[132:135], v[144:147], v[80:95]
	ds_read_b128 v[212:215], v254 offset:4704
	v_mfma_f32_32x32x16_bf16 v[64:79], v[132:135], v[148:151], v[64:79]
	ds_read_b128 v[192:195], v175 offset:96
	v_mfma_f32_32x32x16_bf16 v[48:63], v[136:139], v[144:147], v[48:63]
	v_mfma_f32_32x32x16_bf16 v[32:47], v[136:139], v[148:151], v[32:47]
	ds_read_b128 v[196:199], v175 offset:4704
	v_mfma_f32_32x32x16_bf16 v[16:31], v[140:143], v[144:147], v[16:31]
	ds_read_b128 v[200:203], v175 offset:9312
	v_mfma_f32_32x32x16_bf16 v[0:15], v[140:143], v[148:151], v[0:15]
	ds_read_b128 v[204:207], v175 offset:13920
	s_waitcnt lgkmcnt(0)
	s_barrier
	ds_read_b128 v[144:147], v254 offset:36864
	ds_read_b128 v[148:151], v254 offset:41472
	ds_read_b128 v[128:131], v175 offset:36864
	ds_read_b128 v[132:135], v175 offset:41472
	ds_read_b128 v[136:139], v175 offset:46080
	ds_read_b128 v[140:143], v175 offset:50688
	v_mfma_f32_32x32x16_bf16 v[112:127], v[192:195], v[208:211], v[112:127]
	v_mfma_f32_32x32x16_bf16 v[96:111], v[192:195], v[212:215], v[96:111]
	v_mfma_f32_32x32x16_bf16 v[80:95], v[196:199], v[208:211], v[80:95]
	v_mfma_f32_32x32x16_bf16 v[64:79], v[196:199], v[212:215], v[64:79]
	v_mfma_f32_32x32x16_bf16 v[48:63], v[200:203], v[208:211], v[48:63]
	v_mfma_f32_32x32x16_bf16 v[32:47], v[200:203], v[212:215], v[32:47]
	v_mfma_f32_32x32x16_bf16 v[16:31], v[204:207], v[208:211], v[16:31]
	v_mfma_f32_32x32x16_bf16 v[0:15], v[204:207], v[212:215], v[0:15]
	s_waitcnt lgkmcnt(0)
	v_mfma_f32_32x32x16_bf16 v[112:127], v[128:131], v[144:147], v[112:127]
	v_mfma_f32_32x32x16_bf16 v[96:111], v[128:131], v[148:151], v[96:111]
	ds_read_b128 v[208:211], v254 offset:36896
	v_mfma_f32_32x32x16_bf16 v[80:95], v[132:135], v[144:147], v[80:95]
	ds_read_b128 v[212:215], v254 offset:41504
	v_mfma_f32_32x32x16_bf16 v[64:79], v[132:135], v[148:151], v[64:79]
	ds_read_b128 v[192:195], v175 offset:36896
	v_mfma_f32_32x32x16_bf16 v[48:63], v[136:139], v[144:147], v[48:63]
	v_mfma_f32_32x32x16_bf16 v[32:47], v[136:139], v[148:151], v[32:47]
	ds_read_b128 v[196:199], v175 offset:41504
	v_mfma_f32_32x32x16_bf16 v[16:31], v[140:143], v[144:147], v[16:31]
	ds_read_b128 v[200:203], v175 offset:46112
	v_mfma_f32_32x32x16_bf16 v[0:15], v[140:143], v[148:151], v[0:15]
	ds_read_b128 v[204:207], v175 offset:50720
	s_waitcnt lgkmcnt(0)
	v_mfma_f32_32x32x16_bf16 v[112:127], v[192:195], v[208:211], v[112:127]
	v_mfma_f32_32x32x16_bf16 v[96:111], v[192:195], v[212:215], v[96:111]
	ds_read_b128 v[144:147], v254 offset:36928
	v_mfma_f32_32x32x16_bf16 v[80:95], v[196:199], v[208:211], v[80:95]
	ds_read_b128 v[148:151], v254 offset:41536
	v_mfma_f32_32x32x16_bf16 v[64:79], v[196:199], v[212:215], v[64:79]
	ds_read_b128 v[128:131], v175 offset:36928
	v_mfma_f32_32x32x16_bf16 v[48:63], v[200:203], v[208:211], v[48:63]
	v_mfma_f32_32x32x16_bf16 v[32:47], v[200:203], v[212:215], v[32:47]
	ds_read_b128 v[132:135], v175 offset:41536
	v_mfma_f32_32x32x16_bf16 v[16:31], v[204:207], v[208:211], v[16:31]
	ds_read_b128 v[136:139], v175 offset:46144
	v_mfma_f32_32x32x16_bf16 v[0:15], v[204:207], v[212:215], v[0:15]
	ds_read_b128 v[140:143], v175 offset:50752
	s_waitcnt lgkmcnt(0)
	v_mfma_f32_32x32x16_bf16 v[112:127], v[128:131], v[144:147], v[112:127]
	v_mfma_f32_32x32x16_bf16 v[96:111], v[128:131], v[148:151], v[96:111]
	ds_read_b128 v[208:211], v254 offset:36960
	v_mfma_f32_32x32x16_bf16 v[80:95], v[132:135], v[144:147], v[80:95]
	ds_read_b128 v[212:215], v254 offset:41568
	v_mfma_f32_32x32x16_bf16 v[64:79], v[132:135], v[148:151], v[64:79]
	ds_read_b128 v[192:195], v175 offset:36960
	v_mfma_f32_32x32x16_bf16 v[48:63], v[136:139], v[144:147], v[48:63]
	v_mfma_f32_32x32x16_bf16 v[32:47], v[136:139], v[148:151], v[32:47]
	ds_read_b128 v[196:199], v175 offset:41568
	v_mfma_f32_32x32x16_bf16 v[16:31], v[140:143], v[144:147], v[16:31]
	ds_read_b128 v[200:203], v175 offset:46176
	v_mfma_f32_32x32x16_bf16 v[0:15], v[140:143], v[148:151], v[0:15]
	ds_read_b128 v[204:207], v175 offset:50784
	s_waitcnt lgkmcnt(0)
	s_barrier
	v_mfma_f32_32x32x16_bf16 v[112:127], v[192:195], v[208:211], v[112:127]
	v_mfma_f32_32x32x16_bf16 v[96:111], v[192:195], v[212:215], v[96:111]
	v_mfma_f32_32x32x16_bf16 v[80:95], v[196:199], v[208:211], v[80:95]
	v_mfma_f32_32x32x16_bf16 v[64:79], v[196:199], v[212:215], v[64:79]
	v_mfma_f32_32x32x16_bf16 v[48:63], v[200:203], v[208:211], v[48:63]
	v_mfma_f32_32x32x16_bf16 v[32:47], v[200:203], v[212:215], v[32:47]
	v_mfma_f32_32x32x16_bf16 v[16:31], v[204:207], v[208:211], v[16:31]
	v_mfma_f32_32x32x16_bf16 v[0:15], v[204:207], v[212:215], v[0:15]
	s_nop 7
	s_nop 7
	s_mul_i32 s100, s64, 0x1000
	s_mul_hi_u32 s101, s64, 0x1000
	s_add_u32 s100, s100, 0xa224000
	s_addc_u32 s101, s101, 0
	s_add_u32 s96, s92, s100
	s_addc_u32 s97, s93, s101
	s_and_b32 s97, s97, 0xffff
	s_mov_b32 s98, 0x100000
	s_mov_b32 s99, 0x20000
	s_movk_i32 s46, 0x7fff
	v_and_b32_e32 v132, 31, v190
	v_bfe_u32 v133, v190, 5, 1
	v_bfe_u32 v134, v190, 6, 2
	v_bfe_u32 v135, v190, 8, 1
	v_lshl_add_u32 v132, v134, 6, v132
	v_add_u32_e32 v132, s82, v132
	v_lshlrev_b32_e32 v132, 1, v132
	v_lshlrev_b32_e32 v135, 7, v135
	v_lshl_add_u32 v135, v133, 2, v135
	s_mov_b32 s47, 0x1000
	v_mul_lo_u32 v135, s47, v135
	v_add_u32_e32 v128, v135, v132
	v_add_u32_e32 v129, 0x1000, v128
	v_add_u32_e32 v130, 0x2000, v128
	v_add_u32_e32 v131, 0x3000, v128
	v_bfe_u32 v136, v112, 16, 1
	v_bfe_u32 v137, v113, 16, 1
	v_bfe_u32 v138, v114, 16, 1
	v_bfe_u32 v139, v115, 16, 1
	v_add3_u32 v112, v112, v136, s46
	v_add3_u32 v113, v113, v137, s46
	v_add3_u32 v114, v114, v138, s46
	v_add3_u32 v115, v115, v139, s46
	s_mov_b32 s101, 0x0
	buffer_store_short_d16_hi v112, v128, s[96:99], s101 offen
	buffer_store_short_d16_hi v113, v129, s[96:99], s101 offen
	buffer_store_short_d16_hi v114, v130, s[96:99], s101 offen
	buffer_store_short_d16_hi v115, v131, s[96:99], s101 offen
	v_bfe_u32 v136, v116, 16, 1
	v_bfe_u32 v137, v117, 16, 1
	v_bfe_u32 v138, v118, 16, 1
	v_bfe_u32 v139, v119, 16, 1
	v_add3_u32 v116, v116, v136, s46
	v_add3_u32 v117, v117, v137, s46
	v_add3_u32 v118, v118, v138, s46
	v_add3_u32 v119, v119, v139, s46
	s_mov_b32 s101, 0x8000
	buffer_store_short_d16_hi v116, v128, s[96:99], s101 offen
	buffer_store_short_d16_hi v117, v129, s[96:99], s101 offen
	buffer_store_short_d16_hi v118, v130, s[96:99], s101 offen
	buffer_store_short_d16_hi v119, v131, s[96:99], s101 offen
	v_bfe_u32 v136, v120, 16, 1
	v_bfe_u32 v137, v121, 16, 1
	v_bfe_u32 v138, v122, 16, 1
	v_bfe_u32 v139, v123, 16, 1
	v_add3_u32 v120, v120, v136, s46
	v_add3_u32 v121, v121, v137, s46
	v_add3_u32 v122, v122, v138, s46
	v_add3_u32 v123, v123, v139, s46
	s_mov_b32 s101, 0x10000
	buffer_store_short_d16_hi v120, v128, s[96:99], s101 offen
	buffer_store_short_d16_hi v121, v129, s[96:99], s101 offen
	buffer_store_short_d16_hi v122, v130, s[96:99], s101 offen
	buffer_store_short_d16_hi v123, v131, s[96:99], s101 offen
	v_bfe_u32 v136, v124, 16, 1
	v_bfe_u32 v137, v125, 16, 1
	v_bfe_u32 v138, v126, 16, 1
	v_bfe_u32 v139, v127, 16, 1
	v_add3_u32 v124, v124, v136, s46
	v_add3_u32 v125, v125, v137, s46
	v_add3_u32 v126, v126, v138, s46
	v_add3_u32 v127, v127, v139, s46
	s_mov_b32 s101, 0x18000
	buffer_store_short_d16_hi v124, v128, s[96:99], s101 offen
	buffer_store_short_d16_hi v125, v129, s[96:99], s101 offen
	buffer_store_short_d16_hi v126, v130, s[96:99], s101 offen
	buffer_store_short_d16_hi v127, v131, s[96:99], s101 offen
	v_bfe_u32 v136, v96, 16, 1
	v_bfe_u32 v137, v97, 16, 1
	v_bfe_u32 v138, v98, 16, 1
	v_bfe_u32 v139, v99, 16, 1
	v_add3_u32 v96, v96, v136, s46
	v_add3_u32 v97, v97, v137, s46
	v_add3_u32 v98, v98, v138, s46
	v_add3_u32 v99, v99, v139, s46
	s_mov_b32 s101, 0x0
	buffer_store_short_d16_hi v96, v128, s[96:99], s101 offen offset:64
	buffer_store_short_d16_hi v97, v129, s[96:99], s101 offen offset:64
	buffer_store_short_d16_hi v98, v130, s[96:99], s101 offen offset:64
	buffer_store_short_d16_hi v99, v131, s[96:99], s101 offen offset:64
	v_bfe_u32 v136, v100, 16, 1
	v_bfe_u32 v137, v101, 16, 1
	v_bfe_u32 v138, v102, 16, 1
	v_bfe_u32 v139, v103, 16, 1
	v_add3_u32 v100, v100, v136, s46
	v_add3_u32 v101, v101, v137, s46
	v_add3_u32 v102, v102, v138, s46
	v_add3_u32 v103, v103, v139, s46
	s_mov_b32 s101, 0x8000
	buffer_store_short_d16_hi v100, v128, s[96:99], s101 offen offset:64
	buffer_store_short_d16_hi v101, v129, s[96:99], s101 offen offset:64
	buffer_store_short_d16_hi v102, v130, s[96:99], s101 offen offset:64
	buffer_store_short_d16_hi v103, v131, s[96:99], s101 offen offset:64
	v_bfe_u32 v136, v104, 16, 1
	v_bfe_u32 v137, v105, 16, 1
	v_bfe_u32 v138, v106, 16, 1
	v_bfe_u32 v139, v107, 16, 1
	v_add3_u32 v104, v104, v136, s46
	v_add3_u32 v105, v105, v137, s46
	v_add3_u32 v106, v106, v138, s46
	v_add3_u32 v107, v107, v139, s46
	s_mov_b32 s101, 0x10000
	buffer_store_short_d16_hi v104, v128, s[96:99], s101 offen offset:64
	buffer_store_short_d16_hi v105, v129, s[96:99], s101 offen offset:64
	buffer_store_short_d16_hi v106, v130, s[96:99], s101 offen offset:64
	buffer_store_short_d16_hi v107, v131, s[96:99], s101 offen offset:64
	v_bfe_u32 v136, v108, 16, 1
	v_bfe_u32 v137, v109, 16, 1
	v_bfe_u32 v138, v110, 16, 1
	v_bfe_u32 v139, v111, 16, 1
	v_add3_u32 v108, v108, v136, s46
	v_add3_u32 v109, v109, v137, s46
	v_add3_u32 v110, v110, v138, s46
	v_add3_u32 v111, v111, v139, s46
	s_mov_b32 s101, 0x18000
	buffer_store_short_d16_hi v108, v128, s[96:99], s101 offen offset:64
	buffer_store_short_d16_hi v109, v129, s[96:99], s101 offen offset:64
	buffer_store_short_d16_hi v110, v130, s[96:99], s101 offen offset:64
	buffer_store_short_d16_hi v111, v131, s[96:99], s101 offen offset:64
	v_bfe_u32 v136, v80, 16, 1
	v_bfe_u32 v137, v81, 16, 1
	v_bfe_u32 v138, v82, 16, 1
	v_bfe_u32 v139, v83, 16, 1
	v_add3_u32 v80, v80, v136, s46
	v_add3_u32 v81, v81, v137, s46
	v_add3_u32 v82, v82, v138, s46
	v_add3_u32 v83, v83, v139, s46
	s_mov_b32 s101, 0x20000
	buffer_store_short_d16_hi v80, v128, s[96:99], s101 offen
	buffer_store_short_d16_hi v81, v129, s[96:99], s101 offen
	buffer_store_short_d16_hi v82, v130, s[96:99], s101 offen
	buffer_store_short_d16_hi v83, v131, s[96:99], s101 offen
	v_bfe_u32 v136, v84, 16, 1
	v_bfe_u32 v137, v85, 16, 1
	v_bfe_u32 v138, v86, 16, 1
	v_bfe_u32 v139, v87, 16, 1
	v_add3_u32 v84, v84, v136, s46
	v_add3_u32 v85, v85, v137, s46
	v_add3_u32 v86, v86, v138, s46
	v_add3_u32 v87, v87, v139, s46
	s_mov_b32 s101, 0x28000
	buffer_store_short_d16_hi v84, v128, s[96:99], s101 offen
	buffer_store_short_d16_hi v85, v129, s[96:99], s101 offen
	buffer_store_short_d16_hi v86, v130, s[96:99], s101 offen
	buffer_store_short_d16_hi v87, v131, s[96:99], s101 offen
	v_bfe_u32 v136, v88, 16, 1
	v_bfe_u32 v137, v89, 16, 1
	v_bfe_u32 v138, v90, 16, 1
	v_bfe_u32 v139, v91, 16, 1
	v_add3_u32 v88, v88, v136, s46
	v_add3_u32 v89, v89, v137, s46
	v_add3_u32 v90, v90, v138, s46
	v_add3_u32 v91, v91, v139, s46
	s_mov_b32 s101, 0x30000
	buffer_store_short_d16_hi v88, v128, s[96:99], s101 offen
	buffer_store_short_d16_hi v89, v129, s[96:99], s101 offen
	buffer_store_short_d16_hi v90, v130, s[96:99], s101 offen
	buffer_store_short_d16_hi v91, v131, s[96:99], s101 offen
	v_bfe_u32 v136, v92, 16, 1
	v_bfe_u32 v137, v93, 16, 1
	v_bfe_u32 v138, v94, 16, 1
	v_bfe_u32 v139, v95, 16, 1
	v_add3_u32 v92, v92, v136, s46
	v_add3_u32 v93, v93, v137, s46
	v_add3_u32 v94, v94, v138, s46
	v_add3_u32 v95, v95, v139, s46
	s_mov_b32 s101, 0x38000
	buffer_store_short_d16_hi v92, v128, s[96:99], s101 offen
	buffer_store_short_d16_hi v93, v129, s[96:99], s101 offen
	buffer_store_short_d16_hi v94, v130, s[96:99], s101 offen
	buffer_store_short_d16_hi v95, v131, s[96:99], s101 offen
	v_bfe_u32 v136, v64, 16, 1
	v_bfe_u32 v137, v65, 16, 1
	v_bfe_u32 v138, v66, 16, 1
	v_bfe_u32 v139, v67, 16, 1
	v_add3_u32 v64, v64, v136, s46
	v_add3_u32 v65, v65, v137, s46
	v_add3_u32 v66, v66, v138, s46
	v_add3_u32 v67, v67, v139, s46
	s_mov_b32 s101, 0x20000
	buffer_store_short_d16_hi v64, v128, s[96:99], s101 offen offset:64
	buffer_store_short_d16_hi v65, v129, s[96:99], s101 offen offset:64
	buffer_store_short_d16_hi v66, v130, s[96:99], s101 offen offset:64
	buffer_store_short_d16_hi v67, v131, s[96:99], s101 offen offset:64
	v_bfe_u32 v136, v68, 16, 1
	v_bfe_u32 v137, v69, 16, 1
	v_bfe_u32 v138, v70, 16, 1
	v_bfe_u32 v139, v71, 16, 1
	v_add3_u32 v68, v68, v136, s46
	v_add3_u32 v69, v69, v137, s46
	v_add3_u32 v70, v70, v138, s46
	v_add3_u32 v71, v71, v139, s46
	s_mov_b32 s101, 0x28000
	buffer_store_short_d16_hi v68, v128, s[96:99], s101 offen offset:64
	buffer_store_short_d16_hi v69, v129, s[96:99], s101 offen offset:64
	buffer_store_short_d16_hi v70, v130, s[96:99], s101 offen offset:64
	buffer_store_short_d16_hi v71, v131, s[96:99], s101 offen offset:64
	v_bfe_u32 v136, v72, 16, 1
	v_bfe_u32 v137, v73, 16, 1
	v_bfe_u32 v138, v74, 16, 1
	v_bfe_u32 v139, v75, 16, 1
	v_add3_u32 v72, v72, v136, s46
	v_add3_u32 v73, v73, v137, s46
	v_add3_u32 v74, v74, v138, s46
	v_add3_u32 v75, v75, v139, s46
	s_mov_b32 s101, 0x30000
	buffer_store_short_d16_hi v72, v128, s[96:99], s101 offen offset:64
	buffer_store_short_d16_hi v73, v129, s[96:99], s101 offen offset:64
	buffer_store_short_d16_hi v74, v130, s[96:99], s101 offen offset:64
	buffer_store_short_d16_hi v75, v131, s[96:99], s101 offen offset:64
	v_bfe_u32 v136, v76, 16, 1
	v_bfe_u32 v137, v77, 16, 1
	v_bfe_u32 v138, v78, 16, 1
	v_bfe_u32 v139, v79, 16, 1
	v_add3_u32 v76, v76, v136, s46
	v_add3_u32 v77, v77, v137, s46
	v_add3_u32 v78, v78, v138, s46
	v_add3_u32 v79, v79, v139, s46
	s_mov_b32 s101, 0x38000
	buffer_store_short_d16_hi v76, v128, s[96:99], s101 offen offset:64
	buffer_store_short_d16_hi v77, v129, s[96:99], s101 offen offset:64
	buffer_store_short_d16_hi v78, v130, s[96:99], s101 offen offset:64
	buffer_store_short_d16_hi v79, v131, s[96:99], s101 offen offset:64
	v_bfe_u32 v136, v48, 16, 1
	v_bfe_u32 v137, v49, 16, 1
	v_bfe_u32 v138, v50, 16, 1
	v_bfe_u32 v139, v51, 16, 1
	v_add3_u32 v48, v48, v136, s46
	v_add3_u32 v49, v49, v137, s46
	v_add3_u32 v50, v50, v138, s46
	v_add3_u32 v51, v51, v139, s46
	s_mov_b32 s101, 0x40000
	buffer_store_short_d16_hi v48, v128, s[96:99], s101 offen
	buffer_store_short_d16_hi v49, v129, s[96:99], s101 offen
	buffer_store_short_d16_hi v50, v130, s[96:99], s101 offen
	buffer_store_short_d16_hi v51, v131, s[96:99], s101 offen
	v_bfe_u32 v136, v52, 16, 1
	v_bfe_u32 v137, v53, 16, 1
	v_bfe_u32 v138, v54, 16, 1
	v_bfe_u32 v139, v55, 16, 1
	v_add3_u32 v52, v52, v136, s46
	v_add3_u32 v53, v53, v137, s46
	v_add3_u32 v54, v54, v138, s46
	v_add3_u32 v55, v55, v139, s46
	s_mov_b32 s101, 0x48000
	buffer_store_short_d16_hi v52, v128, s[96:99], s101 offen
	buffer_store_short_d16_hi v53, v129, s[96:99], s101 offen
	buffer_store_short_d16_hi v54, v130, s[96:99], s101 offen
	buffer_store_short_d16_hi v55, v131, s[96:99], s101 offen
	v_bfe_u32 v136, v56, 16, 1
	v_bfe_u32 v137, v57, 16, 1
	v_bfe_u32 v138, v58, 16, 1
	v_bfe_u32 v139, v59, 16, 1
	v_add3_u32 v56, v56, v136, s46
	v_add3_u32 v57, v57, v137, s46
	v_add3_u32 v58, v58, v138, s46
	v_add3_u32 v59, v59, v139, s46
	s_mov_b32 s101, 0x50000
	buffer_store_short_d16_hi v56, v128, s[96:99], s101 offen
	buffer_store_short_d16_hi v57, v129, s[96:99], s101 offen
	buffer_store_short_d16_hi v58, v130, s[96:99], s101 offen
	buffer_store_short_d16_hi v59, v131, s[96:99], s101 offen
	v_bfe_u32 v136, v60, 16, 1
	v_bfe_u32 v137, v61, 16, 1
	v_bfe_u32 v138, v62, 16, 1
	v_bfe_u32 v139, v63, 16, 1
	v_add3_u32 v60, v60, v136, s46
	v_add3_u32 v61, v61, v137, s46
	v_add3_u32 v62, v62, v138, s46
	v_add3_u32 v63, v63, v139, s46
	s_mov_b32 s101, 0x58000
	buffer_store_short_d16_hi v60, v128, s[96:99], s101 offen
	buffer_store_short_d16_hi v61, v129, s[96:99], s101 offen
	buffer_store_short_d16_hi v62, v130, s[96:99], s101 offen
	buffer_store_short_d16_hi v63, v131, s[96:99], s101 offen
	v_bfe_u32 v136, v32, 16, 1
	v_bfe_u32 v137, v33, 16, 1
	v_bfe_u32 v138, v34, 16, 1
	v_bfe_u32 v139, v35, 16, 1
	v_add3_u32 v32, v32, v136, s46
	v_add3_u32 v33, v33, v137, s46
	v_add3_u32 v34, v34, v138, s46
	v_add3_u32 v35, v35, v139, s46
	s_mov_b32 s101, 0x40000
	buffer_store_short_d16_hi v32, v128, s[96:99], s101 offen offset:64
	buffer_store_short_d16_hi v33, v129, s[96:99], s101 offen offset:64
	buffer_store_short_d16_hi v34, v130, s[96:99], s101 offen offset:64
	buffer_store_short_d16_hi v35, v131, s[96:99], s101 offen offset:64
	v_bfe_u32 v136, v36, 16, 1
	v_bfe_u32 v137, v37, 16, 1
	v_bfe_u32 v138, v38, 16, 1
	v_bfe_u32 v139, v39, 16, 1
	v_add3_u32 v36, v36, v136, s46
	v_add3_u32 v37, v37, v137, s46
	v_add3_u32 v38, v38, v138, s46
	v_add3_u32 v39, v39, v139, s46
	s_mov_b32 s101, 0x48000
	buffer_store_short_d16_hi v36, v128, s[96:99], s101 offen offset:64
	buffer_store_short_d16_hi v37, v129, s[96:99], s101 offen offset:64
	buffer_store_short_d16_hi v38, v130, s[96:99], s101 offen offset:64
	buffer_store_short_d16_hi v39, v131, s[96:99], s101 offen offset:64
	v_bfe_u32 v136, v40, 16, 1
	v_bfe_u32 v137, v41, 16, 1
	v_bfe_u32 v138, v42, 16, 1
	v_bfe_u32 v139, v43, 16, 1
	v_add3_u32 v40, v40, v136, s46
	v_add3_u32 v41, v41, v137, s46
	v_add3_u32 v42, v42, v138, s46
	v_add3_u32 v43, v43, v139, s46
	s_mov_b32 s101, 0x50000
	buffer_store_short_d16_hi v40, v128, s[96:99], s101 offen offset:64
	buffer_store_short_d16_hi v41, v129, s[96:99], s101 offen offset:64
	buffer_store_short_d16_hi v42, v130, s[96:99], s101 offen offset:64
	buffer_store_short_d16_hi v43, v131, s[96:99], s101 offen offset:64
	v_bfe_u32 v136, v44, 16, 1
	v_bfe_u32 v137, v45, 16, 1
	v_bfe_u32 v138, v46, 16, 1
	v_bfe_u32 v139, v47, 16, 1
	v_add3_u32 v44, v44, v136, s46
	v_add3_u32 v45, v45, v137, s46
	v_add3_u32 v46, v46, v138, s46
	v_add3_u32 v47, v47, v139, s46
	s_mov_b32 s101, 0x58000
	buffer_store_short_d16_hi v44, v128, s[96:99], s101 offen offset:64
	buffer_store_short_d16_hi v45, v129, s[96:99], s101 offen offset:64
	buffer_store_short_d16_hi v46, v130, s[96:99], s101 offen offset:64
	buffer_store_short_d16_hi v47, v131, s[96:99], s101 offen offset:64
	v_bfe_u32 v136, v16, 16, 1
	v_bfe_u32 v137, v17, 16, 1
	v_bfe_u32 v138, v18, 16, 1
	v_bfe_u32 v139, v19, 16, 1
	v_add3_u32 v16, v16, v136, s46
	v_add3_u32 v17, v17, v137, s46
	v_add3_u32 v18, v18, v138, s46
	v_add3_u32 v19, v19, v139, s46
	s_mov_b32 s101, 0x60000
	buffer_store_short_d16_hi v16, v128, s[96:99], s101 offen
	buffer_store_short_d16_hi v17, v129, s[96:99], s101 offen
	buffer_store_short_d16_hi v18, v130, s[96:99], s101 offen
	buffer_store_short_d16_hi v19, v131, s[96:99], s101 offen
	v_bfe_u32 v136, v20, 16, 1
	v_bfe_u32 v137, v21, 16, 1
	v_bfe_u32 v138, v22, 16, 1
	v_bfe_u32 v139, v23, 16, 1
	v_add3_u32 v20, v20, v136, s46
	v_add3_u32 v21, v21, v137, s46
	v_add3_u32 v22, v22, v138, s46
	v_add3_u32 v23, v23, v139, s46
	s_mov_b32 s101, 0x68000
	buffer_store_short_d16_hi v20, v128, s[96:99], s101 offen
	buffer_store_short_d16_hi v21, v129, s[96:99], s101 offen
	buffer_store_short_d16_hi v22, v130, s[96:99], s101 offen
	buffer_store_short_d16_hi v23, v131, s[96:99], s101 offen
	v_bfe_u32 v136, v24, 16, 1
	v_bfe_u32 v137, v25, 16, 1
	v_bfe_u32 v138, v26, 16, 1
	v_bfe_u32 v139, v27, 16, 1
	v_add3_u32 v24, v24, v136, s46
	v_add3_u32 v25, v25, v137, s46
	v_add3_u32 v26, v26, v138, s46
	v_add3_u32 v27, v27, v139, s46
	s_mov_b32 s101, 0x70000
	buffer_store_short_d16_hi v24, v128, s[96:99], s101 offen
	buffer_store_short_d16_hi v25, v129, s[96:99], s101 offen
	buffer_store_short_d16_hi v26, v130, s[96:99], s101 offen
	buffer_store_short_d16_hi v27, v131, s[96:99], s101 offen
	v_bfe_u32 v136, v28, 16, 1
	v_bfe_u32 v137, v29, 16, 1
	v_bfe_u32 v138, v30, 16, 1
	v_bfe_u32 v139, v31, 16, 1
	v_add3_u32 v28, v28, v136, s46
	v_add3_u32 v29, v29, v137, s46
	v_add3_u32 v30, v30, v138, s46
	v_add3_u32 v31, v31, v139, s46
	s_mov_b32 s101, 0x78000
	buffer_store_short_d16_hi v28, v128, s[96:99], s101 offen
	buffer_store_short_d16_hi v29, v129, s[96:99], s101 offen
	buffer_store_short_d16_hi v30, v130, s[96:99], s101 offen
	buffer_store_short_d16_hi v31, v131, s[96:99], s101 offen
	v_bfe_u32 v136, v0, 16, 1
	v_bfe_u32 v137, v1, 16, 1
	v_bfe_u32 v138, v2, 16, 1
	v_bfe_u32 v139, v3, 16, 1
	v_add3_u32 v0, v0, v136, s46
	v_add3_u32 v1, v1, v137, s46
	v_add3_u32 v2, v2, v138, s46
	v_add3_u32 v3, v3, v139, s46
	s_mov_b32 s101, 0x60000
	buffer_store_short_d16_hi v0, v128, s[96:99], s101 offen offset:64
	buffer_store_short_d16_hi v1, v129, s[96:99], s101 offen offset:64
	buffer_store_short_d16_hi v2, v130, s[96:99], s101 offen offset:64
	buffer_store_short_d16_hi v3, v131, s[96:99], s101 offen offset:64
	v_bfe_u32 v136, v4, 16, 1
	v_bfe_u32 v137, v5, 16, 1
	v_bfe_u32 v138, v6, 16, 1
	v_bfe_u32 v139, v7, 16, 1
	v_add3_u32 v4, v4, v136, s46
	v_add3_u32 v5, v5, v137, s46
	v_add3_u32 v6, v6, v138, s46
	v_add3_u32 v7, v7, v139, s46
	s_mov_b32 s101, 0x68000
	buffer_store_short_d16_hi v4, v128, s[96:99], s101 offen offset:64
	buffer_store_short_d16_hi v5, v129, s[96:99], s101 offen offset:64
	buffer_store_short_d16_hi v6, v130, s[96:99], s101 offen offset:64
	buffer_store_short_d16_hi v7, v131, s[96:99], s101 offen offset:64
	v_bfe_u32 v136, v8, 16, 1
	v_bfe_u32 v137, v9, 16, 1
	v_bfe_u32 v138, v10, 16, 1
	v_bfe_u32 v139, v11, 16, 1
	v_add3_u32 v8, v8, v136, s46
	v_add3_u32 v9, v9, v137, s46
	v_add3_u32 v10, v10, v138, s46
	v_add3_u32 v11, v11, v139, s46
	s_mov_b32 s101, 0x70000
	buffer_store_short_d16_hi v8, v128, s[96:99], s101 offen offset:64
	buffer_store_short_d16_hi v9, v129, s[96:99], s101 offen offset:64
	buffer_store_short_d16_hi v10, v130, s[96:99], s101 offen offset:64
	buffer_store_short_d16_hi v11, v131, s[96:99], s101 offen offset:64
	v_bfe_u32 v136, v12, 16, 1
	v_bfe_u32 v137, v13, 16, 1
	v_bfe_u32 v138, v14, 16, 1
	v_bfe_u32 v139, v15, 16, 1
	v_add3_u32 v12, v12, v136, s46
	v_add3_u32 v13, v13, v137, s46
	v_add3_u32 v14, v14, v138, s46
	v_add3_u32 v15, v15, v139, s46
	s_mov_b32 s101, 0x78000
	buffer_store_short_d16_hi v12, v128, s[96:99], s101 offen offset:64
	buffer_store_short_d16_hi v13, v129, s[96:99], s101 offen offset:64
	buffer_store_short_d16_hi v14, v130, s[96:99], s101 offen offset:64
	buffer_store_short_d16_hi v15, v131, s[96:99], s101 offen offset:64
	s_add_i32 s38, s38, s94
	s_cmpk_lt_i32 s38, 0x200
	s_cbranch_scc1 .Lgwq1_tile
	s_branch .LBB0_2651

	.amdhsa_kernel _Z14fwd_megakernel6Params
		.amdhsa_group_segment_fixed_size 147600
		.amdhsa_private_segment_fixed_size 0
		.amdhsa_kernarg_size 600
		.amdhsa_user_sgpr_count 2
		.amdhsa_user_sgpr_dispatch_ptr 0
		.amdhsa_user_sgpr_queue_ptr 0
		.amdhsa_user_sgpr_kernarg_segment_ptr 1
		.amdhsa_user_sgpr_dispatch_id 0
		.amdhsa_user_sgpr_kernarg_preload_length 0
		.amdhsa_user_sgpr_kernarg_preload_offset 0
		.amdhsa_user_sgpr_private_segment_size 0
		.amdhsa_uses_dynamic_stack 0
		.amdhsa_enable_private_segment 0
		.amdhsa_system_sgpr_workgroup_id_x 1
		.amdhsa_system_sgpr_workgroup_id_y 0
		.amdhsa_system_sgpr_workgroup_id_z 0
		.amdhsa_system_sgpr_workgroup_info 0
		.amdhsa_system_vgpr_workitem_id 2
		.amdhsa_next_free_vgpr 256
		.amdhsa_next_free_sgpr 102
		.amdhsa_accum_offset 256
		.amdhsa_reserve_vcc 1
		.amdhsa_float_round_mode_32 0
		.amdhsa_float_round_mode_16_64 0
		.amdhsa_float_denorm_mode_32 3
		.amdhsa_float_denorm_mode_16_64 3
		.amdhsa_dx10_clamp 1
		.amdhsa_ieee_mode 1
		.amdhsa_fp16_overflow 0
		.amdhsa_tg_split 0
		.amdhsa_exception_fp_ieee_invalid_op 0
		.amdhsa_exception_fp_denorm_src 0
		.amdhsa_exception_fp_ieee_div_zero 0
		.amdhsa_exception_fp_ieee_overflow 0
		.amdhsa_exception_fp_ieee_underflow 0
		.amdhsa_exception_fp_ieee_inexact 0
		.amdhsa_exception_int_div_zero 0
	.end_amdhsa_kernel

amdhsa.kernels:
  - .agpr_count:     0
    .args:
      - .offset:         0
        .size:           344
        .value_kind:     by_value
      - .offset:         344
        .size:           4
        .value_kind:     hidden_block_count_x
      - .offset:         348
        .size:           4
        .value_kind:     hidden_block_count_y
      - .offset:         352
        .size:           4
        .value_kind:     hidden_block_count_z
      - .offset:         356
        .size:           2
        .value_kind:     hidden_group_size_x
      - .offset:         358
        .size:           2
        .value_kind:     hidden_group_size_y
      - .offset:         360
        .size:           2
        .value_kind:     hidden_group_size_z
      - .offset:         362
        .size:           2
        .value_kind:     hidden_remainder_x
      - .offset:         364
        .size:           2
        .value_kind:     hidden_remainder_y
      - .offset:         366
        .size:           2
        .value_kind:     hidden_remainder_z
      - .offset:         384
        .size:           8
        .value_kind:     hidden_global_offset_x
      - .offset:         392
        .size:           8
        .value_kind:     hidden_global_offset_y
      - .offset:         400
        .size:           8
        .value_kind:     hidden_global_offset_z
      - .offset:         408
        .size:           2
        .value_kind:     hidden_grid_dims
      - .offset:         432
        .size:           8
        .value_kind:     hidden_multigrid_sync_arg
    .group_segment_fixed_size: 147600
    .kernarg_segment_align: 8
    .kernarg_segment_size: 600
    .language:       OpenCL C
    .language_version:
      - 2
      - 0
    .max_flat_workgroup_size: 512
    .name:           _Z14fwd_megakernel6Params
    .private_segment_fixed_size: 0
    .sgpr_count:     108
    .sgpr_spill_count: 172
    .symbol:         _Z14fwd_megakernel6Params.kd
    .uniform_work_group_size: 1
    .uses_dynamic_stack: false
    .vgpr_count:     256
    .vgpr_spill_count: 0
    .wavefront_size: 64
